# previous stack + attention loops: removed fmaxf self-canonicalisation pairs and add-zero (exact for non-NaN)
# speedup vs baseline: 1.0148x; 1.0039x over previous
.LBB0_659:
	v_add_f32_e32 v100, v177, v178
	v_add_f32_e32 v101, v179, v180
	v_add_f32_e32 v100, v101, v100
	v_add_f32_e32 v101, v181, v182
	v_add_f32_e32 v100, v101, v100
	v_add_f32_e32 v101, v183, v184
	v_add_f32_e32 v100, v101, v100
	v_add_f32_e32 v101, v185, v186
	v_add_f32_e32 v100, v101, v100
	v_add_f32_e32 v101, v187, v188
	v_add_f32_e32 v100, v101, v100
	v_add_f32_e32 v101, v189, v191
	v_add_f32_e32 v100, v101, v100
	v_add_f32_e32 v101, v190, v192
	v_add_f32_e32 v100, v101, v100
	v_fmac_f32_e32 v100, v156, v14
	v_add_f32_e32 v14, v194, v209
	v_add_f32_e32 v101, v195, v104
	v_add_f32_e32 v14, v101, v14
	v_add_f32_e32 v101, v105, v106
	v_add_f32_e32 v14, v101, v14
	v_add_f32_e32 v101, v107, v210
	v_add_f32_e32 v14, v101, v14
	v_add_f32_e32 v88, v88, v89
	v_add_f32_e32 v14, v88, v14
	v_add_f32_e32 v88, v90, v91
	v_add_f32_e32 v14, v88, v14
	v_add_f32_e32 v88, v92, v94
	v_add_f32_e32 v14, v88, v14
	v_add_f32_e32 v88, v93, v95
	v_add_f32_e32 v156, v88, v14
	v_add_f32_e32 v14, v15, v162
	v_add_f32_e32 v15, v160, v163
	v_add_f32_e32 v14, v15, v14
	v_add_f32_e32 v15, v161, v165
	v_add_f32_e32 v14, v15, v14
	v_add_f32_e32 v15, v164, v166
	v_mfma_f32_32x32x16_bf16 v[32:47], v[10:13], v[80:83], v[32:47]
	v_add_f32_e32 v14, v15, v14
	v_add_f32_e32 v15, v167, v171
	v_add_f32_e32 v14, v15, v14
	v_add_f32_e32 v15, v168, v172
	v_add_f32_e32 v14, v15, v14
	v_add_f32_e32 v15, v169, v173
	v_add_f32_e32 v14, v15, v14
	v_mfma_f32_32x32x16_bf16 v[16:31], v[96:99], v[80:83], v[16:31]
	v_add_f32_e32 v15, v170, v174
	v_add_f32_e32 v14, v15, v14
	v_fmac_f32_e32 v14, v159, v0
	v_add_f32_e32 v0, v205, v207
	v_add_f32_e32 v15, v206, v208
	v_add_f32_e32 v0, v15, v0
	v_add_f32_e32 v10, v109, v193
	v_mfma_f32_32x32x16_bf16 v[32:47], v[6:9], v[84:87], v[32:47]
	v_add_f32_e32 v0, v10, v0
	v_add_f32_e32 v10, v111, v196
	v_add_f32_e32 v0, v10, v0
	v_add_f32_e32 v10, v201, v203
	s_add_i32 s60, s60, 1
	s_add_i32 s23, s54, 1
	v_add_f32_e32 v0, v10, v0
	v_mfma_f32_32x32x16_bf16 v[16:31], v[2:5], v[84:87], v[16:31]
	v_add_f32_e32 v10, v202, v204
	s_cmp_lg_u32 s54, 2
	v_add_f32_e32 v0, v10, v0
	v_add_f32_e32 v10, v197, v199
	s_cselect_b32 s54, s23, 0
	s_add_i32 s23, s55, 1
	v_add_f32_e32 v0, v10, v0
	v_add_f32_e32 v10, v198, v200
	s_cmp_lg_u32 s55, 2
	v_add_f32_e32 v159, v10, v0
	s_cselect_b32 s55, s23, 0
	s_add_i32 s59, s59, 64
	v_fmac_f32_e32 v156, v100, v110
	v_fmac_f32_e32 v159, v14, v108
	s_cmp_lg_u32 s60, 36
	s_cbranch_scc0 .LBB0_632

.LBB0_666:
	s_mul_i32 s23, s54, 0x3400
	v_add_u32_e32 v193, s23, v157
	ds_read_b128 v[2:5], v193
	ds_read_b128 v[6:9], v193 offset:32
	ds_read_b128 v[10:13], v193 offset:64
	ds_read_b128 v[160:163], v193 offset:96
	ds_read_b128 v[164:167], v193 offset:128
	ds_read_b128 v[168:171], v193 offset:160
	s_waitcnt lgkmcnt(5)
	v_mfma_f32_32x32x16_bf16 v[96:111], v[2:5], v[112:115], 0
	s_waitcnt lgkmcnt(4)
	v_mfma_f32_32x32x16_bf16 v[96:111], v[6:9], v[116:119], v[96:111]
	s_waitcnt lgkmcnt(3)
	v_mfma_f32_32x32x16_bf16 v[96:111], v[10:13], v[120:123], v[96:111]
	s_waitcnt lgkmcnt(2)
	v_mfma_f32_32x32x16_bf16 v[96:111], v[160:163], v[124:127], v[96:111]
	s_waitcnt lgkmcnt(1)
	v_mfma_f32_32x32x16_bf16 v[96:111], v[164:167], v[218:221], v[96:111]
	s_waitcnt lgkmcnt(0)
	v_mfma_f32_32x32x16_bf16 v[96:111], v[168:171], v[222:225], v[96:111]
	s_nop 7
	s_waitcnt lgkmcnt(0)
	v_mfma_f32_32x32x16_bf16 v[80:95], v[2:5], v[128:131], 0
	s_nop 1
	v_max3_f32 v0, v96, s62, v97
	v_max3_f32 v0, v0, v98, v99
	v_max3_f32 v0, v0, v100, v101
	v_max3_f32 v0, v0, v102, v103
	v_max3_f32 v0, v0, v104, v105
	v_max3_f32 v0, v0, v106, v107
	v_max3_f32 v0, v0, v108, v109
	v_max3_f32 v0, v0, v110, v111
	v_mov_b32_e32 v2, v0
	s_nop 1
	v_permlane32_swap_b32_e32 v0, v2
	v_max_f32_e32 v0, v0, v2
	v_mul_f32_e32 v0, 0x3e16c740, v0
	v_mfma_f32_32x32x16_bf16 v[80:95], v[6:9], v[132:135], v[80:95]
	v_add_f32_e32 v2, 0x41000000, v176
	v_cmp_gt_f32_e32 vcc, v0, v2
	s_nop 1
	v_cndmask_b32_e32 v196, v176, v0, vcc
	v_sub_f32_e32 v0, v176, v196
	v_fma_f32 v2, v96, s63, -v196
	v_fma_f32 v3, v97, s63, -v196
	v_fma_f32 v4, v98, s63, -v196
	v_fma_f32 v5, v99, s63, -v196
	v_fma_f32 v6, v100, s63, -v196
	v_fma_f32 v7, v101, s63, -v196
	v_fma_f32 v8, v102, s63, -v196
	v_fma_f32 v9, v103, s63, -v196
	v_fma_f32 v14, v104, s63, -v196
	v_fma_f32 v96, v105, s63, -v196
	v_mfma_f32_32x32x16_bf16 v[80:95], v[10:13], v[136:139], v[80:95]
	v_fma_f32 v97, v106, s63, -v196
	v_fma_f32 v10, v107, s63, -v196
	v_fma_f32 v11, v108, s63, -v196
	v_fma_f32 v12, v109, s63, -v196
	v_fma_f32 v13, v110, s63, -v196
	v_fma_f32 v98, v111, s63, -v196
	v_exp_f32_e32 v0, v0
	v_mfma_f32_32x32x16_bf16 v[80:95], v[160:163], v[140:143], v[80:95]
	v_exp_f32_e32 v15, v2
	v_exp_f32_e32 v162, v3
	v_exp_f32_e32 v160, v4
	v_exp_f32_e32 v163, v5
	v_exp_f32_e32 v161, v6
	v_exp_f32_e32 v172, v10
	v_exp_f32_e32 v173, v12
	v_mfma_f32_32x32x16_bf16 v[80:95], v[164:167], v[226:229], v[80:95]
	v_exp_f32_e32 v165, v7
	v_exp_f32_e32 v164, v8
	v_exp_f32_e32 v166, v9
	v_exp_f32_e32 v167, v14
	v_exp_f32_e32 v174, v98
	v_cvt_pk_bf16_f32 v104, v15, v162
	v_cvt_pk_bf16_f32 v105, v160, v163
	v_mfma_f32_32x32x16_bf16 v[80:95], v[168:171], v[244:247], v[80:95]
	v_exp_f32_e32 v171, v96
	v_exp_f32_e32 v168, v97
	v_exp_f32_e32 v169, v11
	v_exp_f32_e32 v170, v13
	v_cvt_pk_bf16_f32 v106, v161, v165
	v_cvt_pk_bf16_f32 v107, v164, v166
	v_cvt_pk_bf16_f32 v2, v167, v171
	v_cvt_pk_bf16_f32 v3, v168, v172
	v_cvt_pk_bf16_f32 v4, v169, v173
	v_cvt_pk_bf16_f32 v5, v170, v174
	v_cmp_eq_f32_e32 vcc, 1.0, v0
	s_cmp_eq_u64 vcc, exec
	s_cbranch_scc1 .LBB0_668
	v_pk_mul_f32 v[78:79], v[78:79], v[0:1] op_sel_hi:[1,0]
	v_pk_mul_f32 v[76:77], v[76:77], v[0:1] op_sel_hi:[1,0]
	v_pk_mul_f32 v[74:75], v[74:75], v[0:1] op_sel_hi:[1,0]
	v_pk_mul_f32 v[72:73], v[72:73], v[0:1] op_sel_hi:[1,0]
	v_pk_mul_f32 v[70:71], v[70:71], v[0:1] op_sel_hi:[1,0]
	v_pk_mul_f32 v[68:69], v[68:69], v[0:1] op_sel_hi:[1,0]
	v_pk_mul_f32 v[66:67], v[66:67], v[0:1] op_sel_hi:[1,0]
	v_pk_mul_f32 v[64:65], v[64:65], v[0:1] op_sel_hi:[1,0]
	v_pk_mul_f32 v[62:63], v[62:63], v[0:1] op_sel_hi:[1,0]
	v_pk_mul_f32 v[60:61], v[60:61], v[0:1] op_sel_hi:[1,0]
	v_pk_mul_f32 v[58:59], v[58:59], v[0:1] op_sel_hi:[1,0]
	v_pk_mul_f32 v[56:57], v[56:57], v[0:1] op_sel_hi:[1,0]
	v_pk_mul_f32 v[54:55], v[54:55], v[0:1] op_sel_hi:[1,0]
	v_pk_mul_f32 v[52:53], v[52:53], v[0:1] op_sel_hi:[1,0]
	v_pk_mul_f32 v[50:51], v[50:51], v[0:1] op_sel_hi:[1,0]
	v_pk_mul_f32 v[48:49], v[48:49], v[0:1] op_sel_hi:[1,0]
.LBB0_668:
	s_lshl_b32 s23, s54, 13
	v_add_u32_e32 v194, s23, v158
	ds_read_b64_tr_b16 v[6:7], v194 offset:39936
	ds_read_b64_tr_b16 v[8:9], v194 offset:40448
	ds_read_b64_tr_b16 v[10:11], v194 offset:40960
	ds_read_b64_tr_b16 v[12:13], v194 offset:41472
	ds_read_b64_tr_b16 v[100:101], v194 offset:44032
	ds_read_b64_tr_b16 v[102:103], v194 offset:44544
	ds_read_b64_tr_b16 v[96:97], v194 offset:45056
	ds_read_b64_tr_b16 v[98:99], v194 offset:45568
	s_waitcnt lgkmcnt(6)
	v_mfma_f32_32x32x16_bf16 v[64:79], v[6:9], v[104:107], v[64:79]
	v_max3_f32 v14, v80, s62, v81
	v_max3_f32 v14, v14, v82, v83
	v_max3_f32 v14, v14, v84, v85
	v_max3_f32 v14, v14, v86, v87
	v_max3_f32 v14, v14, v88, v89
	v_max3_f32 v14, v14, v90, v91
	v_max3_f32 v14, v14, v92, v93
	v_max3_f32 v14, v14, v94, v95
	v_mov_b32_e32 v108, v14
	s_nop 1
	v_permlane32_swap_b32_e32 v14, v108
	v_max_f32_e32 v14, v14, v108
	v_mul_f32_e32 v14, 0x3e16c740, v14
	v_add_f32_e32 v108, 0x41000000, v175
	v_cmp_gt_f32_e32 vcc, v14, v108
	s_nop 1
	v_cndmask_b32_e32 v195, v175, v14, vcc
	v_fma_f32 v14, v80, s63, -v195
	v_exp_f32_e32 v177, v14
	v_fma_f32 v14, v81, s63, -v195
	v_exp_f32_e32 v178, v14
	v_sub_f32_e32 v14, v175, v195
	s_waitcnt lgkmcnt(2)
	v_mfma_f32_32x32x16_bf16 v[48:63], v[100:103], v[104:107], v[48:63]
	v_fma_f32 v80, v82, s63, -v195
	v_exp_f32_e32 v179, v80
	v_fma_f32 v80, v83, s63, -v195
	v_exp_f32_e32 v180, v80
	v_fma_f32 v80, v84, s63, -v195
	v_fma_f32 v84, v88, s63, -v195
	v_exp_f32_e32 v185, v84
	v_fma_f32 v84, v89, s63, -v195
	v_exp_f32_e32 v186, v84
	v_fma_f32 v84, v90, s63, -v195
	v_exp_f32_e32 v181, v80
	v_fma_f32 v80, v85, s63, -v195
	v_exp_f32_e32 v187, v84
	v_fma_f32 v84, v91, s63, -v195
	v_exp_f32_e32 v182, v80
	v_fma_f32 v80, v86, s63, -v195
	v_exp_f32_e32 v188, v84
	v_fma_f32 v84, v92, s63, -v195
	v_exp_f32_e32 v183, v80
	v_fma_f32 v80, v87, s63, -v195
	v_exp_f32_e32 v189, v84
	v_fma_f32 v84, v93, s63, -v195
	v_fma_f32 v85, v94, s63, -v195
	v_fma_f32 v86, v95, s63, -v195
	v_mfma_f32_32x32x16_bf16 v[64:79], v[10:13], v[2:5], v[64:79]
	v_exp_f32_e32 v14, v14
	v_exp_f32_e32 v184, v80
	v_exp_f32_e32 v191, v84
	v_exp_f32_e32 v190, v85
	v_exp_f32_e32 v192, v86
	v_cvt_pk_bf16_f32 v80, v177, v178
	v_cvt_pk_bf16_f32 v81, v179, v180
	s_waitcnt lgkmcnt(0)
	v_mfma_f32_32x32x16_bf16 v[48:63], v[96:99], v[2:5], v[48:63]
	v_cvt_pk_bf16_f32 v82, v181, v182
	v_cvt_pk_bf16_f32 v83, v183, v184
	v_cvt_pk_bf16_f32 v84, v185, v186
	v_cvt_pk_bf16_f32 v85, v187, v188
	v_cvt_pk_bf16_f32 v86, v189, v191
	v_cvt_pk_bf16_f32 v87, v190, v192
	v_cmp_eq_f32_e32 vcc, 1.0, v14
	s_cmp_eq_u64 vcc, exec
	s_cbranch_scc1 .LBB0_670
	v_pk_mul_f32 v[46:47], v[46:47], v[14:15] op_sel_hi:[1,0]
	v_pk_mul_f32 v[44:45], v[44:45], v[14:15] op_sel_hi:[1,0]
	v_pk_mul_f32 v[42:43], v[42:43], v[14:15] op_sel_hi:[1,0]
	v_pk_mul_f32 v[40:41], v[40:41], v[14:15] op_sel_hi:[1,0]
	v_pk_mul_f32 v[38:39], v[38:39], v[14:15] op_sel_hi:[1,0]
	v_pk_mul_f32 v[36:37], v[36:37], v[14:15] op_sel_hi:[1,0]
	v_pk_mul_f32 v[34:35], v[34:35], v[14:15] op_sel_hi:[1,0]
	v_pk_mul_f32 v[32:33], v[32:33], v[14:15] op_sel_hi:[1,0]
	v_pk_mul_f32 v[30:31], v[30:31], v[14:15] op_sel_hi:[1,0]
	v_pk_mul_f32 v[28:29], v[28:29], v[14:15] op_sel_hi:[1,0]
	v_pk_mul_f32 v[26:27], v[26:27], v[14:15] op_sel_hi:[1,0]
	v_pk_mul_f32 v[24:25], v[24:25], v[14:15] op_sel_hi:[1,0]
	v_pk_mul_f32 v[22:23], v[22:23], v[14:15] op_sel_hi:[1,0]
	v_pk_mul_f32 v[20:21], v[20:21], v[14:15] op_sel_hi:[1,0]
	v_pk_mul_f32 v[18:19], v[18:19], v[14:15] op_sel_hi:[1,0]
	v_pk_mul_f32 v[16:17], v[16:17], v[14:15] op_sel_hi:[1,0]
.LBB0_670:
	ds_read_b128 v[2:5], v193 offset:6656
	s_nop 0
	v_mfma_f32_32x32x16_bf16 v[16:31], v[100:103], v[80:83], v[16:31]
	v_mfma_f32_32x32x16_bf16 v[32:47], v[6:9], v[80:83], v[32:47]
	v_mfma_f32_32x32x16_bf16 v[16:31], v[96:99], v[84:87], v[16:31]
	v_mfma_f32_32x32x16_bf16 v[32:47], v[10:13], v[84:87], v[32:47]
	ds_read_b128 v[6:9], v193 offset:6688
	ds_read_b128 v[10:13], v193 offset:6720
	ds_read_b128 v[198:201], v193 offset:6752
	ds_read_b128 v[202:205], v193 offset:6784
	ds_read_b128 v[210:213], v193 offset:6816
	s_waitcnt lgkmcnt(5)
	v_mfma_f32_32x32x16_bf16 v[96:111], v[2:5], v[112:115], 0
	s_waitcnt lgkmcnt(4)
	v_mfma_f32_32x32x16_bf16 v[96:111], v[6:9], v[116:119], v[96:111]
	s_waitcnt lgkmcnt(3)
	v_mfma_f32_32x32x16_bf16 v[96:111], v[10:13], v[120:123], v[96:111]
	s_waitcnt lgkmcnt(2)
	v_mfma_f32_32x32x16_bf16 v[96:111], v[198:201], v[124:127], v[96:111]
	s_waitcnt lgkmcnt(1)
	v_mfma_f32_32x32x16_bf16 v[96:111], v[202:205], v[218:221], v[96:111]
	s_waitcnt lgkmcnt(0)
	v_mfma_f32_32x32x16_bf16 v[96:111], v[210:213], v[222:225], v[96:111]
	s_nop 7
	s_waitcnt lgkmcnt(4)
	v_mfma_f32_32x32x16_bf16 v[80:95], v[2:5], v[128:131], 0
	s_nop 1
	v_max3_f32 v2, v96, s62, v97
	v_max3_f32 v2, v2, v98, v99
	v_max3_f32 v2, v2, v100, v101
	v_max3_f32 v2, v2, v102, v103
	v_max3_f32 v2, v2, v104, v105
	v_max3_f32 v2, v2, v106, v107
	v_max3_f32 v2, v2, v108, v109
	v_max3_f32 v2, v2, v110, v111
	v_mov_b32_e32 v3, v2
	s_nop 1
	v_permlane32_swap_b32_e32 v2, v3
	v_max_f32_e32 v2, v2, v3
	v_mul_f32_e32 v2, 0x3e16c740, v2
	s_waitcnt lgkmcnt(3)
	v_mfma_f32_32x32x16_bf16 v[80:95], v[6:9], v[132:135], v[80:95]
	v_add_f32_e32 v3, 0x41000000, v196
	v_cmp_gt_f32_e32 vcc, v2, v3
	s_nop 1
	v_cndmask_b32_e32 v176, v196, v2, vcc
	v_sub_f32_e32 v2, v196, v176
	v_fma_f32 v3, v96, s63, -v176
	v_fma_f32 v4, v97, s63, -v176
	v_fma_f32 v5, v98, s63, -v176
	v_fma_f32 v6, v99, s63, -v176
	v_fma_f32 v7, v100, s63, -v176
	v_fma_f32 v8, v101, s63, -v176
	v_fma_f32 v9, v102, s63, -v176
	v_fma_f32 v96, v103, s63, -v176
	v_fma_f32 v97, v104, s63, -v176
	v_fma_f32 v98, v105, s63, -v176
	s_waitcnt lgkmcnt(2)
	v_mfma_f32_32x32x16_bf16 v[80:95], v[10:13], v[136:139], v[80:95]
	v_fma_f32 v99, v106, s63, -v176
	v_fma_f32 v10, v107, s63, -v176
	v_fma_f32 v11, v108, s63, -v176
	v_fma_f32 v12, v109, s63, -v176
	v_fma_f32 v13, v110, s63, -v176
	v_fma_f32 v100, v111, s63, -v176
	v_exp_f32_e32 v108, v2
	v_mfma_f32_32x32x16_bf16 v[80:95], v[198:201], v[140:143], v[80:95]
	v_exp_f32_e32 v109, v7
	v_exp_f32_e32 v193, v8
	v_exp_f32_e32 v111, v9
	v_exp_f32_e32 v196, v96
	v_exp_f32_e32 v201, v97
	v_exp_f32_e32 v197, v11
	v_exp_f32_e32 v199, v12
	v_mfma_f32_32x32x16_bf16 v[80:95], v[202:205], v[226:229], v[80:95]
	v_exp_f32_e32 v205, v3
	v_exp_f32_e32 v207, v4
	v_exp_f32_e32 v206, v5
	v_exp_f32_e32 v208, v6
	v_exp_f32_e32 v203, v98
	v_exp_f32_e32 v202, v99
	v_exp_f32_e32 v204, v10
	s_waitcnt lgkmcnt(0)
	v_mfma_f32_32x32x16_bf16 v[80:95], v[210:213], v[244:247], v[80:95]
	v_exp_f32_e32 v198, v13
	v_exp_f32_e32 v200, v100
	v_cvt_pk_bf16_f32 v104, v205, v207
	v_cvt_pk_bf16_f32 v105, v206, v208
	v_cvt_pk_bf16_f32 v106, v109, v193
	v_cvt_pk_bf16_f32 v107, v111, v196
	v_cvt_pk_bf16_f32 v100, v201, v203
	v_cvt_pk_bf16_f32 v101, v202, v204
	v_cvt_pk_bf16_f32 v102, v197, v199
	v_cvt_pk_bf16_f32 v103, v198, v200
	v_cmp_eq_f32_e32 vcc, 1.0, v108
	s_cmp_eq_u64 vcc, exec
	s_cbranch_scc1 .LBB0_672
	v_pk_mul_f32 v[78:79], v[78:79], v[108:109] op_sel_hi:[1,0]
	v_pk_mul_f32 v[76:77], v[76:77], v[108:109] op_sel_hi:[1,0]
	v_pk_mul_f32 v[74:75], v[74:75], v[108:109] op_sel_hi:[1,0]
	v_pk_mul_f32 v[72:73], v[72:73], v[108:109] op_sel_hi:[1,0]
	v_pk_mul_f32 v[70:71], v[70:71], v[108:109] op_sel_hi:[1,0]
	v_pk_mul_f32 v[68:69], v[68:69], v[108:109] op_sel_hi:[1,0]
	v_pk_mul_f32 v[66:67], v[66:67], v[108:109] op_sel_hi:[1,0]
	v_pk_mul_f32 v[64:65], v[64:65], v[108:109] op_sel_hi:[1,0]
	v_pk_mul_f32 v[62:63], v[62:63], v[108:109] op_sel_hi:[1,0]
	v_pk_mul_f32 v[60:61], v[60:61], v[108:109] op_sel_hi:[1,0]
	v_pk_mul_f32 v[58:59], v[58:59], v[108:109] op_sel_hi:[1,0]
	v_pk_mul_f32 v[56:57], v[56:57], v[108:109] op_sel_hi:[1,0]
	v_pk_mul_f32 v[54:55], v[54:55], v[108:109] op_sel_hi:[1,0]
	v_pk_mul_f32 v[52:53], v[52:53], v[108:109] op_sel_hi:[1,0]
	v_pk_mul_f32 v[50:51], v[50:51], v[108:109] op_sel_hi:[1,0]
	v_pk_mul_f32 v[48:49], v[48:49], v[108:109] op_sel_hi:[1,0]
.LBB0_672:
	ds_read_b64_tr_b16 v[10:11], v194 offset:41984
	ds_read_b64_tr_b16 v[12:13], v194 offset:42496
	ds_read_b64_tr_b16 v[6:7], v194 offset:43008
	ds_read_b64_tr_b16 v[8:9], v194 offset:43520
	ds_read_b64_tr_b16 v[96:97], v194 offset:46080
	ds_read_b64_tr_b16 v[98:99], v194 offset:46592
	ds_read_b64_tr_b16 v[2:3], v194 offset:47104
	ds_read_b64_tr_b16 v[4:5], v194 offset:47616
	s_waitcnt lgkmcnt(6)
	v_mfma_f32_32x32x16_bf16 v[64:79], v[10:13], v[104:107], v[64:79]
	v_max3_f32 v110, v80, s62, v81
	v_max3_f32 v110, v110, v82, v83
	v_max3_f32 v110, v110, v84, v85
	v_max3_f32 v110, v110, v86, v87
	v_max3_f32 v110, v110, v88, v89
	v_max3_f32 v110, v110, v90, v91
	v_max3_f32 v110, v110, v92, v93
	v_max3_f32 v110, v110, v94, v95
	v_mov_b32_e32 v175, v110
	s_nop 1
	v_permlane32_swap_b32_e32 v110, v175
	v_max_f32_e32 v110, v110, v175
	v_mul_f32_e32 v110, 0x3e16c740, v110
	v_add_f32_e32 v175, 0x41000000, v195
	v_cmp_gt_f32_e32 vcc, v110, v175
	s_nop 1
	v_cndmask_b32_e32 v175, v195, v110, vcc
	v_fma_f32 v80, v80, s63, -v175
	v_exp_f32_e32 v194, v80
	v_fma_f32 v80, v81, s63, -v175
	v_exp_f32_e32 v209, v80
	v_sub_f32_e32 v80, v195, v175
	s_waitcnt lgkmcnt(2)
	v_mfma_f32_32x32x16_bf16 v[48:63], v[96:99], v[104:107], v[48:63]
	v_exp_f32_e32 v110, v80
	v_fma_f32 v80, v82, s63, -v175
	v_exp_f32_e32 v195, v80
	v_fma_f32 v80, v83, s63, -v175
	v_exp_f32_e32 v104, v80
	v_fma_f32 v80, v84, s63, -v175
	v_fma_f32 v84, v88, s63, -v175
	v_exp_f32_e32 v88, v84
	v_fma_f32 v84, v89, s63, -v175
	v_exp_f32_e32 v89, v84
	v_fma_f32 v84, v90, s63, -v175
	v_exp_f32_e32 v105, v80
	v_fma_f32 v80, v85, s63, -v175
	v_exp_f32_e32 v90, v84
	v_fma_f32 v84, v91, s63, -v175
	v_exp_f32_e32 v106, v80
	v_fma_f32 v80, v86, s63, -v175
	v_exp_f32_e32 v91, v84
	v_fma_f32 v84, v92, s63, -v175
	v_exp_f32_e32 v107, v80
	v_fma_f32 v80, v87, s63, -v175
	v_exp_f32_e32 v92, v84
	v_fma_f32 v84, v93, s63, -v175
	v_fma_f32 v85, v94, s63, -v175
	v_fma_f32 v86, v95, s63, -v175
	v_mfma_f32_32x32x16_bf16 v[64:79], v[6:9], v[100:103], v[64:79]
	v_exp_f32_e32 v210, v80
	v_exp_f32_e32 v94, v84
	v_exp_f32_e32 v93, v85
	v_exp_f32_e32 v95, v86
	v_cvt_pk_bf16_f32 v80, v194, v209
	v_cvt_pk_bf16_f32 v81, v195, v104
	v_cvt_pk_bf16_f32 v82, v105, v106
	s_waitcnt lgkmcnt(0)
	v_mfma_f32_32x32x16_bf16 v[48:63], v[2:5], v[100:103], v[48:63]
	v_cvt_pk_bf16_f32 v83, v107, v210
	v_cvt_pk_bf16_f32 v84, v88, v89
	v_cvt_pk_bf16_f32 v85, v90, v91
	v_cvt_pk_bf16_f32 v86, v92, v94
	v_cvt_pk_bf16_f32 v87, v93, v95
	v_cmp_eq_f32_e32 vcc, 1.0, v110
	s_cmp_eq_u64 vcc, exec
	s_cbranch_scc1 .LBB0_659
	v_pk_mul_f32 v[46:47], v[46:47], v[110:111] op_sel_hi:[1,0]
	v_pk_mul_f32 v[44:45], v[44:45], v[110:111] op_sel_hi:[1,0]
	v_pk_mul_f32 v[42:43], v[42:43], v[110:111] op_sel_hi:[1,0]
	v_pk_mul_f32 v[40:41], v[40:41], v[110:111] op_sel_hi:[1,0]
	v_pk_mul_f32 v[38:39], v[38:39], v[110:111] op_sel_hi:[1,0]
	v_pk_mul_f32 v[36:37], v[36:37], v[110:111] op_sel_hi:[1,0]
	v_pk_mul_f32 v[34:35], v[34:35], v[110:111] op_sel_hi:[1,0]
	v_pk_mul_f32 v[32:33], v[32:33], v[110:111] op_sel_hi:[1,0]
	v_pk_mul_f32 v[30:31], v[30:31], v[110:111] op_sel_hi:[1,0]
	v_pk_mul_f32 v[28:29], v[28:29], v[110:111] op_sel_hi:[1,0]
	v_pk_mul_f32 v[26:27], v[26:27], v[110:111] op_sel_hi:[1,0]
	v_pk_mul_f32 v[24:25], v[24:25], v[110:111] op_sel_hi:[1,0]
	v_pk_mul_f32 v[22:23], v[22:23], v[110:111] op_sel_hi:[1,0]
	v_pk_mul_f32 v[20:21], v[20:21], v[110:111] op_sel_hi:[1,0]
	v_pk_mul_f32 v[18:19], v[18:19], v[110:111] op_sel_hi:[1,0]
	v_pk_mul_f32 v[16:17], v[16:17], v[110:111] op_sel_hi:[1,0]
	s_branch .LBB0_659

.LBB0_777:
	s_cmp_ge_i32 s60, s51
	s_cselect_b64 s[4:5], -1, 0
	s_cmp_lt_i32 s60, s51
	s_cselect_b64 s[26:27], -1, 0
	s_add_i32 s60, s49, s60
	s_cmp_ge_u32 s60, s48
	s_cselect_b64 s[68:69], -1, 0
	s_cmp_lt_u32 s60, s52
	s_cselect_b64 s[70:71], -1, 0
	s_and_b64 s[68:69], s[68:69], s[70:71]
	s_or_b64 s[68:69], s[4:5], s[68:69]
	s_andn2_b64 vcc, exec, s[68:69]
	s_cbranch_vccnz .LBB0_802
	s_and_b64 s[4:5], s[4:5], exec
	s_mul_i32 s5, s53, 0x3400
	v_add_u32_e32 v226, s5, v181
	s_cselect_b32 s4, 0, s60
	s_waitcnt lgkmcnt(0)
	ds_read_b128 v[4:7], v226
	s_sub_i32 s4, s4, s46
	s_lshl_b32 s4, s4, 9
	s_add_i32 s61, s4, 0
	s_lshl_b32 s60, s53, 13
	s_add_i32 s61, s61, 0xfc00
	s_mov_b64 s[4:5], -1
	s_and_b64 vcc, exec, s[26:27]
	v_add_f32_e32 v177, 0x41000000, v227
	v_lshlrev_b32_e32 v243, 2, v190
	s_cbranch_vccz .LBB0_784
	s_waitcnt lgkmcnt(0)
	v_mfma_f32_32x32x16_bf16 v[80:95], v[4:7], v[144:147], 0
	ds_read_b128 v[8:11], v226 offset:32
	ds_read_b128 v[12:15], v226 offset:64
	v_add3_u32 v0, s61, v225, v243
	v_add_u32_e32 v2, 0xf00, v0
	v_add_u32_e32 v96, 0xf48, v0
	v_add_u32_e32 v98, 0xf60, v0
	v_mfma_f32_32x32x16_bf16 v[100:115], v[4:7], v[160:163], 0
	s_waitcnt lgkmcnt(0)
	v_mfma_f32_32x32x16_bf16 v[80:95], v[8:11], v[148:151], v[80:95]
	v_mfma_f32_32x32x16_bf16 v[100:115], v[8:11], v[164:167], v[100:115]
	ds_read_b128 v[8:11], v226 offset:96
	v_mfma_f32_32x32x16_bf16 v[80:95], v[12:15], v[152:155], v[80:95]
	v_mfma_f32_32x32x16_bf16 v[100:115], v[12:15], v[168:171], v[100:115]
	v_add_u32_e32 v12, 0xf28, v0
	v_add_u32_e32 v14, 0xf40, v0
	s_waitcnt lgkmcnt(0)
	v_mfma_f32_32x32x16_bf16 v[80:95], v[8:11], v[156:159], v[80:95]
	v_mfma_f32_32x32x16_bf16 v[100:115], v[8:11], v[172:175], v[100:115]
	v_add_u32_e32 v8, 0xf08, v0
	v_add_u32_e32 v10, 0xf20, v0
	s_nop 9
	v_mov_b32_e32 v102, v191
	ds_read2_b32 v[2:3], v2 offset1:1
	v_add_u32_e32 v103, 16, v102
	ds_read2_b32 v[8:9], v8 offset1:1
	v_cmp_ge_i32_e32 vcc, v190, v102
	v_cmp_lt_i32_e64 s[4:5], v190, v103
	s_and_b64 vcc, vcc, s[4:5]
	s_waitcnt lgkmcnt(0)
	v_fmamk_f32 v2, v80, 0x3e38aa3b, v2
	v_cndmask_b32_e32 v2, v237, v2, vcc
	v_cmp_ge_i32_e32 vcc, v194, v102
	v_cmp_lt_i32_e64 s[4:5], v194, v103
	s_and_b64 vcc, vcc, s[4:5]
	v_fmac_f32_e32 v3, 0x3e38aa3b, v81
	ds_read2_b32 v[10:11], v10 offset1:1
	v_cndmask_b32_e32 v3, v237, v3, vcc
	v_cmp_ge_i32_e32 vcc, v195, v102
	v_cmp_lt_i32_e64 s[4:5], v195, v103
	s_and_b64 vcc, vcc, s[4:5]
	v_fmamk_f32 v8, v82, 0x3e38aa3b, v8
	v_cndmask_b32_e32 v8, v237, v8, vcc
	v_cmp_ge_i32_e32 vcc, v196, v102
	v_cmp_lt_i32_e64 s[4:5], v196, v103
	s_and_b64 vcc, vcc, s[4:5]
	v_fmac_f32_e32 v9, 0x3e38aa3b, v83
	ds_read2_b32 v[12:13], v12 offset1:1
	v_cndmask_b32_e32 v9, v237, v9, vcc
	v_cmp_ge_i32_e32 vcc, v197, v102
	v_cmp_lt_i32_e64 s[4:5], v197, v103
	s_and_b64 vcc, vcc, s[4:5]
	s_waitcnt lgkmcnt(0)
	v_fmamk_f32 v10, v84, 0x3e38aa3b, v10
	v_cndmask_b32_e32 v10, v237, v10, vcc
	v_cmp_ge_i32_e32 vcc, v198, v102
	v_cmp_lt_i32_e64 s[4:5], v198, v103
	s_and_b64 vcc, vcc, s[4:5]
	v_fmac_f32_e32 v11, 0x3e38aa3b, v85
	v_cndmask_b32_e32 v11, v237, v11, vcc
	v_cmp_ge_i32_e32 vcc, v199, v102
	v_cmp_lt_i32_e64 s[4:5], v199, v103
	ds_read2_b32 v[14:15], v14 offset1:1
	s_and_b64 vcc, vcc, s[4:5]
	v_fmamk_f32 v12, v86, 0x3e38aa3b, v12
	v_cndmask_b32_e32 v81, v237, v12, vcc
	v_cmp_ge_i32_e32 vcc, v200, v102
	v_cmp_lt_i32_e64 s[4:5], v200, v103
	s_and_b64 vcc, vcc, s[4:5]
	v_fmac_f32_e32 v13, 0x3e38aa3b, v87
	v_max3_f32 v80, v2, s62, v3
	v_cndmask_b32_e32 v82, v237, v13, vcc
	v_add_u32_e32 v13, 16, v190
	ds_read2_b32 v[96:97], v96 offset1:1
	v_max3_f32 v80, v80, v8, v9
	v_cmp_ge_i32_e32 vcc, v13, v102
	v_cmp_lt_i32_e64 s[4:5], v190, v102
	v_max3_f32 v80, v80, v10, v11
	s_and_b64 vcc, vcc, s[4:5]
	s_waitcnt lgkmcnt(0)
	v_fmamk_f32 v13, v88, 0x3e38aa3b, v14
	v_max3_f32 v12, v80, v81, v82
	v_cndmask_b32_e32 v80, v237, v13, vcc
	v_cmp_ge_i32_e32 vcc, v201, v102
	v_cmp_lt_i32_e64 s[4:5], v201, v103
	s_and_b64 vcc, vcc, s[4:5]
	v_fmac_f32_e32 v15, 0x3e38aa3b, v89
	ds_read2_b32 v[98:99], v98 offset1:1
	v_cndmask_b32_e32 v83, v237, v15, vcc
	v_cmp_ge_i32_e32 vcc, v202, v102
	v_cmp_lt_i32_e64 s[4:5], v202, v103
	s_and_b64 vcc, vcc, s[4:5]
	v_fmamk_f32 v13, v90, 0x3e38aa3b, v96
	v_cndmask_b32_e32 v84, v237, v13, vcc
	v_cmp_ge_i32_e32 vcc, v203, v102
	v_cmp_lt_i32_e64 s[4:5], v203, v103
	v_add_u32_e32 v100, 0xf68, v0
	s_and_b64 vcc, vcc, s[4:5]
	v_fmac_f32_e32 v97, 0x3e38aa3b, v91
	ds_read2_b32 v[100:101], v100 offset1:1
	v_cndmask_b32_e32 v85, v237, v97, vcc
	v_cmp_ge_i32_e32 vcc, v204, v102
	v_cmp_lt_i32_e64 s[4:5], v204, v103
	s_and_b64 vcc, vcc, s[4:5]
	s_waitcnt lgkmcnt(0)
	v_fmamk_f32 v13, v92, 0x3e38aa3b, v98
	v_cndmask_b32_e32 v86, v237, v13, vcc
	v_cmp_ge_i32_e32 vcc, v205, v102
	v_cmp_lt_i32_e64 s[4:5], v205, v103
	s_and_b64 vcc, vcc, s[4:5]
	v_fmac_f32_e32 v99, 0x3e38aa3b, v93
	v_cndmask_b32_e32 v87, v237, v99, vcc
	v_cmp_ge_i32_e32 vcc, v206, v102
	v_cmp_lt_i32_e64 s[4:5], v206, v103
	s_and_b64 vcc, vcc, s[4:5]
	v_fmamk_f32 v13, v94, 0x3e38aa3b, v100
	v_max3_f32 v12, v12, v80, v83
	v_cndmask_b32_e32 v88, v237, v13, vcc
	v_cmp_ge_i32_e32 vcc, v207, v102
	v_cmp_lt_i32_e64 s[4:5], v207, v103
	v_max3_f32 v12, v12, v84, v85
	s_and_b64 vcc, vcc, s[4:5]
	v_fmac_f32_e32 v101, 0x3e38aa3b, v95
	v_max3_f32 v12, v12, v86, v87
	v_cndmask_b32_e32 v89, v237, v101, vcc
	v_max3_f32 v12, v12, v88, v89
	v_mov_b32_e32 v13, v12
	s_nop 1
	v_permlane32_swap_b32_e32 v12, v13
	v_max_f32_e32 v12, v12, v13
	v_cmp_gt_f32_e32 vcc, v12, v177
	v_mov_b64_e32 v[110:111], v[46:47]
	v_mov_b64_e32 v[108:109], v[44:45]
	v_cndmask_b32_e32 v230, v227, v12, vcc
	v_sub_f32_e32 v2, v2, v230
	v_exp_f32_e32 v179, v2
	v_sub_f32_e32 v2, v3, v230
	v_exp_f32_e32 v242, v2
	v_sub_f32_e32 v2, v8, v230
	v_exp_f32_e32 v244, v2
	v_sub_f32_e32 v2, v9, v230
	v_exp_f32_e32 v245, v2
	v_sub_f32_e32 v2, v10, v230
	v_exp_f32_e32 v246, v2
	v_sub_f32_e32 v2, v11, v230
	v_exp_f32_e32 v247, v2
	v_sub_f32_e32 v2, v81, v230
	v_exp_f32_e32 v248, v2
	v_sub_f32_e32 v2, v82, v230
	v_exp_f32_e32 v249, v2
	v_sub_f32_e32 v2, v80, v230
	v_exp_f32_e32 v250, v2
	v_sub_f32_e32 v2, v83, v230
	v_exp_f32_e32 v251, v2
	v_sub_f32_e32 v2, v84, v230
	v_exp_f32_e32 v252, v2
	v_sub_f32_e32 v2, v85, v230
	v_exp_f32_e32 v253, v2
	v_sub_f32_e32 v2, v86, v230
	v_sub_f32_e32 v90, v227, v230
	v_exp_f32_e32 v254, v2
	v_sub_f32_e32 v2, v87, v230
	v_exp_f32_e32 v235, v2
	v_sub_f32_e32 v2, v88, v230
	v_exp_f32_e32 v176, v90
	v_exp_f32_e32 v238, v2
	v_sub_f32_e32 v2, v89, v230
	v_exp_f32_e32 v234, v2
	v_cmp_eq_f32_e32 vcc, 1.0, v176
	v_mov_b64_e32 v[94:95], v[30:31]
	s_cmp_eq_u64 vcc, exec
	v_mov_b64_e32 v[106:107], v[42:43]
	v_mov_b64_e32 v[104:105], v[40:41]
	v_mov_b64_e32 v[102:103], v[38:39]
	v_mov_b64_e32 v[100:101], v[36:37]
	v_mov_b64_e32 v[98:99], v[34:35]
	v_mov_b64_e32 v[96:97], v[32:33]
	v_mov_b64_e32 v[92:93], v[28:29]
	v_mov_b64_e32 v[90:91], v[26:27]
	v_mov_b64_e32 v[88:89], v[24:25]
	v_mov_b64_e32 v[86:87], v[22:23]
	v_mov_b64_e32 v[84:85], v[20:21]
	v_mov_b64_e32 v[82:83], v[18:19]
	v_mov_b64_e32 v[80:81], v[16:17]
	v_cvt_pk_bf16_f32 v12, v179, v242
	v_cvt_pk_bf16_f32 v13, v244, v245
	v_cvt_pk_bf16_f32 v14, v246, v247
	v_cvt_pk_bf16_f32 v15, v248, v249
	v_cvt_pk_bf16_f32 v8, v250, v251
	v_cvt_pk_bf16_f32 v9, v252, v253
	v_cvt_pk_bf16_f32 v10, v254, v235
	v_cvt_pk_bf16_f32 v11, v238, v234
	s_cbranch_scc1 .LBB0_781
	v_pk_mul_f32 v[94:95], v[30:31], v[176:177] op_sel_hi:[1,0]
	v_pk_mul_f32 v[92:93], v[28:29], v[176:177] op_sel_hi:[1,0]
	v_pk_mul_f32 v[90:91], v[26:27], v[176:177] op_sel_hi:[1,0]
	v_pk_mul_f32 v[88:89], v[24:25], v[176:177] op_sel_hi:[1,0]
	v_pk_mul_f32 v[86:87], v[22:23], v[176:177] op_sel_hi:[1,0]
	v_pk_mul_f32 v[84:85], v[20:21], v[176:177] op_sel_hi:[1,0]
	v_pk_mul_f32 v[82:83], v[18:19], v[176:177] op_sel_hi:[1,0]
	v_pk_mul_f32 v[80:81], v[16:17], v[176:177] op_sel_hi:[1,0]
	v_pk_mul_f32 v[110:111], v[46:47], v[176:177] op_sel_hi:[1,0]
	v_pk_mul_f32 v[108:109], v[44:45], v[176:177] op_sel_hi:[1,0]
	v_pk_mul_f32 v[106:107], v[42:43], v[176:177] op_sel_hi:[1,0]
	v_pk_mul_f32 v[104:105], v[40:41], v[176:177] op_sel_hi:[1,0]
	v_pk_mul_f32 v[102:103], v[38:39], v[176:177] op_sel_hi:[1,0]
	v_pk_mul_f32 v[100:101], v[36:37], v[176:177] op_sel_hi:[1,0]
	v_pk_mul_f32 v[98:99], v[34:35], v[176:177] op_sel_hi:[1,0]
	v_pk_mul_f32 v[96:97], v[32:33], v[176:177] op_sel_hi:[1,0]
.LBB0_781:
	v_mov_b32_e32 v118, v208
	v_add_u32_e32 v2, 0xee0, v0
	v_add_u32_e32 v0, 0xee8, v0
	ds_read2_b32 v[2:3], v2 offset1:1
	ds_read2_b32 v[116:117], v0 offset1:1
	v_add_u32_e32 v0, 16, v118
	v_cmp_ge_i32_e32 vcc, v204, v118
	v_cmp_lt_i32_e64 s[4:5], v204, v0
	s_waitcnt lgkmcnt(0)
	v_fmamk_f32 v2, v112, 0x3e38aa3b, v2
	s_and_b64 vcc, vcc, s[4:5]
	v_cndmask_b32_e32 v2, v237, v2, vcc
	v_cmp_ge_i32_e32 vcc, v205, v118
	v_cmp_lt_i32_e64 s[4:5], v205, v0
	v_fmac_f32_e32 v3, 0x3e38aa3b, v113
	s_and_b64 vcc, vcc, s[4:5]
	v_cndmask_b32_e32 v3, v237, v3, vcc
	v_cmp_ge_i32_e32 vcc, v206, v118
	v_cmp_lt_i32_e64 s[4:5], v206, v0
	v_fmamk_f32 v113, v114, 0x3e38aa3b, v116
	s_and_b64 vcc, vcc, s[4:5]
	v_cndmask_b32_e32 v113, v237, v113, vcc
	v_cmp_ge_i32_e32 vcc, v207, v118
	v_cmp_lt_i32_e64 s[4:5], v207, v0
	v_fmac_f32_e32 v117, 0x3e38aa3b, v115
	s_and_b64 vcc, vcc, s[4:5]
	v_max3_f32 v112, v2, s62, v3
	v_cndmask_b32_e32 v114, v237, v117, vcc
	v_max3_f32 v0, v112, v113, v114
	v_mov_b32_e32 v112, v0
	s_nop 1
	v_permlane32_swap_b32_e32 v0, v112
	v_max_f32_e32 v0, v0, v112
	v_add_f32_e32 v112, 0x41000000, v228
	v_cmp_gt_f32_e32 vcc, v0, v112
	v_mov_b64_e32 v[142:143], v[78:79]
	v_mov_b64_e32 v[140:141], v[76:77]
	v_cndmask_b32_e32 v240, v228, v0, vcc
	v_sub_f32_e32 v112, v228, v240
	v_sub_f32_e32 v0, v2, v240
	v_sub_f32_e32 v2, v3, v240
	v_exp_f32_e32 v229, v2
	v_sub_f32_e32 v2, v113, v240
	v_exp_f32_e32 v178, v112
	v_exp_f32_e32 v241, v2
	v_sub_f32_e32 v2, v114, v240
	v_exp_f32_e32 v0, v0
	v_exp_f32_e32 v239, v2
	v_cmp_eq_f32_e32 vcc, 1.0, v178
	v_mov_b64_e32 v[126:127], v[62:63]
	s_cmp_eq_u64 vcc, exec
	v_mov_b64_e32 v[138:139], v[74:75]
	v_mov_b64_e32 v[136:137], v[72:73]
	v_mov_b64_e32 v[134:135], v[70:71]
	v_mov_b64_e32 v[132:133], v[68:69]
	v_mov_b64_e32 v[130:131], v[66:67]
	v_mov_b64_e32 v[128:129], v[64:65]
	v_mov_b64_e32 v[124:125], v[60:61]
	v_mov_b64_e32 v[122:123], v[58:59]
	v_mov_b64_e32 v[120:121], v[56:57]
	v_mov_b64_e32 v[118:119], v[54:55]
	v_mov_b64_e32 v[116:117], v[52:53]
	v_mov_b64_e32 v[114:115], v[50:51]
	v_mov_b64_e32 v[112:113], v[48:49]
	v_cvt_pk_bf16_f32 v2, v0, v229
	v_cvt_pk_bf16_f32 v3, v241, v239
	s_cbranch_scc1 .LBB0_783
	v_pk_mul_f32 v[126:127], v[62:63], v[178:179] op_sel_hi:[1,0]
	v_pk_mul_f32 v[124:125], v[60:61], v[178:179] op_sel_hi:[1,0]
	v_pk_mul_f32 v[122:123], v[58:59], v[178:179] op_sel_hi:[1,0]
	v_pk_mul_f32 v[120:121], v[56:57], v[178:179] op_sel_hi:[1,0]
	v_pk_mul_f32 v[118:119], v[54:55], v[178:179] op_sel_hi:[1,0]
	v_pk_mul_f32 v[116:117], v[52:53], v[178:179] op_sel_hi:[1,0]
	v_pk_mul_f32 v[114:115], v[50:51], v[178:179] op_sel_hi:[1,0]
	v_pk_mul_f32 v[112:113], v[48:49], v[178:179] op_sel_hi:[1,0]
	v_pk_mul_f32 v[142:143], v[78:79], v[178:179] op_sel_hi:[1,0]
	v_pk_mul_f32 v[140:141], v[76:77], v[178:179] op_sel_hi:[1,0]
	v_pk_mul_f32 v[138:139], v[74:75], v[178:179] op_sel_hi:[1,0]
	v_pk_mul_f32 v[136:137], v[72:73], v[178:179] op_sel_hi:[1,0]
	v_pk_mul_f32 v[134:135], v[70:71], v[178:179] op_sel_hi:[1,0]
	v_pk_mul_f32 v[132:133], v[68:69], v[178:179] op_sel_hi:[1,0]
	v_pk_mul_f32 v[130:131], v[66:67], v[178:179] op_sel_hi:[1,0]
	v_pk_mul_f32 v[128:129], v[64:65], v[178:179] op_sel_hi:[1,0]
.LBB0_783:
	v_add_f32_e32 v0, v0, v229
	v_add_f32_e32 v229, v241, v239
	v_add_f32_e32 v241, v229, v0
	v_fmac_f32_e32 v241, v192, v178
	v_add_f32_e32 v178, v179, v242
	v_add_f32_e32 v179, v244, v245
	v_add_f32_e32 v178, v179, v178
	v_add_f32_e32 v179, v246, v247
	v_add_f32_e32 v178, v179, v178
	v_add_f32_e32 v179, v248, v249
	v_add_f32_e32 v178, v179, v178
	v_add_f32_e32 v179, v250, v251
	v_add_f32_e32 v178, v179, v178
	v_add_f32_e32 v179, v252, v253
	v_add_f32_e32 v178, v179, v178
	v_add_f32_e32 v179, v254, v235
	v_add_f32_e32 v178, v179, v178
	v_add_f32_e32 v179, v238, v234
	v_add_f32_e32 v242, v179, v178
	v_fmac_f32_e32 v242, v193, v176
	v_add_u32_e32 v176, s60, v183
	ds_read_b64_tr_b16 v[244:245], v176 offset:39936
	ds_read_b64_tr_b16 v[246:247], v176 offset:40448
	ds_read_b64_tr_b16 v[248:249], v176 offset:44032
	ds_read_b64_tr_b16 v[250:251], v176 offset:44544
	s_waitcnt lgkmcnt(2)
	v_mfma_f32_32x32x16_bf16 v[80:95], v[244:247], v[12:15], v[80:95]
	v_mov_b32_e32 v0, v1
	s_mov_b64 s[4:5], 0
	s_waitcnt lgkmcnt(0)
	v_mfma_f32_32x32x16_bf16 v[96:111], v[248:251], v[12:15], v[96:111]
	ds_read_b64_tr_b16 v[12:13], v176 offset:40960
	ds_read_b64_tr_b16 v[14:15], v176 offset:41472
	ds_read_b64_tr_b16 v[244:245], v176 offset:45056
	ds_read_b64_tr_b16 v[246:247], v176 offset:45568
	s_waitcnt lgkmcnt(2)
	v_mfma_f32_32x32x16_bf16 v[80:95], v[12:15], v[8:11], v[80:95]
	s_waitcnt lgkmcnt(0)
	v_mfma_f32_32x32x16_bf16 v[96:111], v[244:247], v[8:11], v[96:111]
	v_mfma_f32_32x32x16_bf16 v[112:127], v[12:15], v[0:3], v[112:127]
	v_mfma_f32_32x32x16_bf16 v[128:143], v[244:247], v[0:3], v[128:143]
.LBB0_784:
	s_and_b64 vcc, exec, s[4:5]
	s_cbranch_vccz .LBB0_790
	s_waitcnt lgkmcnt(0)
	v_mfma_f32_32x32x16_bf16 v[80:95], v[4:7], v[144:147], 0
	ds_read_b128 v[2:5], v226 offset:32
	s_waitcnt lgkmcnt(0)
	v_mfma_f32_32x32x16_bf16 v[80:95], v[2:5], v[148:151], v[80:95]
	ds_read_b128 v[2:5], v226 offset:64
	s_waitcnt lgkmcnt(0)
	v_mfma_f32_32x32x16_bf16 v[80:95], v[2:5], v[152:155], v[80:95]
	ds_read_b128 v[2:5], v226 offset:96
	s_waitcnt lgkmcnt(0)
	v_mfma_f32_32x32x16_bf16 v[80:95], v[2:5], v[156:159], v[80:95]
	ds_read_b128 v[2:5], v226
	ds_read_b128 v[6:9], v226 offset:32
	ds_read_b128 v[10:13], v226 offset:64
	ds_read_b128 v[96:99], v226 offset:96
	s_waitcnt lgkmcnt(0)
	v_mfma_f32_32x32x16_bf16 v[112:127], v[2:5], v[160:163], 0
	s_nop 5
	v_max3_f32 v0, v80, s62, v81
	v_max3_f32 v0, v0, v82, v83
	v_max3_f32 v0, v0, v84, v85
	v_max3_f32 v0, v0, v86, v87
	v_max3_f32 v0, v0, v88, v89
	v_max3_f32 v0, v0, v90, v91
	v_max3_f32 v0, v0, v92, v93
	v_max3_f32 v0, v0, v94, v95
	v_mov_b32_e32 v2, v0
	s_nop 1
	v_permlane32_swap_b32_e32 v0, v2
	v_max_f32_e32 v0, v0, v2
	v_mul_f32_e32 v0, 0x3e38aa3b, v0
	v_mfma_f32_32x32x16_bf16 v[112:127], v[6:9], v[164:167], v[112:127]
	v_cmp_gt_f32_e32 vcc, v0, v177
	s_nop 1
	v_cndmask_b32_e32 v230, v227, v0, vcc
	v_sub_f32_e32 v0, v227, v230
	v_fma_f32 v2, v80, s91, -v230
	v_fma_f32 v3, v81, s91, -v230
	v_fma_f32 v4, v82, s91, -v230
	v_fma_f32 v5, v83, s91, -v230
	v_fma_f32 v6, v84, s91, -v230
	v_fma_f32 v7, v85, s91, -v230
	v_fma_f32 v8, v86, s91, -v230
	v_fma_f32 v9, v87, s91, -v230
	v_fma_f32 v14, v88, s91, -v230
	v_fma_f32 v15, v89, s91, -v230
	v_fma_f32 v84, v90, s91, -v230
	v_mfma_f32_32x32x16_bf16 v[112:127], v[10:13], v[168:171], v[112:127]
	v_fma_f32 v85, v91, s91, -v230
	v_fma_f32 v10, v92, s91, -v230
	v_fma_f32 v11, v93, s91, -v230
	v_fma_f32 v12, v94, s91, -v230
	v_fma_f32 v13, v95, s91, -v230
	v_exp_f32_e32 v0, v0
	v_exp_f32_e32 v140, v2
	v_mfma_f32_32x32x16_bf16 v[112:127], v[96:99], v[172:175], v[112:127]
	v_exp_f32_e32 v177, v3
	v_exp_f32_e32 v141, v4
	v_exp_f32_e32 v178, v5
	v_exp_f32_e32 v136, v6
	v_exp_f32_e32 v138, v7
	v_exp_f32_e32 v137, v8
	v_exp_f32_e32 v139, v9
	v_exp_f32_e32 v244, v14
	v_exp_f32_e32 v245, v15
	v_exp_f32_e32 v142, v84
	v_exp_f32_e32 v179, v85
	v_exp_f32_e32 v143, v10
	v_exp_f32_e32 v227, v11
	v_exp_f32_e32 v176, v12
	v_exp_f32_e32 v242, v13
	v_cvt_pk_bf16_f32 v80, v140, v177
	v_cvt_pk_bf16_f32 v81, v141, v178
	v_cvt_pk_bf16_f32 v82, v136, v138
	v_cvt_pk_bf16_f32 v83, v137, v139
	v_cvt_pk_bf16_f32 v132, v244, v245
	v_cvt_pk_bf16_f32 v133, v142, v179
	v_cvt_pk_bf16_f32 v134, v143, v227
	v_cvt_pk_bf16_f32 v135, v176, v242
	v_cmp_eq_f32_e32 vcc, 1.0, v0
	s_cmp_eq_u64 vcc, exec
	s_cbranch_scc1 .LBB0_787
	v_pk_mul_f32 v[30:31], v[30:31], v[0:1] op_sel_hi:[1,0]
	v_pk_mul_f32 v[28:29], v[28:29], v[0:1] op_sel_hi:[1,0]
	v_pk_mul_f32 v[26:27], v[26:27], v[0:1] op_sel_hi:[1,0]
	v_pk_mul_f32 v[24:25], v[24:25], v[0:1] op_sel_hi:[1,0]
	v_pk_mul_f32 v[22:23], v[22:23], v[0:1] op_sel_hi:[1,0]
	v_pk_mul_f32 v[20:21], v[20:21], v[0:1] op_sel_hi:[1,0]
	v_pk_mul_f32 v[18:19], v[18:19], v[0:1] op_sel_hi:[1,0]
	v_pk_mul_f32 v[16:17], v[16:17], v[0:1] op_sel_hi:[1,0]
	v_pk_mul_f32 v[46:47], v[46:47], v[0:1] op_sel_hi:[1,0]
	v_pk_mul_f32 v[44:45], v[44:45], v[0:1] op_sel_hi:[1,0]
	v_pk_mul_f32 v[42:43], v[42:43], v[0:1] op_sel_hi:[1,0]
	v_pk_mul_f32 v[40:41], v[40:41], v[0:1] op_sel_hi:[1,0]
	v_pk_mul_f32 v[38:39], v[38:39], v[0:1] op_sel_hi:[1,0]
	v_pk_mul_f32 v[36:37], v[36:37], v[0:1] op_sel_hi:[1,0]
	v_pk_mul_f32 v[34:35], v[34:35], v[0:1] op_sel_hi:[1,0]
	v_pk_mul_f32 v[32:33], v[32:33], v[0:1] op_sel_hi:[1,0]
.LBB0_787:
	v_add_u32_e32 v4, s60, v183
	ds_read_b64_tr_b16 v[10:11], v4 offset:39936
	ds_read_b64_tr_b16 v[12:13], v4 offset:40448
	ds_read_b64_tr_b16 v[6:7], v4 offset:40960
	ds_read_b64_tr_b16 v[8:9], v4 offset:41472
	ds_read_b64_tr_b16 v[128:129], v4 offset:44032
	ds_read_b64_tr_b16 v[130:131], v4 offset:44544
	ds_read_b64_tr_b16 v[2:3], v4 offset:45056
	ds_read_b64_tr_b16 v[4:5], v4 offset:45568
	s_waitcnt lgkmcnt(6)
	v_mfma_f32_32x32x16_bf16 v[16:31], v[10:13], v[80:83], v[16:31]
	v_max3_f32 v14, v112, s62, v113
	v_max3_f32 v14, v14, v114, v115
	v_max3_f32 v14, v14, v116, v117
	v_max3_f32 v14, v14, v118, v119
	v_max3_f32 v14, v14, v120, v121
	v_max3_f32 v14, v14, v122, v123
	v_max3_f32 v14, v14, v124, v125
	v_max3_f32 v14, v14, v126, v127
	v_mov_b32_e32 v15, v14
	s_nop 1
	v_permlane32_swap_b32_e32 v14, v15
	v_max_f32_e32 v14, v14, v15
	v_mul_f32_e32 v14, 0x3e38aa3b, v14
	v_add_f32_e32 v15, 0x41000000, v228
	v_cmp_gt_f32_e32 vcc, v14, v15
	s_nop 1
	v_cndmask_b32_e32 v240, v228, v14, vcc
	v_sub_f32_e32 v14, v228, v240
	v_fma_f32 v15, v114, s91, -v240
	s_waitcnt lgkmcnt(2)
	v_mfma_f32_32x32x16_bf16 v[32:47], v[128:131], v[80:83], v[32:47]
	v_mov_b64_e32 v[94:95], v[30:31]
	v_mov_b64_e32 v[92:93], v[28:29]
	v_mov_b64_e32 v[90:91], v[26:27]
	v_mov_b64_e32 v[88:89], v[24:25]
	v_mov_b64_e32 v[86:87], v[22:23]
	v_mov_b64_e32 v[84:85], v[20:21]
	v_mov_b64_e32 v[82:83], v[18:19]
	v_mov_b64_e32 v[80:81], v[16:17]
	s_nop 3
	v_mov_b64_e32 v[110:111], v[46:47]
	v_exp_f32_e32 v22, v14
	v_fma_f32 v14, v112, s91, -v240
	v_mov_b64_e32 v[108:109], v[44:45]
	v_mov_b64_e32 v[106:107], v[42:43]
	v_mov_b64_e32 v[104:105], v[40:41]
	v_mov_b64_e32 v[102:103], v[38:39]
	v_mov_b64_e32 v[100:101], v[36:37]
	v_mov_b64_e32 v[98:99], v[34:35]
	v_mov_b64_e32 v[96:97], v[32:33]
	v_exp_f32_e32 v23, v14
	v_fma_f32 v14, v113, s91, -v240
	v_exp_f32_e32 v25, v15
	v_fma_f32 v15, v115, s91, -v240
	v_fma_f32 v16, v116, s91, -v240
	v_mfma_f32_32x32x16_bf16 v[80:95], v[6:9], v[132:135], v[80:95]
	v_fma_f32 v17, v118, s91, -v240
	v_fma_f32 v18, v120, s91, -v240
	v_fma_f32 v19, v122, s91, -v240
	v_fma_f32 v20, v124, s91, -v240
	v_fma_f32 v21, v126, s91, -v240
	v_exp_f32_e32 v27, v16
	v_fma_f32 v16, v117, s91, -v240
	v_exp_f32_e32 v29, v17
	v_fma_f32 v17, v119, s91, -v240
	v_exp_f32_e32 v31, v18
	v_fma_f32 v18, v121, s91, -v240
	v_exp_f32_e32 v33, v19
	v_fma_f32 v19, v123, s91, -v240
	v_exp_f32_e32 v36, v20
	v_fma_f32 v20, v125, s91, -v240
	v_exp_f32_e32 v34, v21
	v_fma_f32 v21, v127, s91, -v240
	s_waitcnt lgkmcnt(0)
	v_mfma_f32_32x32x16_bf16 v[96:111], v[2:5], v[132:135], v[96:111]
	v_exp_f32_e32 v24, v14
	v_exp_f32_e32 v26, v15
	v_exp_f32_e32 v28, v16
	v_exp_f32_e32 v30, v17
	v_exp_f32_e32 v32, v18
	v_exp_f32_e32 v35, v19
	v_exp_f32_e32 v37, v20
	v_exp_f32_e32 v38, v21
	v_cvt_pk_bf16_f32 v14, v23, v24
	v_cvt_pk_bf16_f32 v15, v25, v26
	v_cvt_pk_bf16_f32 v16, v27, v28
	v_cvt_pk_bf16_f32 v17, v29, v30
	v_cvt_pk_bf16_f32 v18, v31, v32
	v_cvt_pk_bf16_f32 v19, v33, v35
	v_cvt_pk_bf16_f32 v20, v36, v37
	v_cvt_pk_bf16_f32 v21, v34, v38
	v_cmp_eq_f32_e32 vcc, 1.0, v22
	s_cmp_eq_u64 vcc, exec
	s_cbranch_scc1 .LBB0_789
	v_pk_mul_f32 v[62:63], v[62:63], v[22:23] op_sel_hi:[1,0]
	v_pk_mul_f32 v[60:61], v[60:61], v[22:23] op_sel_hi:[1,0]
	v_pk_mul_f32 v[58:59], v[58:59], v[22:23] op_sel_hi:[1,0]
	v_pk_mul_f32 v[56:57], v[56:57], v[22:23] op_sel_hi:[1,0]
	v_pk_mul_f32 v[54:55], v[54:55], v[22:23] op_sel_hi:[1,0]
	v_pk_mul_f32 v[52:53], v[52:53], v[22:23] op_sel_hi:[1,0]
	v_pk_mul_f32 v[50:51], v[50:51], v[22:23] op_sel_hi:[1,0]
	v_pk_mul_f32 v[48:49], v[48:49], v[22:23] op_sel_hi:[1,0]
	v_pk_mul_f32 v[78:79], v[78:79], v[22:23] op_sel_hi:[1,0]
	v_pk_mul_f32 v[76:77], v[76:77], v[22:23] op_sel_hi:[1,0]
	v_pk_mul_f32 v[74:75], v[74:75], v[22:23] op_sel_hi:[1,0]
	v_pk_mul_f32 v[72:73], v[72:73], v[22:23] op_sel_hi:[1,0]
	v_pk_mul_f32 v[70:71], v[70:71], v[22:23] op_sel_hi:[1,0]
	v_pk_mul_f32 v[68:69], v[68:69], v[22:23] op_sel_hi:[1,0]
	v_pk_mul_f32 v[66:67], v[66:67], v[22:23] op_sel_hi:[1,0]
	v_pk_mul_f32 v[64:65], v[64:65], v[22:23] op_sel_hi:[1,0]
.LBB0_789:
	v_add_f32_e32 v23, v23, v24
	v_mfma_f32_32x32x16_bf16 v[48:63], v[10:13], v[14:17], v[48:63]
	v_add_f32_e32 v24, v25, v26
	v_add_f32_e32 v23, v24, v23
	v_add_f32_e32 v24, v27, v28
	v_add_f32_e32 v23, v24, v23
	v_add_f32_e32 v24, v29, v30
	v_add_f32_e32 v23, v24, v23
	v_mfma_f32_32x32x16_bf16 v[64:79], v[128:131], v[14:17], v[64:79]
	v_add_f32_e32 v24, v31, v32
	v_add_f32_e32 v23, v24, v23
	v_add_f32_e32 v24, v33, v35
	v_add_f32_e32 v23, v24, v23
	v_add_f32_e32 v24, v36, v37
	v_add_f32_e32 v10, v24, v23
	v_add_f32_e32 v11, v34, v38
	v_add_f32_e32 v241, v11, v10
	v_add_f32_e32 v10, v140, v177
	v_mfma_f32_32x32x16_bf16 v[48:63], v[6:9], v[18:21], v[48:63]
	v_add_f32_e32 v11, v141, v178
	v_add_f32_e32 v10, v11, v10
	v_add_f32_e32 v11, v136, v138
	v_add_f32_e32 v10, v11, v10
	v_add_f32_e32 v11, v137, v139
	v_add_f32_e32 v10, v11, v10
	v_mfma_f32_32x32x16_bf16 v[64:79], v[2:5], v[18:21], v[64:79]
	v_add_f32_e32 v11, v244, v245
	v_add_f32_e32 v10, v11, v10
	v_add_f32_e32 v6, v142, v179
	v_add_f32_e32 v6, v6, v10
	v_add_f32_e32 v7, v143, v227
	v_add_f32_e32 v6, v7, v6
	v_add_f32_e32 v7, v176, v242
	v_add_f32_e32 v242, v7, v6
	v_mov_b64_e32 v[126:127], v[62:63]
	s_nop 2
	v_mov_b64_e32 v[142:143], v[78:79]
	v_fmac_f32_e32 v241, v192, v22
	v_fmac_f32_e32 v242, v193, v0
	v_mov_b64_e32 v[124:125], v[60:61]
	v_mov_b64_e32 v[122:123], v[58:59]
	v_mov_b64_e32 v[120:121], v[56:57]
	v_mov_b64_e32 v[118:119], v[54:55]
	v_mov_b64_e32 v[116:117], v[52:53]
	v_mov_b64_e32 v[114:115], v[50:51]
	v_mov_b64_e32 v[112:113], v[48:49]
	v_mov_b64_e32 v[140:141], v[76:77]
	v_mov_b64_e32 v[138:139], v[74:75]
	v_mov_b64_e32 v[136:137], v[72:73]
	v_mov_b64_e32 v[134:135], v[70:71]
	v_mov_b64_e32 v[132:133], v[68:69]
	v_mov_b64_e32 v[130:131], v[66:67]
	v_mov_b64_e32 v[128:129], v[64:65]
.LBB0_790:
	ds_read_b128 v[176:179], v226 offset:4608
	s_mov_b64 s[4:5], -1
	s_andn2_b64 vcc, exec, s[26:27]
	v_add_f32_e32 v244, 0x41000000, v230
	s_cbranch_vccnz .LBB0_796
	s_waitcnt lgkmcnt(0)
	v_mfma_f32_32x32x16_bf16 v[2:17], v[176:179], v[144:147], 0
	ds_read_b128 v[18:21], v226 offset:4640
	ds_read_b128 v[22:25], v226 offset:4672
	v_mov_b32_e32 v0, v191
	v_mov_b64_e32 v[32:33], v[96:97]
	v_mov_b64_e32 v[34:35], v[98:99]
	v_mov_b64_e32 v[36:37], v[100:101]
	v_mov_b64_e32 v[38:39], v[102:103]
	v_mov_b64_e32 v[40:41], v[104:105]
	v_mfma_f32_32x32x16_bf16 v[48:63], v[176:179], v[160:163], 0
	v_mov_b64_e32 v[42:43], v[106:107]
	v_mov_b64_e32 v[44:45], v[108:109]
	v_mov_b64_e32 v[46:47], v[110:111]
	s_waitcnt lgkmcnt(0)
	v_mfma_f32_32x32x16_bf16 v[2:17], v[18:21], v[148:151], v[2:17]
	v_mfma_f32_32x32x16_bf16 v[48:63], v[18:21], v[164:167], v[48:63]
	ds_read_b128 v[18:21], v226 offset:4704
	s_nop 0
	v_cmp_ge_i32_e32 vcc, v209, v0
	v_mfma_f32_32x32x16_bf16 v[2:17], v[22:25], v[152:155], v[2:17]
	s_waitcnt lgkmcnt(0)
	v_mfma_f32_32x32x16_bf16 v[2:17], v[18:21], v[156:159], v[2:17]
	v_mfma_f32_32x32x16_bf16 v[48:63], v[22:25], v[168:171], v[48:63]
	s_nop 10
	v_add3_u32 v6, s61, v225, v243
	v_add_u32_e32 v7, 0xf80, v6
	ds_read2_b32 v[8:9], v7 offset1:1
	v_add_u32_e32 v7, 0xf88, v6
	ds_read2_b32 v[10:11], v7 offset1:1
	v_add_u32_e32 v7, 16, v0
	v_cmp_lt_i32_e64 s[4:5], v209, v7
	s_and_b64 vcc, vcc, s[4:5]
	s_waitcnt lgkmcnt(0)
	v_fmamk_f32 v2, v2, 0x3e38aa3b, v8
	v_cndmask_b32_e32 v2, v237, v2, vcc
	v_cmp_ge_i32_e32 vcc, v210, v0
	v_cmp_lt_i32_e64 s[4:5], v210, v7
	s_and_b64 vcc, vcc, s[4:5]
	v_fmac_f32_e32 v9, 0x3e38aa3b, v3
	v_cndmask_b32_e32 v3, v237, v9, vcc
	v_cmp_ge_i32_e32 vcc, v211, v0
	v_cmp_lt_i32_e64 s[4:5], v211, v7
	s_and_b64 vcc, vcc, s[4:5]
	v_fmamk_f32 v4, v4, 0x3e38aa3b, v10
	v_cndmask_b32_e32 v4, v237, v4, vcc
	v_cmp_ge_i32_e32 vcc, v212, v0
	v_cmp_lt_i32_e64 s[4:5], v212, v7
	s_and_b64 vcc, vcc, s[4:5]
	v_fmac_f32_e32 v11, 0x3e38aa3b, v5
	v_max3_f32 v8, v2, s62, v3
	v_cndmask_b32_e32 v0, v237, v11, vcc
	v_max3_f32 v5, v8, v4, v0
	v_mov_b32_e32 v7, v5
	s_nop 1
	v_permlane32_swap_b32_e32 v5, v7
	v_max_f32_e32 v5, v5, v7
	v_cmp_gt_f32_e32 vcc, v5, v244
	v_mfma_f32_32x32x16_bf16 v[48:63], v[18:21], v[172:175], v[48:63]
	v_mov_b64_e32 v[16:17], v[80:81]
	v_cndmask_b32_e32 v227, v230, v5, vcc
	v_sub_f32_e32 v7, v230, v227
	v_sub_f32_e32 v0, v0, v227
	v_sub_f32_e32 v2, v2, v227
	v_exp_f32_e32 v193, v0
	v_exp_f32_e32 v0, v7
	v_exp_f32_e32 v5, v2
	v_sub_f32_e32 v2, v3, v227
	v_sub_f32_e32 v3, v4, v227
	v_exp_f32_e32 v14, v2
	v_exp_f32_e32 v15, v3
	v_cmp_eq_f32_e32 vcc, 1.0, v0
	s_cmp_eq_u64 vcc, exec
	v_mov_b64_e32 v[18:19], v[82:83]
	v_mov_b64_e32 v[20:21], v[84:85]
	v_mov_b64_e32 v[22:23], v[86:87]
	v_mov_b64_e32 v[24:25], v[88:89]
	v_mov_b64_e32 v[26:27], v[90:91]
	v_mov_b64_e32 v[28:29], v[92:93]
	v_mov_b64_e32 v[30:31], v[94:95]
	v_cvt_pk_bf16_f32 v2, v5, v14
	v_cvt_pk_bf16_f32 v3, v15, v193
	s_cbranch_scc1 .LBB0_793
	v_pk_mul_f32 v[30:31], v[94:95], v[0:1] op_sel_hi:[1,0]
	v_pk_mul_f32 v[28:29], v[92:93], v[0:1] op_sel_hi:[1,0]
	v_pk_mul_f32 v[26:27], v[90:91], v[0:1] op_sel_hi:[1,0]
	v_pk_mul_f32 v[24:25], v[88:89], v[0:1] op_sel_hi:[1,0]
	v_pk_mul_f32 v[22:23], v[86:87], v[0:1] op_sel_hi:[1,0]
	v_pk_mul_f32 v[20:21], v[84:85], v[0:1] op_sel_hi:[1,0]
	v_pk_mul_f32 v[18:19], v[82:83], v[0:1] op_sel_hi:[1,0]
	v_pk_mul_f32 v[16:17], v[80:81], v[0:1] op_sel_hi:[1,0]
	v_pk_mul_f32 v[46:47], v[110:111], v[0:1] op_sel_hi:[1,0]
	v_pk_mul_f32 v[44:45], v[108:109], v[0:1] op_sel_hi:[1,0]
	v_pk_mul_f32 v[42:43], v[106:107], v[0:1] op_sel_hi:[1,0]
	v_pk_mul_f32 v[40:41], v[104:105], v[0:1] op_sel_hi:[1,0]
	v_pk_mul_f32 v[38:39], v[102:103], v[0:1] op_sel_hi:[1,0]
	v_pk_mul_f32 v[36:37], v[100:101], v[0:1] op_sel_hi:[1,0]
	v_pk_mul_f32 v[34:35], v[98:99], v[0:1] op_sel_hi:[1,0]
	v_pk_mul_f32 v[32:33], v[96:97], v[0:1] op_sel_hi:[1,0]
.LBB0_793:
	v_mov_b32_e32 v4, v208
	v_add_u32_e32 v7, 0xf00, v6
	v_add_u32_e32 v10, 0xf08, v6
	v_add_u32_e32 v12, 0xf20, v6
	v_add_u32_e32 v64, 0xf28, v6
	ds_read2_b32 v[8:9], v7 offset1:1
	ds_read2_b32 v[10:11], v10 offset1:1
	ds_read2_b32 v[12:13], v12 offset1:1
	ds_read2_b32 v[64:65], v64 offset1:1
	v_add_u32_e32 v72, 16, v4
	v_cmp_ge_i32_e32 vcc, v209, v4
	v_cmp_lt_i32_e64 s[4:5], v209, v72
	s_waitcnt lgkmcnt(0)
	v_fmamk_f32 v8, v48, 0x3e38aa3b, v8
	s_and_b64 vcc, vcc, s[4:5]
	v_cndmask_b32_e32 v8, v237, v8, vcc
	v_cmp_ge_i32_e32 vcc, v210, v4
	v_cmp_lt_i32_e64 s[4:5], v210, v72
	v_fmac_f32_e32 v9, 0x3e38aa3b, v49
	s_and_b64 vcc, vcc, s[4:5]
	v_cndmask_b32_e32 v9, v237, v9, vcc
	v_cmp_ge_i32_e32 vcc, v211, v4
	v_cmp_lt_i32_e64 s[4:5], v211, v72
	v_fmamk_f32 v10, v50, 0x3e38aa3b, v10
	s_and_b64 vcc, vcc, s[4:5]
	v_cndmask_b32_e32 v49, v237, v10, vcc
	v_cmp_ge_i32_e32 vcc, v212, v4
	v_cmp_lt_i32_e64 s[4:5], v212, v72
	v_fmac_f32_e32 v11, 0x3e38aa3b, v51
	s_and_b64 vcc, vcc, s[4:5]
	v_cndmask_b32_e32 v11, v237, v11, vcc
	v_cmp_ge_i32_e32 vcc, v213, v4
	v_cmp_lt_i32_e64 s[4:5], v213, v72
	v_fmamk_f32 v12, v52, 0x3e38aa3b, v12
	s_and_b64 vcc, vcc, s[4:5]
	v_cndmask_b32_e32 v12, v237, v12, vcc
	v_cmp_ge_i32_e32 vcc, v214, v4
	v_cmp_lt_i32_e64 s[4:5], v214, v72
	v_fmac_f32_e32 v13, 0x3e38aa3b, v53
	s_and_b64 vcc, vcc, s[4:5]
	v_max3_f32 v48, v8, s62, v9
	v_cndmask_b32_e32 v13, v237, v13, vcc
	v_cmp_ge_i32_e32 vcc, v215, v4
	v_cmp_lt_i32_e64 s[4:5], v215, v72
	v_max3_f32 v10, v48, v49, v11
	v_fmamk_f32 v48, v54, 0x3e38aa3b, v64
	s_and_b64 vcc, vcc, s[4:5]
	v_add_u32_e32 v7, 0xf40, v6
	v_add_u32_e32 v66, 0xf48, v6
	v_add_u32_e32 v68, 0xf60, v6
	v_add_u32_e32 v70, 0xf68, v6
	v_cndmask_b32_e32 v48, v237, v48, vcc
	v_cmp_ge_i32_e32 vcc, v216, v4
	v_cmp_lt_i32_e64 s[4:5], v216, v72
	ds_read2_b32 v[6:7], v7 offset1:1
	ds_read2_b32 v[66:67], v66 offset1:1
	ds_read2_b32 v[68:69], v68 offset1:1
	ds_read2_b32 v[70:71], v70 offset1:1
	v_fmac_f32_e32 v65, 0x3e38aa3b, v55
	s_and_b64 vcc, vcc, s[4:5]
	v_cndmask_b32_e32 v50, v237, v65, vcc
	v_cmp_ge_i32_e32 vcc, v217, v4
	v_cmp_lt_i32_e64 s[4:5], v217, v72
	s_waitcnt lgkmcnt(0)
	v_fmamk_f32 v6, v56, 0x3e38aa3b, v6
	s_and_b64 vcc, vcc, s[4:5]
	v_cndmask_b32_e32 v6, v237, v6, vcc
	v_cmp_ge_i32_e32 vcc, v218, v4
	v_cmp_lt_i32_e64 s[4:5], v218, v72
	v_fmac_f32_e32 v7, 0x3e38aa3b, v57
	s_and_b64 vcc, vcc, s[4:5]
	v_cndmask_b32_e32 v7, v237, v7, vcc
	v_cmp_ge_i32_e32 vcc, v219, v4
	v_cmp_lt_i32_e64 s[4:5], v219, v72
	v_fmamk_f32 v51, v58, 0x3e38aa3b, v66
	s_and_b64 vcc, vcc, s[4:5]
	v_cndmask_b32_e32 v51, v237, v51, vcc
	v_cmp_ge_i32_e32 vcc, v220, v4
	v_cmp_lt_i32_e64 s[4:5], v220, v72
	v_fmac_f32_e32 v67, 0x3e38aa3b, v59
	s_and_b64 vcc, vcc, s[4:5]
	v_cndmask_b32_e32 v52, v237, v67, vcc
	v_cmp_ge_i32_e32 vcc, v221, v4
	v_cmp_lt_i32_e64 s[4:5], v221, v72
	v_fmamk_f32 v53, v60, 0x3e38aa3b, v68
	s_and_b64 vcc, vcc, s[4:5]
	v_cndmask_b32_e32 v53, v237, v53, vcc
	v_cmp_ge_i32_e32 vcc, v222, v4
	v_cmp_lt_i32_e64 s[4:5], v222, v72
	v_fmac_f32_e32 v69, 0x3e38aa3b, v61
	s_and_b64 vcc, vcc, s[4:5]
	v_max3_f32 v10, v10, v12, v13
	v_cndmask_b32_e32 v54, v237, v69, vcc
	v_cmp_ge_i32_e32 vcc, v223, v4
	v_cmp_lt_i32_e64 s[4:5], v223, v72
	v_max3_f32 v10, v10, v48, v50
	v_fmamk_f32 v55, v62, 0x3e38aa3b, v70
	s_and_b64 vcc, vcc, s[4:5]
	v_max3_f32 v10, v10, v6, v7
	v_cndmask_b32_e32 v55, v237, v55, vcc
	v_cmp_ge_i32_e32 vcc, v224, v4
	v_cmp_lt_i32_e64 s[4:5], v224, v72
	v_max3_f32 v10, v10, v51, v52
	v_fmac_f32_e32 v71, 0x3e38aa3b, v63
	s_and_b64 vcc, vcc, s[4:5]
	v_max3_f32 v10, v10, v53, v54
	v_cndmask_b32_e32 v4, v237, v71, vcc
	v_max3_f32 v10, v10, v55, v4
	v_mov_b32_e32 v56, v10
	s_nop 1
	v_permlane32_swap_b32_e32 v10, v56
	v_max_f32_e32 v10, v10, v56
	v_add_f32_e32 v56, 0x41000000, v240
	v_cmp_gt_f32_e32 vcc, v10, v56
	v_mov_b64_e32 v[64:65], v[128:129]
	v_mov_b64_e32 v[66:67], v[130:131]
	v_cndmask_b32_e32 v228, v240, v10, vcc
	v_sub_f32_e32 v8, v8, v228
	v_exp_f32_e32 v192, v8
	v_sub_f32_e32 v8, v9, v228
	v_sub_f32_e32 v9, v49, v228
	v_sub_f32_e32 v6, v6, v228
	v_exp_f32_e32 v235, v9
	v_sub_f32_e32 v9, v11, v228
	v_exp_f32_e32 v248, v6
	v_sub_f32_e32 v6, v7, v228
	v_sub_f32_e32 v7, v51, v228
	v_exp_f32_e32 v238, v9
	v_sub_f32_e32 v9, v12, v228
	v_exp_f32_e32 v250, v7
	v_sub_f32_e32 v7, v52, v228
	v_exp_f32_e32 v234, v8
	v_sub_f32_e32 v8, v240, v228
	v_exp_f32_e32 v243, v9
	v_sub_f32_e32 v9, v13, v228
	v_exp_f32_e32 v251, v7
	v_sub_f32_e32 v7, v53, v228
	v_sub_f32_e32 v4, v4, v228
	v_exp_f32_e32 v245, v9
	v_sub_f32_e32 v9, v48, v228
	v_exp_f32_e32 v252, v7
	v_sub_f32_e32 v7, v54, v228
	v_exp_f32_e32 v229, v4
	v_exp_f32_e32 v4, v8
	v_exp_f32_e32 v246, v9
	v_sub_f32_e32 v9, v50, v228
	v_exp_f32_e32 v253, v7
	v_sub_f32_e32 v7, v55, v228
	v_exp_f32_e32 v247, v9
	v_exp_f32_e32 v249, v6
	v_exp_f32_e32 v254, v7
	v_cmp_eq_f32_e32 vcc, 1.0, v4
	v_mov_b64_e32 v[48:49], v[112:113]
	s_cmp_eq_u64 vcc, exec
	v_mov_b64_e32 v[68:69], v[132:133]
	v_mov_b64_e32 v[70:71], v[134:135]
	v_mov_b64_e32 v[72:73], v[136:137]
	v_mov_b64_e32 v[74:75], v[138:139]
	v_mov_b64_e32 v[76:77], v[140:141]
	v_mov_b64_e32 v[78:79], v[142:143]
	v_mov_b64_e32 v[50:51], v[114:115]
	v_mov_b64_e32 v[52:53], v[116:117]
	v_mov_b64_e32 v[54:55], v[118:119]
	v_mov_b64_e32 v[56:57], v[120:121]
	v_mov_b64_e32 v[58:59], v[122:123]
	v_mov_b64_e32 v[60:61], v[124:125]
	v_mov_b64_e32 v[62:63], v[126:127]
	v_cvt_pk_bf16_f32 v10, v192, v234
	v_cvt_pk_bf16_f32 v11, v235, v238
	v_cvt_pk_bf16_f32 v12, v243, v245
	v_cvt_pk_bf16_f32 v13, v246, v247
	v_cvt_pk_bf16_f32 v6, v248, v249
	v_cvt_pk_bf16_f32 v7, v250, v251
	v_cvt_pk_bf16_f32 v8, v252, v253
	v_cvt_pk_bf16_f32 v9, v254, v229
	s_cbranch_scc1 .LBB0_795
	v_pk_mul_f32 v[62:63], v[126:127], v[4:5] op_sel_hi:[1,0]
	v_pk_mul_f32 v[60:61], v[124:125], v[4:5] op_sel_hi:[1,0]
	v_pk_mul_f32 v[58:59], v[122:123], v[4:5] op_sel_hi:[1,0]
	v_pk_mul_f32 v[56:57], v[120:121], v[4:5] op_sel_hi:[1,0]
	v_pk_mul_f32 v[54:55], v[118:119], v[4:5] op_sel_hi:[1,0]
	v_pk_mul_f32 v[52:53], v[116:117], v[4:5] op_sel_hi:[1,0]
	v_pk_mul_f32 v[50:51], v[114:115], v[4:5] op_sel_hi:[1,0]
	v_pk_mul_f32 v[48:49], v[112:113], v[4:5] op_sel_hi:[1,0]
	v_pk_mul_f32 v[78:79], v[142:143], v[4:5] op_sel_hi:[1,0]
	v_pk_mul_f32 v[76:77], v[140:141], v[4:5] op_sel_hi:[1,0]
	v_pk_mul_f32 v[74:75], v[138:139], v[4:5] op_sel_hi:[1,0]
	v_pk_mul_f32 v[72:73], v[136:137], v[4:5] op_sel_hi:[1,0]
	v_pk_mul_f32 v[70:71], v[134:135], v[4:5] op_sel_hi:[1,0]
	v_pk_mul_f32 v[68:69], v[132:133], v[4:5] op_sel_hi:[1,0]
	v_pk_mul_f32 v[66:67], v[130:131], v[4:5] op_sel_hi:[1,0]
	v_pk_mul_f32 v[64:65], v[128:129], v[4:5] op_sel_hi:[1,0]
.LBB0_795:
	v_add_f32_e32 v192, v192, v234
	v_add_f32_e32 v234, v235, v238
	v_add_f32_e32 v192, v234, v192
	v_add_f32_e32 v234, v243, v245
	v_add_f32_e32 v192, v234, v192
	v_add_f32_e32 v234, v246, v247
	v_add_f32_e32 v192, v234, v192
	v_add_f32_e32 v234, v248, v249
	v_add_f32_e32 v192, v234, v192
	v_add_f32_e32 v234, v250, v251
	v_add_f32_e32 v192, v234, v192
	v_add_f32_e32 v234, v252, v253
	v_add_f32_e32 v192, v234, v192
	v_add_f32_e32 v229, v254, v229
	v_add_f32_e32 v192, v229, v192
	v_fmac_f32_e32 v192, v241, v4
	v_add_f32_e32 v4, v5, v14
	v_add_f32_e32 v5, v15, v193
	v_add_f32_e32 v193, v5, v4
	v_fmac_f32_e32 v193, v242, v0
	v_add_u32_e32 v0, s60, v183
	ds_read_b64_tr_b16 v[246:247], v0 offset:41984
	ds_read_b64_tr_b16 v[248:249], v0 offset:42496
	ds_read_b64_tr_b16 v[250:251], v0 offset:46080
	ds_read_b64_tr_b16 v[252:253], v0 offset:46592
	s_waitcnt lgkmcnt(2)
	v_mfma_f32_32x32x16_bf16 v[48:63], v[246:249], v[10:13], v[48:63]
	v_mov_b32_e32 v4, v1
	v_mov_b32_e32 v5, v1
	s_mov_b64 s[4:5], 0
	s_waitcnt lgkmcnt(0)
	v_mfma_f32_32x32x16_bf16 v[64:79], v[250:253], v[10:13], v[64:79]
	v_mfma_f32_32x32x16_bf16 v[16:31], v[246:249], v[2:5], v[16:31]
	v_mfma_f32_32x32x16_bf16 v[32:47], v[250:253], v[2:5], v[32:47]
	ds_read_b64_tr_b16 v[2:3], v0 offset:43008
	ds_read_b64_tr_b16 v[4:5], v0 offset:43520
	ds_read_b64_tr_b16 v[10:11], v0 offset:47104
	ds_read_b64_tr_b16 v[12:13], v0 offset:47616
	s_waitcnt lgkmcnt(2)
	v_mfma_f32_32x32x16_bf16 v[48:63], v[2:5], v[6:9], v[48:63]
	s_waitcnt lgkmcnt(0)
	v_mfma_f32_32x32x16_bf16 v[64:79], v[10:13], v[6:9], v[64:79]
.LBB0_796:
	s_and_b64 vcc, exec, s[4:5]
	s_cbranch_vccz .LBB0_802
	s_nop 0
	ds_read_b128 v[18:21], v226 offset:4640
	s_waitcnt lgkmcnt(0)
	v_mfma_f32_32x32x16_bf16 v[2:17], v[176:179], v[144:147], 0
	v_mfma_f32_32x32x16_bf16 v[2:17], v[18:21], v[148:151], v[2:17]
	ds_read_b128 v[18:21], v226 offset:4672
	s_waitcnt lgkmcnt(0)
	v_mfma_f32_32x32x16_bf16 v[2:17], v[18:21], v[152:155], v[2:17]
	ds_read_b128 v[18:21], v226 offset:4704
	s_waitcnt lgkmcnt(0)
	v_mfma_f32_32x32x16_bf16 v[2:17], v[18:21], v[156:159], v[2:17]
	ds_read_b128 v[18:21], v226 offset:4608
	ds_read_b128 v[22:25], v226 offset:4640
	ds_read_b128 v[26:29], v226 offset:4672
	ds_read_b128 v[30:33], v226 offset:4704
	s_waitcnt lgkmcnt(0)
	v_mfma_f32_32x32x16_bf16 v[48:63], v[18:21], v[160:163], 0
	s_nop 5
	v_max3_f32 v0, v2, s62, v3
	v_max3_f32 v0, v0, v4, v5
	v_max3_f32 v0, v0, v6, v7
	v_max3_f32 v0, v0, v8, v9
	v_max3_f32 v0, v0, v10, v11
	v_max3_f32 v0, v0, v12, v13
	v_max3_f32 v0, v0, v14, v15
	v_max3_f32 v0, v0, v16, v17
	v_mov_b32_e32 v18, v0
	s_nop 1
	v_permlane32_swap_b32_e32 v0, v18
	v_max_f32_e32 v0, v0, v18
	v_mul_f32_e32 v0, 0x3e38aa3b, v0
	v_mfma_f32_32x32x16_bf16 v[48:63], v[22:25], v[164:167], v[48:63]
	v_cmp_gt_f32_e32 vcc, v0, v244
	s_nop 1
	v_cndmask_b32_e32 v227, v230, v0, vcc
	v_sub_f32_e32 v0, v230, v227
	v_fma_f32 v2, v2, s91, -v227
	v_fma_f32 v3, v3, s91, -v227
	v_fma_f32 v4, v4, s91, -v227
	v_fma_f32 v5, v5, s91, -v227
	v_fma_f32 v6, v6, s91, -v227
	v_fma_f32 v7, v7, s91, -v227
	v_fma_f32 v8, v8, s91, -v227
	v_fma_f32 v9, v9, s91, -v227
	v_fma_f32 v10, v10, s91, -v227
	v_fma_f32 v11, v11, s91, -v227
	v_fma_f32 v12, v12, s91, -v227
	v_mfma_f32_32x32x16_bf16 v[48:63], v[26:29], v[168:171], v[48:63]
	v_fma_f32 v13, v13, s91, -v227
	v_fma_f32 v18, v14, s91, -v227
	v_fma_f32 v19, v15, s91, -v227
	v_fma_f32 v20, v16, s91, -v227
	v_fma_f32 v21, v17, s91, -v227
	v_exp_f32_e32 v0, v0
	v_exp_f32_e32 v76, v2
	v_mfma_f32_32x32x16_bf16 v[48:63], v[30:33], v[172:175], v[48:63]
	v_exp_f32_e32 v177, v3
	v_exp_f32_e32 v77, v4
	v_exp_f32_e32 v178, v5
	v_exp_f32_e32 v72, v6
	v_exp_f32_e32 v74, v7
	v_exp_f32_e32 v73, v8
	v_exp_f32_e32 v75, v9
	v_exp_f32_e32 v230, v10
	v_exp_f32_e32 v243, v11
	v_exp_f32_e32 v78, v12
	v_exp_f32_e32 v179, v13
	v_exp_f32_e32 v79, v18
	v_exp_f32_e32 v193, v19
	v_exp_f32_e32 v176, v20
	v_exp_f32_e32 v226, v21
	v_cvt_pk_bf16_f32 v14, v76, v177
	v_cvt_pk_bf16_f32 v15, v77, v178
	v_cvt_pk_bf16_f32 v16, v72, v74
	v_cvt_pk_bf16_f32 v17, v73, v75
	v_cvt_pk_bf16_f32 v68, v230, v243
	v_cvt_pk_bf16_f32 v69, v78, v179
	v_cvt_pk_bf16_f32 v70, v79, v193
	v_cvt_pk_bf16_f32 v71, v176, v226
	v_cmp_eq_f32_e32 vcc, 1.0, v0
	s_cmp_eq_u64 vcc, exec
	s_cbranch_scc1 .LBB0_799
	v_pk_mul_f32 v[94:95], v[94:95], v[0:1] op_sel_hi:[1,0]
	v_pk_mul_f32 v[92:93], v[92:93], v[0:1] op_sel_hi:[1,0]
	v_pk_mul_f32 v[90:91], v[90:91], v[0:1] op_sel_hi:[1,0]
	v_pk_mul_f32 v[88:89], v[88:89], v[0:1] op_sel_hi:[1,0]
	v_pk_mul_f32 v[86:87], v[86:87], v[0:1] op_sel_hi:[1,0]
	v_pk_mul_f32 v[84:85], v[84:85], v[0:1] op_sel_hi:[1,0]
	v_pk_mul_f32 v[82:83], v[82:83], v[0:1] op_sel_hi:[1,0]
	v_pk_mul_f32 v[80:81], v[80:81], v[0:1] op_sel_hi:[1,0]
	v_pk_mul_f32 v[110:111], v[110:111], v[0:1] op_sel_hi:[1,0]
	v_pk_mul_f32 v[108:109], v[108:109], v[0:1] op_sel_hi:[1,0]
	v_pk_mul_f32 v[106:107], v[106:107], v[0:1] op_sel_hi:[1,0]
	v_pk_mul_f32 v[104:105], v[104:105], v[0:1] op_sel_hi:[1,0]
	v_pk_mul_f32 v[102:103], v[102:103], v[0:1] op_sel_hi:[1,0]
	v_pk_mul_f32 v[100:101], v[100:101], v[0:1] op_sel_hi:[1,0]
	v_pk_mul_f32 v[98:99], v[98:99], v[0:1] op_sel_hi:[1,0]
	v_pk_mul_f32 v[96:97], v[96:97], v[0:1] op_sel_hi:[1,0]
.LBB0_799:
	v_add_u32_e32 v4, s60, v183
	ds_read_b64_tr_b16 v[10:11], v4 offset:41984
	ds_read_b64_tr_b16 v[12:13], v4 offset:42496
	ds_read_b64_tr_b16 v[6:7], v4 offset:43008
	ds_read_b64_tr_b16 v[8:9], v4 offset:43520
	ds_read_b64_tr_b16 v[64:65], v4 offset:46080
	ds_read_b64_tr_b16 v[66:67], v4 offset:46592
	ds_read_b64_tr_b16 v[2:3], v4 offset:47104
	ds_read_b64_tr_b16 v[4:5], v4 offset:47616
	s_waitcnt lgkmcnt(6)
	v_mfma_f32_32x32x16_bf16 v[80:95], v[10:13], v[14:17], v[80:95]
	s_waitcnt lgkmcnt(2)
	v_mfma_f32_32x32x16_bf16 v[96:111], v[64:67], v[14:17], v[96:111]
	v_max3_f32 v14, v48, s62, v49
	v_max3_f32 v14, v14, v50, v51
	s_nop 7
	v_mov_b64_e32 v[16:17], v[80:81]
	v_max3_f32 v14, v14, v52, v53
	v_mov_b64_e32 v[18:19], v[82:83]
	v_mov_b64_e32 v[20:21], v[84:85]
	v_mov_b64_e32 v[22:23], v[86:87]
	v_mov_b64_e32 v[24:25], v[88:89]
	v_mov_b64_e32 v[26:27], v[90:91]
	v_mov_b64_e32 v[28:29], v[92:93]
	v_mov_b64_e32 v[30:31], v[94:95]
	v_mov_b64_e32 v[32:33], v[96:97]
	v_max3_f32 v14, v14, v54, v55
	v_mov_b64_e32 v[34:35], v[98:99]
	v_mov_b64_e32 v[36:37], v[100:101]
	v_mov_b64_e32 v[38:39], v[102:103]
	v_mov_b64_e32 v[40:41], v[104:105]
	v_mov_b64_e32 v[42:43], v[106:107]
	v_mov_b64_e32 v[44:45], v[108:109]
	v_mov_b64_e32 v[46:47], v[110:111]
	v_mfma_f32_32x32x16_bf16 v[16:31], v[6:9], v[68:71], v[16:31]
	v_max3_f32 v14, v14, v56, v57
	v_max3_f32 v14, v14, v58, v59
	v_max3_f32 v14, v14, v60, v61
	v_max3_f32 v14, v14, v62, v63
	v_mov_b32_e32 v15, v14
	s_nop 1
	v_permlane32_swap_b32_e32 v14, v15
	v_max_f32_e32 v14, v14, v15
	v_mul_f32_e32 v14, 0x3e38aa3b, v14
	v_add_f32_e32 v15, 0x41000000, v240
	v_cmp_gt_f32_e32 vcc, v14, v15
	s_nop 1
	v_cndmask_b32_e32 v228, v240, v14, vcc
	v_fma_f32 v15, v48, s91, -v228
	v_fma_f32 v48, v49, s91, -v228
	v_fma_f32 v49, v50, s91, -v228
	v_fma_f32 v50, v52, s91, -v228
	v_fma_f32 v52, v56, s91, -v228
	v_sub_f32_e32 v14, v240, v228
	v_exp_f32_e32 v56, v52
	v_fma_f32 v52, v57, s91, -v228
	s_waitcnt lgkmcnt(0)
	v_mfma_f32_32x32x16_bf16 v[32:47], v[2:5], v[68:71], v[32:47]
	v_exp_f32_e32 v69, v49
	v_fma_f32 v49, v51, s91, -v228
	v_fma_f32 v51, v54, s91, -v228
	v_exp_f32_e32 v71, v50
	v_fma_f32 v50, v53, s91, -v228
	v_exp_f32_e32 v81, v51
	v_fma_f32 v51, v55, s91, -v228
	v_fma_f32 v53, v58, s91, -v228
	v_fma_f32 v54, v60, s91, -v228
	v_fma_f32 v55, v62, s91, -v228
	v_exp_f32_e32 v58, v53
	v_fma_f32 v53, v59, s91, -v228
	v_exp_f32_e32 v60, v54
	v_fma_f32 v54, v61, s91, -v228
	v_exp_f32_e32 v59, v55
	v_fma_f32 v55, v63, s91, -v228
	v_exp_f32_e32 v14, v14
	v_exp_f32_e32 v15, v15
	v_exp_f32_e32 v68, v48
	v_exp_f32_e32 v70, v49
	v_exp_f32_e32 v80, v50
	v_exp_f32_e32 v82, v51
	v_exp_f32_e32 v57, v52
	v_exp_f32_e32 v83, v53
	v_exp_f32_e32 v61, v54
	v_exp_f32_e32 v62, v55
	v_cvt_pk_bf16_f32 v48, v15, v68
	v_cvt_pk_bf16_f32 v49, v69, v70
	v_cvt_pk_bf16_f32 v50, v71, v80
	v_cvt_pk_bf16_f32 v51, v81, v82
	v_cvt_pk_bf16_f32 v52, v56, v57
	v_cvt_pk_bf16_f32 v53, v58, v83
	v_cvt_pk_bf16_f32 v54, v60, v61
	v_cvt_pk_bf16_f32 v55, v59, v62
	v_cmp_eq_f32_e32 vcc, 1.0, v14
	s_cmp_eq_u64 vcc, exec
	s_cbranch_scc1 .LBB0_801
	v_pk_mul_f32 v[126:127], v[126:127], v[14:15] op_sel_hi:[1,0]
	v_pk_mul_f32 v[124:125], v[124:125], v[14:15] op_sel_hi:[1,0]
	v_pk_mul_f32 v[122:123], v[122:123], v[14:15] op_sel_hi:[1,0]
	v_pk_mul_f32 v[120:121], v[120:121], v[14:15] op_sel_hi:[1,0]
	v_pk_mul_f32 v[118:119], v[118:119], v[14:15] op_sel_hi:[1,0]
	v_pk_mul_f32 v[116:117], v[116:117], v[14:15] op_sel_hi:[1,0]
	v_pk_mul_f32 v[114:115], v[114:115], v[14:15] op_sel_hi:[1,0]
	v_pk_mul_f32 v[112:113], v[112:113], v[14:15] op_sel_hi:[1,0]
	v_pk_mul_f32 v[142:143], v[142:143], v[14:15] op_sel_hi:[1,0]
	v_pk_mul_f32 v[140:141], v[140:141], v[14:15] op_sel_hi:[1,0]
	v_pk_mul_f32 v[138:139], v[138:139], v[14:15] op_sel_hi:[1,0]
	v_pk_mul_f32 v[136:137], v[136:137], v[14:15] op_sel_hi:[1,0]
	v_pk_mul_f32 v[134:135], v[134:135], v[14:15] op_sel_hi:[1,0]
	v_pk_mul_f32 v[132:133], v[132:133], v[14:15] op_sel_hi:[1,0]
	v_pk_mul_f32 v[130:131], v[130:131], v[14:15] op_sel_hi:[1,0]
	v_pk_mul_f32 v[128:129], v[128:129], v[14:15] op_sel_hi:[1,0]
.LBB0_801:
	v_add_f32_e32 v15, v15, v68
	v_mfma_f32_32x32x16_bf16 v[112:127], v[10:13], v[48:51], v[112:127]
	v_add_f32_e32 v63, v69, v70
	v_add_f32_e32 v15, v63, v15
	v_add_f32_e32 v63, v71, v80
	v_add_f32_e32 v15, v63, v15
	v_add_f32_e32 v63, v81, v82
	v_add_f32_e32 v15, v63, v15
	v_mfma_f32_32x32x16_bf16 v[128:143], v[64:67], v[48:51], v[128:143]
	v_add_f32_e32 v56, v56, v57
	v_add_f32_e32 v15, v56, v15
	v_add_f32_e32 v56, v58, v83
	v_add_f32_e32 v15, v56, v15
	v_add_f32_e32 v56, v60, v61
	v_add_f32_e32 v10, v56, v15
	v_add_f32_e32 v11, v59, v62
	v_add_f32_e32 v192, v11, v10
	v_add_f32_e32 v10, v76, v177
	v_mfma_f32_32x32x16_bf16 v[112:127], v[6:9], v[52:55], v[112:127]
	v_add_f32_e32 v11, v77, v178
	v_add_f32_e32 v10, v11, v10
	v_add_f32_e32 v11, v72, v74
	v_add_f32_e32 v10, v11, v10
	v_add_f32_e32 v11, v73, v75
	v_add_f32_e32 v10, v11, v10
	v_mfma_f32_32x32x16_bf16 v[128:143], v[2:5], v[52:55], v[128:143]
	v_add_f32_e32 v11, v230, v243
	v_add_f32_e32 v10, v11, v10
	v_add_f32_e32 v6, v78, v179
	v_add_f32_e32 v6, v6, v10
	v_add_f32_e32 v7, v79, v193
	v_add_f32_e32 v6, v7, v6
	v_add_f32_e32 v7, v176, v226
	v_add_f32_e32 v193, v7, v6
	v_mov_b64_e32 v[48:49], v[112:113]
	s_nop 2
	v_mov_b64_e32 v[64:65], v[128:129]
	v_fmac_f32_e32 v192, v241, v14
	v_fmac_f32_e32 v193, v242, v0
	v_mov_b64_e32 v[50:51], v[114:115]
	v_mov_b64_e32 v[52:53], v[116:117]
	v_mov_b64_e32 v[54:55], v[118:119]
	v_mov_b64_e32 v[56:57], v[120:121]
	v_mov_b64_e32 v[58:59], v[122:123]
	v_mov_b64_e32 v[60:61], v[124:125]
	v_mov_b64_e32 v[62:63], v[126:127]
	v_mov_b64_e32 v[66:67], v[130:131]
	v_mov_b64_e32 v[68:69], v[132:133]
	v_mov_b64_e32 v[70:71], v[134:135]
	v_mov_b64_e32 v[72:73], v[136:137]
	v_mov_b64_e32 v[74:75], v[138:139]
	v_mov_b64_e32 v[76:77], v[140:141]
	v_mov_b64_e32 v[78:79], v[142:143]

.LBB0_870:
	v_add_f32_e32 v41, v75, v118
	v_add_f32_e32 v42, v107, v119
	v_add_f32_e32 v41, v42, v41
	v_add_f32_e32 v42, v108, v120
	v_add_f32_e32 v41, v42, v41
	v_add_f32_e32 v42, v109, v121
	v_add_f32_e32 v41, v42, v41
	v_add_f32_e32 v42, v110, v122
	v_add_f32_e32 v41, v42, v41
	v_add_f32_e32 v42, v111, v123
	v_add_f32_e32 v41, v42, v41
	v_add_f32_e32 v42, v112, v124
	v_add_f32_e32 v41, v42, v41
	v_add_f32_e32 v42, v113, v125
	v_add_f32_e32 v41, v42, v41
	v_fmac_f32_e32 v41, v116, v0
	v_add_f32_e32 v0, v126, v127
	v_add_f32_e32 v42, v128, v129
	v_add_f32_e32 v0, v42, v0
	v_add_f32_e32 v42, v130, v131
	v_add_f32_e32 v0, v42, v0
	v_add_f32_e32 v42, v132, v133
	v_add_f32_e32 v0, v42, v0
	v_add_f32_e32 v42, v134, v135
	v_add_f32_e32 v0, v42, v0
	v_add_f32_e32 v42, v136, v137
	v_add_f32_e32 v0, v42, v0
	v_add_f32_e32 v42, v138, v139
	v_add_f32_e32 v0, v42, v0
	v_add_f32_e32 v42, v140, v141
	v_add_f32_e32 v0, v42, v0
	v_fmac_f32_e32 v0, v41, v74
	v_mul_f32_e32 v42, v0, v106
	v_add_f32_e32 v0, v142, v143
	v_add_f32_e32 v43, v38, v39
	v_pk_add_f32 v[38:39], v[76:77], v[80:81]
	v_pk_add_f32 v[44:45], v[82:83], v[84:85]
	v_pk_add_f32 v[38:39], v[38:39], v[0:1]
	v_pk_add_f32 v[46:47], v[86:87], v[88:89]
	v_pk_add_f32 v[38:39], v[44:45], v[38:39]
	v_pk_add_f32 v[48:49], v[90:91], v[92:93]
	v_pk_add_f32 v[38:39], v[46:47], v[38:39]
	v_pk_add_f32 v[54:55], v[94:95], v[96:97]
	v_pk_add_f32 v[38:39], v[48:49], v[38:39]
	v_pk_add_f32 v[56:57], v[98:99], v[100:101]
	v_pk_add_f32 v[38:39], v[54:55], v[38:39]
	v_pk_add_f32 v[58:59], v[102:103], v[104:105]
	v_pk_add_f32 v[38:39], v[56:57], v[38:39]
	s_mov_b32 s81, s87
	v_pk_add_f32 v[38:39], v[58:59], v[38:39]
	s_nop 0
	v_pk_add_f32 v[38:39], v[42:43], v[38:39]
	ds_read_b64_tr_b16 v[42:43], v114 offset:41984
	ds_read_b64_tr_b16 v[44:45], v114 offset:42496
	ds_read_b64_tr_b16 v[46:47], v114 offset:46080
	ds_read_b64_tr_b16 v[48:49], v114 offset:46592
	s_waitcnt lgkmcnt(2)
	v_mfma_f32_32x32x16_bf16 v[2:17], v[42:45], v[50:53], v[2:17]
	v_fmac_f32_e32 v39, v38, v40
	v_mov_b32_e32 v0, v39
	s_nop 1
	v_permlane32_swap_b32_e32 v39, v0
	v_add_f32_e32 v0, v39, v0
	v_lshlrev_b32_e32 v40, 2, v115
	v_ashrrev_i32_e32 v41, 31, v40
	s_waitcnt lgkmcnt(0)
	v_mfma_f32_32x32x16_bf16 v[18:33], v[46:49], v[50:53], v[18:33]
	ds_read_b64_tr_b16 v[42:43], v114 offset:43008
	ds_read_b64_tr_b16 v[44:45], v114 offset:43520
	ds_read_b64_tr_b16 v[46:47], v114 offset:47104
	ds_read_b64_tr_b16 v[48:49], v114 offset:47616
	s_waitcnt lgkmcnt(2)
	v_mfma_f32_32x32x16_bf16 v[2:17], v[42:45], v[34:37], v[2:17]
	s_waitcnt lgkmcnt(0)
	v_mfma_f32_32x32x16_bf16 v[18:33], v[46:49], v[34:37], v[18:33]
	v_div_scale_f32 v36, s[38:39], v0, v0, 1.0
	v_rcp_f32_e32 v37, v36
	v_lshlrev_b64 v[34:35], 10, v[78:79]
	v_lshl_add_u64 v[34:35], s[96:97], 0, v[34:35]
	v_lshl_add_u64 v[34:35], v[34:35], 0, s[80:81]
	v_fma_f32 v38, -v36, v37, 1.0
	v_fmac_f32_e32 v37, v38, v37
	v_div_scale_f32 v38, vcc, 1.0, v0, 1.0
	v_mul_f32_e32 v39, v38, v37
	v_lshl_add_u64 v[34:35], v[40:41], 1, v[34:35]
	v_fma_f32 v40, -v36, v39, v38
	v_fmac_f32_e32 v39, v40, v37
	v_fma_f32 v36, -v36, v39, v38
	v_div_fmas_f32 v36, v36, v37, v39
	v_div_fixup_f32 v0, v36, v0, 1.0
	v_mul_f32_e32 v2, v2, v0
	v_mul_f32_e32 v3, v3, v0
	v_cvt_pk_bf16_f32 v2, v2, v3
	v_mul_f32_e32 v3, v4, v0
	v_mul_f32_e32 v4, v5, v0
	v_cvt_pk_bf16_f32 v3, v3, v4
	v_mul_f32_e32 v4, v18, v0
	v_mul_f32_e32 v5, v19, v0
	v_cvt_pk_bf16_f32 v4, v4, v5
	v_mul_f32_e32 v5, v20, v0
	v_mul_f32_e32 v18, v21, v0
	v_cvt_pk_bf16_f32 v5, v5, v18
	global_store_dwordx2 v[34:35], v[2:3], off
	global_store_dwordx2 v[34:35], v[4:5], off offset:64
	v_mul_f32_e32 v2, v6, v0
	v_mul_f32_e32 v3, v7, v0
	v_cvt_pk_bf16_f32 v2, v2, v3
	v_mul_f32_e32 v3, v8, v0
	v_mul_f32_e32 v4, v9, v0
	v_cvt_pk_bf16_f32 v3, v3, v4
	v_mul_f32_e32 v4, v22, v0
	v_mul_f32_e32 v5, v23, v0
	v_cvt_pk_bf16_f32 v4, v4, v5
	v_mul_f32_e32 v5, v24, v0
	v_mul_f32_e32 v6, v25, v0
	v_cvt_pk_bf16_f32 v5, v5, v6
	global_store_dwordx2 v[34:35], v[2:3], off offset:16
	global_store_dwordx2 v[34:35], v[4:5], off offset:80
	v_mul_f32_e32 v2, v10, v0
	v_mul_f32_e32 v3, v11, v0
	v_cvt_pk_bf16_f32 v2, v2, v3
	v_mul_f32_e32 v3, v12, v0
	v_mul_f32_e32 v4, v13, v0
	v_cvt_pk_bf16_f32 v3, v3, v4
	v_mul_f32_e32 v4, v26, v0
	v_mul_f32_e32 v5, v27, v0
	v_cvt_pk_bf16_f32 v4, v4, v5
	v_mul_f32_e32 v5, v28, v0
	v_mul_f32_e32 v6, v29, v0
	v_cvt_pk_bf16_f32 v5, v5, v6
	global_store_dwordx2 v[34:35], v[2:3], off offset:32
	global_store_dwordx2 v[34:35], v[4:5], off offset:96
	v_mul_f32_e32 v2, v14, v0
	v_mul_f32_e32 v3, v15, v0
	v_cvt_pk_bf16_f32 v2, v2, v3
	v_mul_f32_e32 v3, v16, v0
	v_mul_f32_e32 v4, v17, v0
	v_cvt_pk_bf16_f32 v3, v3, v4
	v_mul_f32_e32 v4, v30, v0
	v_mul_f32_e32 v5, v31, v0
	v_cvt_pk_bf16_f32 v4, v4, v5
	v_mul_f32_e32 v5, v32, v0
	v_mul_f32_e32 v0, v33, v0
	v_cvt_pk_bf16_f32 v5, v5, v0
	global_store_dwordx2 v[34:35], v[2:3], off offset:48
	global_store_dwordx2 v[34:35], v[4:5], off offset:112
	s_barrier
	s_movk_i32 s80, 0x580
	s_movk_i32 s81, 0x380

.LBB0_888:
	s_or_b32 s56, s72, s69
	s_mulk_i32 s56, 0x3000
	s_add_u32 s72, s4, s56
	s_addc_u32 s73, s5, 0
	s_lshl_b32 s56, s71, 13
	s_add_i32 s56, s56, 0x9c00
	s_mul_i32 s78, s71, 0x3400
	s_and_b64 s[74:75], s[14:15], exec
	s_cselect_b32 s74, s78, s56
	s_add_i32 m0, s61, s74
	s_and_b64 s[74:75], s[12:13], exec
	s_waitcnt vmcnt(3)
	s_barrier
	v_lshl_add_u64 v[34:35], v[74:75], 1, s[72:73]
	s_cselect_b32 s74, s78, s56
	global_load_lds_dwordx4 v[34:35], off
	v_lshl_add_u64 v[34:35], v[72:73], 1, s[72:73]
	s_add_i32 m0, s59, s74
	s_nop 0
	global_load_lds_dwordx4 v[34:35], off
	v_lshl_add_u64 v[34:35], v[76:77], 1, s[72:73]
	s_and_b64 s[72:73], s[20:21], exec
	s_cselect_b32 s56, s78, s56
	s_add_i32 m0, s60, s56
	s_mul_i32 s56, s70, 0x3400
	global_load_lds_dwordx4 v[34:35], off
	v_add_u32_e32 v128, s56, v109
	ds_read_b128 v[34:37], v128
	ds_read_b128 v[112:115], v128 offset:32
	s_waitcnt lgkmcnt(0)
	v_mfma_f32_32x32x16_bf16 v[34:49], v[34:37], v[62:65], 0
	v_mfma_f32_32x32x16_bf16 v[34:49], v[112:115], v[58:61], v[34:49]
	ds_read_b128 v[112:115], v128 offset:64
	s_waitcnt lgkmcnt(0)
	v_mfma_f32_32x32x16_bf16 v[34:49], v[112:115], v[54:57], v[34:49]
	ds_read_b128 v[112:115], v128 offset:96
	s_waitcnt lgkmcnt(0)
	v_mfma_f32_32x32x16_bf16 v[34:49], v[112:115], v[50:53], v[34:49]
	s_nop 11
	v_max3_f32 v0, v34, s62, v35
	v_max3_f32 v0, v0, v36, v37
	v_max3_f32 v0, v0, v38, v39
	v_max3_f32 v0, v0, v40, v41
	v_max3_f32 v0, v0, v42, v43
	v_max3_f32 v0, v0, v44, v45
	v_max3_f32 v0, v0, v46, v47
	v_max3_f32 v0, v0, v48, v49
	v_mov_b32_e32 v111, v0
	s_nop 1
	v_permlane32_swap_b32_e32 v0, v111
	v_max_f32_e32 v0, v0, v111
	v_mul_f32_e32 v0, 0x3e38aa3b, v0
	v_add_f32_e32 v111, 0x41000000, v110
	v_cmp_gt_f32_e32 vcc, v0, v111
	s_nop 1
	v_cndmask_b32_e32 v127, v110, v0, vcc
	v_fma_f32 v34, v34, s91, -v127
	v_exp_f32_e32 v111, v34
	v_fma_f32 v34, v35, s91, -v127
	v_fma_f32 v35, v36, s91, -v127
	v_sub_f32_e32 v0, v110, v127
	v_exp_f32_e32 v113, v35
	v_fma_f32 v35, v37, s91, -v127
	v_fma_f32 v36, v38, s91, -v127
	v_fma_f32 v37, v40, s91, -v127
	v_exp_f32_e32 v115, v36
	v_fma_f32 v36, v39, s91, -v127
	v_exp_f32_e32 v117, v37
	v_fma_f32 v37, v41, s91, -v127
	v_fma_f32 v38, v42, s91, -v127
	v_fma_f32 v39, v44, s91, -v127
	v_fma_f32 v40, v46, s91, -v127
	v_fma_f32 v41, v48, s91, -v127
	v_exp_f32_e32 v0, v0
	v_exp_f32_e32 v119, v38
	v_fma_f32 v38, v43, s91, -v127
	v_exp_f32_e32 v121, v39
	v_fma_f32 v39, v45, s91, -v127
	v_exp_f32_e32 v123, v40
	v_fma_f32 v40, v47, s91, -v127
	v_exp_f32_e32 v125, v41
	v_fma_f32 v41, v49, s91, -v127
	v_exp_f32_e32 v112, v34
	v_exp_f32_e32 v114, v35
	v_exp_f32_e32 v116, v36
	v_exp_f32_e32 v118, v37
	v_exp_f32_e32 v120, v38
	v_exp_f32_e32 v122, v39
	v_exp_f32_e32 v124, v40
	v_exp_f32_e32 v126, v41
	v_cmp_eq_f32_e32 vcc, 1.0, v0
	s_cmp_eq_u64 vcc, exec
	v_cvt_pk_bf16_f32 v34, v111, v112
	v_cvt_pk_bf16_f32 v35, v113, v114
	v_cvt_pk_bf16_f32 v36, v115, v116
	v_cvt_pk_bf16_f32 v37, v117, v118
	v_cvt_pk_bf16_f32 v38, v119, v120
	v_cvt_pk_bf16_f32 v39, v121, v122
	v_cvt_pk_bf16_f32 v40, v123, v124
	v_cvt_pk_bf16_f32 v41, v125, v126
	s_cbranch_scc1 .LBB0_890
	v_pk_mul_f32 v[32:33], v[104:105], v[0:1] op_sel_hi:[1,0]
	v_pk_mul_f32 v[30:31], v[102:103], v[0:1] op_sel_hi:[1,0]
	v_pk_mul_f32 v[28:29], v[100:101], v[0:1] op_sel_hi:[1,0]
	v_pk_mul_f32 v[26:27], v[98:99], v[0:1] op_sel_hi:[1,0]
	v_pk_mul_f32 v[24:25], v[96:97], v[0:1] op_sel_hi:[1,0]
	v_pk_mul_f32 v[22:23], v[94:95], v[0:1] op_sel_hi:[1,0]
	v_pk_mul_f32 v[20:21], v[92:93], v[0:1] op_sel_hi:[1,0]
	v_pk_mul_f32 v[18:19], v[90:91], v[0:1] op_sel_hi:[1,0]
	v_pk_mul_f32 v[16:17], v[88:89], v[0:1] op_sel_hi:[1,0]
	v_pk_mul_f32 v[14:15], v[86:87], v[0:1] op_sel_hi:[1,0]
	v_pk_mul_f32 v[12:13], v[84:85], v[0:1] op_sel_hi:[1,0]
	v_pk_mul_f32 v[10:11], v[82:83], v[0:1] op_sel_hi:[1,0]
	v_pk_mul_f32 v[8:9], v[80:81], v[0:1] op_sel_hi:[1,0]
	v_pk_mul_f32 v[6:7], v[78:79], v[0:1] op_sel_hi:[1,0]
	v_pk_mul_f32 v[4:5], v[68:69], v[0:1] op_sel_hi:[1,0]
	v_pk_mul_f32 v[2:3], v[66:67], v[0:1] op_sel_hi:[1,0]
.LBB0_890:
	s_lshl_b32 s56, s70, 13
	v_add_u32_e32 v78, s56, v106
	ds_read_b64_tr_b16 v[42:43], v78 offset:39936
	ds_read_b64_tr_b16 v[44:45], v78 offset:40448
	ds_read_b64_tr_b16 v[46:47], v78 offset:44032
	ds_read_b64_tr_b16 v[48:49], v78 offset:44544
	s_waitcnt lgkmcnt(2)
	v_mfma_f32_32x32x16_bf16 v[2:17], v[42:45], v[34:37], v[2:17]
	s_waitcnt lgkmcnt(0)
	v_mfma_f32_32x32x16_bf16 v[18:33], v[46:49], v[34:37], v[18:33]
	ds_read_b64_tr_b16 v[34:35], v78 offset:40960
	ds_read_b64_tr_b16 v[36:37], v78 offset:41472
	ds_read_b64_tr_b16 v[42:43], v78 offset:45056
	ds_read_b64_tr_b16 v[44:45], v78 offset:45568
	s_waitcnt lgkmcnt(2)
	v_mfma_f32_32x32x16_bf16 v[2:17], v[34:37], v[38:41], v[2:17]
	ds_read_b128 v[34:37], v128 offset:4608
	ds_read_b128 v[66:69], v128 offset:4640
	s_waitcnt lgkmcnt(2)
	v_mfma_f32_32x32x16_bf16 v[18:33], v[42:45], v[38:41], v[18:33]
	s_waitcnt lgkmcnt(1)
	v_mfma_f32_32x32x16_bf16 v[34:49], v[34:37], v[62:65], 0
	s_waitcnt lgkmcnt(0)
	v_mfma_f32_32x32x16_bf16 v[34:49], v[66:69], v[58:61], v[34:49]
	ds_read_b128 v[66:69], v128 offset:4672
	s_waitcnt lgkmcnt(0)
	v_mfma_f32_32x32x16_bf16 v[34:49], v[66:69], v[54:57], v[34:49]
	ds_read_b128 v[66:69], v128 offset:4704
	s_waitcnt lgkmcnt(0)
	v_mfma_f32_32x32x16_bf16 v[34:49], v[66:69], v[50:53], v[34:49]
	s_nop 11
	v_max3_f32 v66, v34, s62, v35
	v_max3_f32 v66, v66, v36, v37
	v_max3_f32 v66, v66, v38, v39
	v_max3_f32 v66, v66, v40, v41
	v_max3_f32 v66, v66, v42, v43
	v_max3_f32 v66, v66, v44, v45
	v_max3_f32 v66, v66, v46, v47
	v_max3_f32 v66, v66, v48, v49
	v_mov_b32_e32 v67, v66
	s_nop 1
	v_permlane32_swap_b32_e32 v66, v67
	v_max_f32_e32 v66, v66, v67
	v_mul_f32_e32 v66, 0x3e38aa3b, v66
	v_add_f32_e32 v67, 0x41000000, v127
	v_cmp_gt_f32_e32 vcc, v66, v67
	s_nop 1
	v_cndmask_b32_e32 v110, v127, v66, vcc
	v_fma_f32 v34, v34, s91, -v110
	v_exp_f32_e32 v79, v34
	v_fma_f32 v34, v35, s91, -v110
	v_exp_f32_e32 v80, v34
	v_fma_f32 v34, v36, s91, -v110
	v_exp_f32_e32 v81, v34
	v_fma_f32 v34, v37, s91, -v110
	v_exp_f32_e32 v82, v34
	v_fma_f32 v34, v38, s91, -v110
	v_exp_f32_e32 v83, v34
	v_fma_f32 v34, v39, s91, -v110
	v_exp_f32_e32 v39, v34
	v_fma_f32 v34, v40, s91, -v110
	v_sub_f32_e32 v84, v127, v110
	v_exp_f32_e32 v40, v34
	v_fma_f32 v34, v41, s91, -v110
	v_exp_f32_e32 v41, v34
	v_fma_f32 v34, v42, s91, -v110
	v_fma_f32 v35, v44, s91, -v110
	v_fma_f32 v36, v46, s91, -v110
	v_fma_f32 v37, v48, s91, -v110
	v_exp_f32_e32 v38, v84
	v_exp_f32_e32 v42, v34
	v_fma_f32 v34, v43, s91, -v110
	v_exp_f32_e32 v44, v35
	v_fma_f32 v35, v45, s91, -v110
	v_exp_f32_e32 v46, v36
	v_fma_f32 v36, v47, s91, -v110
	v_exp_f32_e32 v48, v37
	v_fma_f32 v37, v49, s91, -v110
	v_exp_f32_e32 v43, v34
	v_exp_f32_e32 v45, v35
	v_exp_f32_e32 v47, v36
	v_exp_f32_e32 v49, v37
	v_cmp_eq_f32_e32 vcc, 1.0, v38
	s_cmp_eq_u64 vcc, exec
	v_cvt_pk_bf16_f32 v66, v79, v80
	v_cvt_pk_bf16_f32 v67, v81, v82
	v_cvt_pk_bf16_f32 v68, v83, v39
	v_cvt_pk_bf16_f32 v69, v40, v41
	v_cvt_pk_bf16_f32 v34, v42, v43
	v_cvt_pk_bf16_f32 v35, v44, v45
	v_cvt_pk_bf16_f32 v36, v46, v47
	v_cvt_pk_bf16_f32 v37, v48, v49
	s_cbranch_scc1 .LBB0_892
	v_pk_mul_f32 v[16:17], v[16:17], v[38:39] op_sel_hi:[1,0]
	v_pk_mul_f32 v[14:15], v[14:15], v[38:39] op_sel_hi:[1,0]
	v_pk_mul_f32 v[12:13], v[12:13], v[38:39] op_sel_hi:[1,0]
	v_pk_mul_f32 v[10:11], v[10:11], v[38:39] op_sel_hi:[1,0]
	v_pk_mul_f32 v[8:9], v[8:9], v[38:39] op_sel_hi:[1,0]
	v_pk_mul_f32 v[6:7], v[6:7], v[38:39] op_sel_hi:[1,0]
	v_pk_mul_f32 v[4:5], v[4:5], v[38:39] op_sel_hi:[1,0]
	v_pk_mul_f32 v[2:3], v[2:3], v[38:39] op_sel_hi:[1,0]
	v_pk_mul_f32 v[32:33], v[32:33], v[38:39] op_sel_hi:[1,0]
	v_pk_mul_f32 v[30:31], v[30:31], v[38:39] op_sel_hi:[1,0]
	v_pk_mul_f32 v[28:29], v[28:29], v[38:39] op_sel_hi:[1,0]
	v_pk_mul_f32 v[26:27], v[26:27], v[38:39] op_sel_hi:[1,0]
	v_pk_mul_f32 v[24:25], v[24:25], v[38:39] op_sel_hi:[1,0]
	v_pk_mul_f32 v[22:23], v[22:23], v[38:39] op_sel_hi:[1,0]
	v_pk_mul_f32 v[20:21], v[20:21], v[38:39] op_sel_hi:[1,0]
	v_pk_mul_f32 v[18:19], v[18:19], v[38:39] op_sel_hi:[1,0]
.LBB0_892:
	v_add_f32_e32 v84, v111, v112
	v_add_f32_e32 v85, v113, v114
	v_add_f32_e32 v84, v85, v84
	v_add_f32_e32 v85, v115, v116
	v_add_f32_e32 v84, v85, v84
	v_add_f32_e32 v85, v117, v118
	v_add_f32_e32 v84, v85, v84
	v_add_f32_e32 v85, v119, v120
	v_add_f32_e32 v84, v85, v84
	v_add_f32_e32 v85, v121, v122
	v_add_f32_e32 v84, v85, v84
	v_add_f32_e32 v85, v123, v124
	v_add_f32_e32 v84, v85, v84
	v_add_f32_e32 v85, v125, v126
	v_add_f32_e32 v84, v85, v84
	v_fmac_f32_e32 v84, v108, v0
	v_add_f32_e32 v0, v79, v80
	v_add_f32_e32 v79, v81, v82
	v_add_f32_e32 v0, v79, v0
	v_add_f32_e32 v39, v83, v39
	v_add_f32_e32 v0, v39, v0
	v_add_f32_e32 v39, v40, v41
	v_add_f32_e32 v0, v39, v0
	v_add_f32_e32 v39, v42, v43
	v_add_f32_e32 v0, v39, v0
	v_add_f32_e32 v39, v44, v45
	v_add_f32_e32 v0, v39, v0
	v_add_f32_e32 v39, v46, v47
	v_add_f32_e32 v0, v39, v0
	v_add_f32_e32 v39, v48, v49
	v_add_f32_e32 v108, v39, v0
	v_fmac_f32_e32 v108, v84, v38
	ds_read_b64_tr_b16 v[38:39], v78 offset:41984
	ds_read_b64_tr_b16 v[40:41], v78 offset:42496
	ds_read_b64_tr_b16 v[42:43], v78 offset:46080
	ds_read_b64_tr_b16 v[44:45], v78 offset:46592
	s_waitcnt lgkmcnt(2)
	v_mfma_f32_32x32x16_bf16 v[2:17], v[38:41], v[66:69], v[2:17]
	s_add_i32 s56, s70, 1
	s_cmp_lg_u32 s70, 2
	s_cselect_b32 s70, s56, 0
	s_add_i32 s56, s71, 1
	s_cmp_lg_u32 s71, 2
	s_cselect_b32 s71, s56, 0
	s_mov_b32 s72, 64
	s_waitcnt lgkmcnt(0)
	v_mfma_f32_32x32x16_bf16 v[18:33], v[42:45], v[66:69], v[18:33]
	ds_read_b64_tr_b16 v[38:39], v78 offset:43008
	ds_read_b64_tr_b16 v[40:41], v78 offset:43520
	ds_read_b64_tr_b16 v[42:43], v78 offset:47104
	ds_read_b64_tr_b16 v[44:45], v78 offset:47616
	s_and_b64 vcc, exec, s[38:39]
	s_waitcnt lgkmcnt(2)
	v_mfma_f32_32x32x16_bf16 v[2:17], v[38:41], v[34:37], v[2:17]
	s_waitcnt lgkmcnt(0)
	v_mfma_f32_32x32x16_bf16 v[18:33], v[42:45], v[34:37], v[18:33]
	s_cbranch_vccnz .LBB0_894
	s_mov_b64 s[38:39], -1
	s_nop 7
	v_mov_b32_e32 v66, v2
	v_mov_b32_e32 v67, v3
	v_mov_b32_e32 v68, v4
	v_mov_b32_e32 v69, v5
	v_mov_b32_e32 v78, v6
	v_mov_b32_e32 v79, v7
	v_mov_b32_e32 v80, v8
	v_mov_b32_e32 v81, v9
	v_mov_b32_e32 v82, v10
	v_mov_b32_e32 v83, v11
	v_mov_b32_e32 v84, v12
	v_mov_b32_e32 v85, v13
	v_mov_b32_e32 v86, v14
	v_mov_b32_e32 v87, v15
	v_mov_b32_e32 v88, v16
	v_mov_b32_e32 v89, v17
	v_mov_b32_e32 v90, v18
	v_mov_b32_e32 v91, v19
	v_mov_b32_e32 v92, v20
	v_mov_b32_e32 v93, v21
	v_mov_b32_e32 v94, v22
	v_mov_b32_e32 v95, v23
	v_mov_b32_e32 v96, v24
	v_mov_b32_e32 v97, v25
	v_mov_b32_e32 v98, v26
	v_mov_b32_e32 v99, v27
	v_mov_b32_e32 v100, v28
	v_mov_b32_e32 v101, v29
	v_mov_b32_e32 v102, v30
	v_mov_b32_e32 v103, v31
	v_mov_b32_e32 v104, v32
	v_mov_b32_e32 v105, v33
	s_branch .LBB0_888
.LBB0_894:
	s_waitcnt vmcnt(3)
	s_barrier
	ds_read_b128 v[34:37], v109 offset:26624
	ds_read_b128 v[66:69], v109 offset:26656
	s_waitcnt lgkmcnt(1)
	v_mfma_f32_32x32x16_bf16 v[34:49], v[34:37], v[62:65], 0
	s_waitcnt lgkmcnt(0)
	v_mfma_f32_32x32x16_bf16 v[34:49], v[66:69], v[58:61], v[34:49]
	ds_read_b128 v[66:69], v109 offset:26688
	s_waitcnt lgkmcnt(0)
	v_mfma_f32_32x32x16_bf16 v[34:49], v[66:69], v[54:57], v[34:49]
	ds_read_b128 v[66:69], v109 offset:26720
	s_waitcnt lgkmcnt(0)
	v_mfma_f32_32x32x16_bf16 v[34:49], v[66:69], v[50:53], v[34:49]
	s_nop 11
	v_max3_f32 v0, v34, s62, v35
	v_max3_f32 v0, v0, v36, v37
	v_max3_f32 v0, v0, v38, v39
	v_max3_f32 v0, v0, v40, v41
	v_max3_f32 v0, v0, v42, v43
	v_max3_f32 v0, v0, v44, v45
	v_max3_f32 v0, v0, v46, v47
	v_max3_f32 v0, v0, v48, v49
	v_mov_b32_e32 v66, v0
	s_nop 1
	v_permlane32_swap_b32_e32 v0, v66
	v_max_f32_e32 v0, v0, v66
	v_mul_f32_e32 v0, 0x3e38aa3b, v0
	v_add_f32_e32 v66, 0x41000000, v110
	v_cmp_gt_f32_e32 vcc, v0, v66
	s_nop 1
	v_cndmask_b32_e32 v66, v110, v0, vcc
	v_fma_f32 v34, v34, s91, -v66
	v_exp_f32_e32 v67, v34
	v_fma_f32 v34, v35, s91, -v66
	v_fma_f32 v35, v36, s91, -v66
	v_sub_f32_e32 v0, v110, v66
	v_exp_f32_e32 v100, v35
	v_fma_f32 v35, v37, s91, -v66
	v_fma_f32 v36, v38, s91, -v66
	v_fma_f32 v37, v40, s91, -v66
	v_exp_f32_e32 v102, v36
	v_fma_f32 v36, v39, s91, -v66
	v_exp_f32_e32 v104, v37
	v_fma_f32 v37, v41, s91, -v66
	v_fma_f32 v38, v42, s91, -v66
	v_fma_f32 v39, v44, s91, -v66
	v_fma_f32 v40, v46, s91, -v66
	v_fma_f32 v41, v48, s91, -v66
	v_exp_f32_e32 v0, v0
	v_exp_f32_e32 v110, v38
	v_fma_f32 v38, v43, s91, -v66
	v_exp_f32_e32 v112, v39
	v_fma_f32 v39, v45, s91, -v66
	v_exp_f32_e32 v114, v40
	v_fma_f32 v40, v47, s91, -v66
	v_exp_f32_e32 v116, v41
	v_fma_f32 v41, v49, s91, -v66
	v_exp_f32_e32 v99, v34
	v_exp_f32_e32 v101, v35
	v_exp_f32_e32 v103, v36
	v_exp_f32_e32 v105, v37
	v_exp_f32_e32 v111, v38
	v_exp_f32_e32 v113, v39
	v_exp_f32_e32 v115, v40
	v_exp_f32_e32 v117, v41
	v_cmp_eq_f32_e32 vcc, 1.0, v0
	s_cmp_eq_u64 vcc, exec
	v_cvt_pk_bf16_f32 v34, v67, v99
	v_cvt_pk_bf16_f32 v35, v100, v101
	v_cvt_pk_bf16_f32 v36, v102, v103
	v_cvt_pk_bf16_f32 v37, v104, v105
	v_cvt_pk_bf16_f32 v38, v110, v111
	v_cvt_pk_bf16_f32 v39, v112, v113
	v_cvt_pk_bf16_f32 v40, v114, v115
	v_cvt_pk_bf16_f32 v41, v116, v117
	s_cbranch_scc1 .LBB0_896
	v_pk_mul_f32 v[16:17], v[16:17], v[0:1] op_sel_hi:[1,0]
	v_pk_mul_f32 v[14:15], v[14:15], v[0:1] op_sel_hi:[1,0]
	v_pk_mul_f32 v[12:13], v[12:13], v[0:1] op_sel_hi:[1,0]
	v_pk_mul_f32 v[10:11], v[10:11], v[0:1] op_sel_hi:[1,0]
	v_pk_mul_f32 v[8:9], v[8:9], v[0:1] op_sel_hi:[1,0]
	v_pk_mul_f32 v[6:7], v[6:7], v[0:1] op_sel_hi:[1,0]
	v_pk_mul_f32 v[4:5], v[4:5], v[0:1] op_sel_hi:[1,0]
	v_pk_mul_f32 v[2:3], v[2:3], v[0:1] op_sel_hi:[1,0]
	v_pk_mul_f32 v[32:33], v[32:33], v[0:1] op_sel_hi:[1,0]
	v_pk_mul_f32 v[30:31], v[30:31], v[0:1] op_sel_hi:[1,0]
	v_pk_mul_f32 v[28:29], v[28:29], v[0:1] op_sel_hi:[1,0]
	v_pk_mul_f32 v[26:27], v[26:27], v[0:1] op_sel_hi:[1,0]
	v_pk_mul_f32 v[24:25], v[24:25], v[0:1] op_sel_hi:[1,0]
	v_pk_mul_f32 v[22:23], v[22:23], v[0:1] op_sel_hi:[1,0]
	v_pk_mul_f32 v[20:21], v[20:21], v[0:1] op_sel_hi:[1,0]
	v_pk_mul_f32 v[18:19], v[18:19], v[0:1] op_sel_hi:[1,0]
.LBB0_896:
	ds_read_b64_tr_b16 v[42:43], v106 offset:56320
	ds_read_b64_tr_b16 v[44:45], v106 offset:56832
	ds_read_b64_tr_b16 v[46:47], v106 offset:60416
	ds_read_b64_tr_b16 v[48:49], v106 offset:60928
	s_mov_b32 s92, 0x1ffffffc
	s_mov_b32 s93, 0x38e38e39
	s_waitcnt lgkmcnt(2)
	v_mfma_f32_32x32x16_bf16 v[2:17], v[42:45], v[34:37], v[2:17]
	s_waitcnt lgkmcnt(0)
	v_mfma_f32_32x32x16_bf16 v[18:33], v[46:49], v[34:37], v[18:33]
	ds_read_b64_tr_b16 v[34:35], v106 offset:57344
	ds_read_b64_tr_b16 v[36:37], v106 offset:57856
	ds_read_b64_tr_b16 v[42:43], v106 offset:61440
	ds_read_b64_tr_b16 v[44:45], v106 offset:61952
	s_waitcnt lgkmcnt(2)
	v_mfma_f32_32x32x16_bf16 v[2:17], v[34:37], v[38:41], v[2:17]
	ds_read_b128 v[34:37], v109 offset:31232
	ds_read_b128 v[72:75], v109 offset:31264
	s_waitcnt lgkmcnt(2)
	v_mfma_f32_32x32x16_bf16 v[18:33], v[42:45], v[38:41], v[18:33]
	s_waitcnt lgkmcnt(1)
	v_mfma_f32_32x32x16_bf16 v[34:49], v[34:37], v[62:65], 0
	s_waitcnt lgkmcnt(0)
	v_mfma_f32_32x32x16_bf16 v[34:49], v[72:75], v[58:61], v[34:49]
	ds_read_b128 v[72:75], v109 offset:31296
	s_waitcnt lgkmcnt(0)
	v_mfma_f32_32x32x16_bf16 v[34:49], v[72:75], v[54:57], v[34:49]
	ds_read_b128 v[72:75], v109 offset:31328
	s_waitcnt lgkmcnt(0)
	v_mfma_f32_32x32x16_bf16 v[34:49], v[72:75], v[50:53], v[34:49]
	s_nop 11
	v_max3_f32 v68, v34, s62, v35
	v_max3_f32 v68, v68, v36, v37
	v_max3_f32 v68, v68, v38, v39
	v_max3_f32 v68, v68, v40, v41
	v_max3_f32 v68, v68, v42, v43
	v_max3_f32 v68, v68, v44, v45
	v_max3_f32 v68, v68, v46, v47
	v_max3_f32 v68, v68, v48, v49
	v_mov_b32_e32 v69, v68
	s_nop 1
	v_permlane32_swap_b32_e32 v68, v69
	v_max_f32_e32 v68, v68, v69
	v_mul_f32_e32 v68, 0x3e38aa3b, v68
	v_add_f32_e32 v69, 0x41000000, v66
	v_cmp_gt_f32_e32 vcc, v68, v69
	s_nop 1
	v_cndmask_b32_e32 v68, v66, v68, vcc
	v_fma_f32 v34, v34, s91, -v68
	v_exp_f32_e32 v118, v34
	v_fma_f32 v34, v35, s91, -v68
	v_fma_f32 v35, v36, s91, -v68
	v_sub_f32_e32 v66, v66, v68
	v_exp_f32_e32 v120, v35
	v_fma_f32 v35, v37, s91, -v68
	v_fma_f32 v36, v38, s91, -v68
	v_fma_f32 v37, v40, s91, -v68
	v_exp_f32_e32 v122, v36
	v_fma_f32 v36, v39, s91, -v68
	v_exp_f32_e32 v124, v37
	v_fma_f32 v37, v41, s91, -v68
	v_fma_f32 v38, v42, s91, -v68
	v_fma_f32 v39, v44, s91, -v68
	v_fma_f32 v40, v46, s91, -v68
	v_fma_f32 v41, v48, s91, -v68
	v_exp_f32_e32 v66, v66
	v_exp_f32_e32 v126, v38
	v_fma_f32 v38, v43, s91, -v68
	v_exp_f32_e32 v128, v39
	v_fma_f32 v39, v45, s91, -v68
	v_exp_f32_e32 v130, v40
	v_fma_f32 v40, v47, s91, -v68
	v_exp_f32_e32 v132, v41
	v_fma_f32 v41, v49, s91, -v68
	v_exp_f32_e32 v119, v34
	v_exp_f32_e32 v121, v35
	v_exp_f32_e32 v123, v36
	v_exp_f32_e32 v125, v37
	v_exp_f32_e32 v127, v38
	v_exp_f32_e32 v129, v39
	v_exp_f32_e32 v131, v40
	v_exp_f32_e32 v133, v41
	v_cmp_eq_f32_e32 vcc, 1.0, v66
	s_cmp_eq_u64 vcc, exec
	v_cvt_pk_bf16_f32 v34, v118, v119
	v_cvt_pk_bf16_f32 v35, v120, v121
	v_cvt_pk_bf16_f32 v36, v122, v123
	v_cvt_pk_bf16_f32 v37, v124, v125
	v_cvt_pk_bf16_f32 v38, v126, v127
	v_cvt_pk_bf16_f32 v39, v128, v129
	v_cvt_pk_bf16_f32 v40, v130, v131
	v_cvt_pk_bf16_f32 v41, v132, v133
	s_cbranch_scc1 .LBB0_898
	v_pk_mul_f32 v[16:17], v[16:17], v[66:67] op_sel_hi:[1,0]
	v_pk_mul_f32 v[14:15], v[14:15], v[66:67] op_sel_hi:[1,0]
	v_pk_mul_f32 v[12:13], v[12:13], v[66:67] op_sel_hi:[1,0]
	v_pk_mul_f32 v[10:11], v[10:11], v[66:67] op_sel_hi:[1,0]
	v_pk_mul_f32 v[8:9], v[8:9], v[66:67] op_sel_hi:[1,0]
	v_pk_mul_f32 v[6:7], v[6:7], v[66:67] op_sel_hi:[1,0]
	v_pk_mul_f32 v[4:5], v[4:5], v[66:67] op_sel_hi:[1,0]
	v_pk_mul_f32 v[2:3], v[2:3], v[66:67] op_sel_hi:[1,0]
	v_pk_mul_f32 v[32:33], v[32:33], v[66:67] op_sel_hi:[1,0]
	v_pk_mul_f32 v[30:31], v[30:31], v[66:67] op_sel_hi:[1,0]
	v_pk_mul_f32 v[28:29], v[28:29], v[66:67] op_sel_hi:[1,0]
	v_pk_mul_f32 v[26:27], v[26:27], v[66:67] op_sel_hi:[1,0]
	v_pk_mul_f32 v[24:25], v[24:25], v[66:67] op_sel_hi:[1,0]
	v_pk_mul_f32 v[22:23], v[22:23], v[66:67] op_sel_hi:[1,0]
	v_pk_mul_f32 v[20:21], v[20:21], v[66:67] op_sel_hi:[1,0]
	v_pk_mul_f32 v[18:19], v[18:19], v[66:67] op_sel_hi:[1,0]
.LBB0_898:
	ds_read_b64_tr_b16 v[42:43], v106 offset:58368
	ds_read_b64_tr_b16 v[44:45], v106 offset:58880
	ds_read_b64_tr_b16 v[46:47], v106 offset:62464
	ds_read_b64_tr_b16 v[48:49], v106 offset:62976
	s_waitcnt lgkmcnt(2)
	v_mfma_f32_32x32x16_bf16 v[2:17], v[42:45], v[34:37], v[2:17]
	s_waitcnt lgkmcnt(0)
	v_mfma_f32_32x32x16_bf16 v[18:33], v[46:49], v[34:37], v[18:33]
	ds_read_b64_tr_b16 v[34:35], v106 offset:59392
	ds_read_b64_tr_b16 v[36:37], v106 offset:59904
	ds_read_b64_tr_b16 v[42:43], v106 offset:63488
	ds_read_b64_tr_b16 v[44:45], v106 offset:64000
	s_waitcnt vmcnt(0)
	s_barrier
	s_waitcnt lgkmcnt(2)
	v_mfma_f32_32x32x16_bf16 v[2:17], v[34:37], v[38:41], v[2:17]
	ds_read_b128 v[34:37], v109
	ds_read_b128 v[72:75], v109 offset:32
	s_waitcnt lgkmcnt(2)
	v_mfma_f32_32x32x16_bf16 v[18:33], v[42:45], v[38:41], v[18:33]
	s_waitcnt lgkmcnt(1)
	v_mfma_f32_32x32x16_bf16 v[34:49], v[34:37], v[62:65], 0
	s_waitcnt lgkmcnt(0)
	v_mfma_f32_32x32x16_bf16 v[34:49], v[72:75], v[58:61], v[34:49]
	ds_read_b128 v[72:75], v109 offset:64
	s_waitcnt lgkmcnt(0)
	v_mfma_f32_32x32x16_bf16 v[34:49], v[72:75], v[54:57], v[34:49]
	ds_read_b128 v[72:75], v109 offset:96
	s_waitcnt lgkmcnt(0)
	v_mfma_f32_32x32x16_bf16 v[34:49], v[72:75], v[50:53], v[34:49]
	s_nop 11
	v_max3_f32 v69, v34, s62, v35
	v_max3_f32 v69, v69, v36, v37
	v_max3_f32 v69, v69, v38, v39
	v_max3_f32 v69, v69, v40, v41
	v_max3_f32 v69, v69, v42, v43
	v_max3_f32 v69, v69, v44, v45
	v_max3_f32 v69, v69, v46, v47
	v_max3_f32 v69, v69, v48, v49
	v_mov_b32_e32 v72, v69
	s_nop 1
	v_permlane32_swap_b32_e32 v69, v72
	v_max_f32_e32 v69, v69, v72
	v_mul_f32_e32 v69, 0x3e38aa3b, v69
	v_add_f32_e32 v72, 0x41000000, v68
	v_cmp_gt_f32_e32 vcc, v69, v72
	s_nop 1
	v_cndmask_b32_e32 v69, v68, v69, vcc
	v_fma_f32 v34, v34, s91, -v69
	v_exp_f32_e32 v134, v34
	v_fma_f32 v34, v35, s91, -v69
	v_fma_f32 v35, v36, s91, -v69
	v_sub_f32_e32 v73, v68, v69
	v_exp_f32_e32 v68, v35
	v_fma_f32 v35, v37, s91, -v69
	v_fma_f32 v36, v38, s91, -v69
	v_fma_f32 v37, v40, s91, -v69
	v_exp_f32_e32 v74, v36
	v_fma_f32 v36, v39, s91, -v69
	v_exp_f32_e32 v78, v37
	v_fma_f32 v37, v41, s91, -v69
	v_fma_f32 v38, v42, s91, -v69
	v_fma_f32 v39, v44, s91, -v69
	v_fma_f32 v40, v46, s91, -v69
	v_fma_f32 v41, v48, s91, -v69
	v_exp_f32_e32 v98, v73
	v_exp_f32_e32 v82, v38
	v_fma_f32 v38, v43, s91, -v69
	v_exp_f32_e32 v86, v39
	v_fma_f32 v39, v45, s91, -v69
	v_exp_f32_e32 v90, v40
	v_fma_f32 v40, v47, s91, -v69
	v_exp_f32_e32 v94, v41
	v_fma_f32 v41, v49, s91, -v69
	v_exp_f32_e32 v135, v34
	v_exp_f32_e32 v72, v35
	v_exp_f32_e32 v76, v36
	v_exp_f32_e32 v80, v37
	v_exp_f32_e32 v84, v38
	v_exp_f32_e32 v88, v39
	v_exp_f32_e32 v92, v40
	v_exp_f32_e32 v96, v41
	v_cmp_eq_f32_e32 vcc, 1.0, v98
	s_cmp_eq_u64 vcc, exec
	v_cvt_pk_bf16_f32 v34, v134, v135
	v_cvt_pk_bf16_f32 v35, v68, v72
	v_cvt_pk_bf16_f32 v36, v74, v76
	v_cvt_pk_bf16_f32 v37, v78, v80
	v_cvt_pk_bf16_f32 v38, v82, v84
	v_cvt_pk_bf16_f32 v39, v86, v88
	v_cvt_pk_bf16_f32 v40, v90, v92
	v_cvt_pk_bf16_f32 v41, v94, v96
	s_cbranch_scc1 .LBB0_900
	v_pk_mul_f32 v[16:17], v[16:17], v[98:99] op_sel_hi:[1,0]
	v_pk_mul_f32 v[14:15], v[14:15], v[98:99] op_sel_hi:[1,0]
	v_pk_mul_f32 v[12:13], v[12:13], v[98:99] op_sel_hi:[1,0]
	v_pk_mul_f32 v[10:11], v[10:11], v[98:99] op_sel_hi:[1,0]
	v_pk_mul_f32 v[8:9], v[8:9], v[98:99] op_sel_hi:[1,0]
	v_pk_mul_f32 v[6:7], v[6:7], v[98:99] op_sel_hi:[1,0]
	v_pk_mul_f32 v[4:5], v[4:5], v[98:99] op_sel_hi:[1,0]
	v_pk_mul_f32 v[2:3], v[2:3], v[98:99] op_sel_hi:[1,0]
	v_pk_mul_f32 v[32:33], v[32:33], v[98:99] op_sel_hi:[1,0]
	v_pk_mul_f32 v[30:31], v[30:31], v[98:99] op_sel_hi:[1,0]
	v_pk_mul_f32 v[28:29], v[28:29], v[98:99] op_sel_hi:[1,0]
	v_pk_mul_f32 v[26:27], v[26:27], v[98:99] op_sel_hi:[1,0]
	v_pk_mul_f32 v[24:25], v[24:25], v[98:99] op_sel_hi:[1,0]
	v_pk_mul_f32 v[22:23], v[22:23], v[98:99] op_sel_hi:[1,0]
	v_pk_mul_f32 v[20:21], v[20:21], v[98:99] op_sel_hi:[1,0]
	v_pk_mul_f32 v[18:19], v[18:19], v[98:99] op_sel_hi:[1,0]
.LBB0_900:
	ds_read_b64_tr_b16 v[42:43], v106 offset:39936
	ds_read_b64_tr_b16 v[44:45], v106 offset:40448
	ds_read_b64_tr_b16 v[46:47], v106 offset:44032
	ds_read_b64_tr_b16 v[48:49], v106 offset:44544
	s_waitcnt lgkmcnt(2)
	v_mfma_f32_32x32x16_bf16 v[2:17], v[42:45], v[34:37], v[2:17]
	s_waitcnt lgkmcnt(0)
	v_mfma_f32_32x32x16_bf16 v[18:33], v[46:49], v[34:37], v[18:33]
	ds_read_b64_tr_b16 v[34:35], v106 offset:40960
	ds_read_b64_tr_b16 v[36:37], v106 offset:41472
	ds_read_b64_tr_b16 v[42:43], v106 offset:45056
	ds_read_b64_tr_b16 v[44:45], v106 offset:45568
	s_waitcnt lgkmcnt(2)
	v_mfma_f32_32x32x16_bf16 v[2:17], v[34:37], v[38:41], v[2:17]
	ds_read_b128 v[34:37], v109 offset:4608
	ds_read_b128 v[136:139], v109 offset:4640
	s_waitcnt lgkmcnt(2)
	v_mfma_f32_32x32x16_bf16 v[18:33], v[42:45], v[38:41], v[18:33]
	s_waitcnt lgkmcnt(1)
	v_mfma_f32_32x32x16_bf16 v[34:49], v[34:37], v[62:65], 0
	s_waitcnt lgkmcnt(0)
	v_mfma_f32_32x32x16_bf16 v[34:49], v[136:139], v[58:61], v[34:49]
	ds_read_b128 v[58:61], v109 offset:4672
	s_waitcnt lgkmcnt(0)
	v_mfma_f32_32x32x16_bf16 v[34:49], v[58:61], v[54:57], v[34:49]
	ds_read_b128 v[54:57], v109 offset:4704
	s_waitcnt lgkmcnt(0)
	v_mfma_f32_32x32x16_bf16 v[34:49], v[54:57], v[50:53], v[34:49]
	s_nop 11
	v_max3_f32 v50, v34, s62, v35
	v_max3_f32 v50, v50, v36, v37
	v_max3_f32 v50, v50, v38, v39
	v_max3_f32 v50, v50, v40, v41
	v_max3_f32 v50, v50, v42, v43
	v_max3_f32 v50, v50, v44, v45
	v_max3_f32 v50, v50, v46, v47
	v_max3_f32 v50, v50, v48, v49
	v_mov_b32_e32 v51, v50
	s_nop 1
	v_permlane32_swap_b32_e32 v50, v51
	v_max_f32_e32 v50, v50, v51
	v_mul_f32_e32 v50, 0x3e38aa3b, v50
	v_add_f32_e32 v51, 0x41000000, v69
	v_cmp_gt_f32_e32 vcc, v50, v51
	s_nop 1
	v_cndmask_b32_e32 v54, v69, v50, vcc
	v_fma_f32 v34, v34, s91, -v54
	v_sub_f32_e32 v55, v69, v54
	v_exp_f32_e32 v69, v34
	v_fma_f32 v34, v35, s91, -v54
	v_exp_f32_e32 v73, v34
	v_fma_f32 v34, v36, s91, -v54
	v_exp_f32_e32 v75, v34
	v_fma_f32 v34, v37, s91, -v54
	v_exp_f32_e32 v77, v34
	v_fma_f32 v34, v38, s91, -v54
	v_exp_f32_e32 v79, v34
	v_fma_f32 v34, v39, s91, -v54
	v_exp_f32_e32 v81, v34
	v_fma_f32 v34, v40, s91, -v54
	v_exp_f32_e32 v83, v34
	v_fma_f32 v34, v41, s91, -v54
	v_exp_f32_e32 v85, v34
	v_fma_f32 v34, v42, s91, -v54
	v_fma_f32 v35, v44, s91, -v54
	v_fma_f32 v36, v46, s91, -v54
	v_fma_f32 v37, v48, s91, -v54
	v_exp_f32_e32 v40, v55
	v_exp_f32_e32 v87, v34
	v_fma_f32 v34, v43, s91, -v54
	v_exp_f32_e32 v91, v35
	v_fma_f32 v35, v45, s91, -v54
	v_exp_f32_e32 v95, v36
	v_fma_f32 v36, v47, s91, -v54
	v_exp_f32_e32 v38, v37
	v_fma_f32 v37, v49, s91, -v54
	v_exp_f32_e32 v89, v34
	v_exp_f32_e32 v93, v35
	v_exp_f32_e32 v97, v36
	v_exp_f32_e32 v39, v37
	v_cmp_eq_f32_e32 vcc, 1.0, v40
	s_cmp_eq_u64 vcc, exec
	v_cvt_pk_bf16_f32 v50, v69, v73
	v_cvt_pk_bf16_f32 v51, v75, v77
	v_cvt_pk_bf16_f32 v52, v79, v81
	v_cvt_pk_bf16_f32 v53, v83, v85
	v_cvt_pk_bf16_f32 v34, v87, v89
	v_cvt_pk_bf16_f32 v35, v91, v93
	v_cvt_pk_bf16_f32 v36, v95, v97
	v_cvt_pk_bf16_f32 v37, v38, v39
	s_cbranch_scc1 .LBB0_902
	v_pk_mul_f32 v[16:17], v[16:17], v[40:41] op_sel_hi:[1,0]
	v_pk_mul_f32 v[14:15], v[14:15], v[40:41] op_sel_hi:[1,0]
	v_pk_mul_f32 v[12:13], v[12:13], v[40:41] op_sel_hi:[1,0]
	v_pk_mul_f32 v[10:11], v[10:11], v[40:41] op_sel_hi:[1,0]
	v_pk_mul_f32 v[8:9], v[8:9], v[40:41] op_sel_hi:[1,0]
	v_pk_mul_f32 v[6:7], v[6:7], v[40:41] op_sel_hi:[1,0]
	v_pk_mul_f32 v[4:5], v[4:5], v[40:41] op_sel_hi:[1,0]
	v_pk_mul_f32 v[2:3], v[2:3], v[40:41] op_sel_hi:[1,0]
	v_pk_mul_f32 v[32:33], v[32:33], v[40:41] op_sel_hi:[1,0]
	v_pk_mul_f32 v[30:31], v[30:31], v[40:41] op_sel_hi:[1,0]
	v_pk_mul_f32 v[28:29], v[28:29], v[40:41] op_sel_hi:[1,0]
	v_pk_mul_f32 v[26:27], v[26:27], v[40:41] op_sel_hi:[1,0]
	v_pk_mul_f32 v[24:25], v[24:25], v[40:41] op_sel_hi:[1,0]
	v_pk_mul_f32 v[22:23], v[22:23], v[40:41] op_sel_hi:[1,0]
	v_pk_mul_f32 v[20:21], v[20:21], v[40:41] op_sel_hi:[1,0]
	v_pk_mul_f32 v[18:19], v[18:19], v[40:41] op_sel_hi:[1,0]
.LBB0_902:
	v_add_f32_e32 v41, v67, v99
	v_add_f32_e32 v42, v100, v101
	v_add_f32_e32 v41, v42, v41
	v_add_f32_e32 v42, v102, v103
	v_add_f32_e32 v41, v42, v41
	v_add_f32_e32 v42, v104, v105
	v_add_f32_e32 v41, v42, v41
	v_add_f32_e32 v42, v110, v111
	v_add_f32_e32 v41, v42, v41
	v_add_f32_e32 v42, v112, v113
	v_add_f32_e32 v41, v42, v41
	v_add_f32_e32 v42, v114, v115
	v_add_f32_e32 v41, v42, v41
	v_add_f32_e32 v42, v116, v117
	v_add_f32_e32 v41, v42, v41
	v_fmac_f32_e32 v41, v108, v0
	v_add_f32_e32 v0, v118, v119
	v_add_f32_e32 v42, v120, v121
	v_add_f32_e32 v0, v42, v0
	v_add_f32_e32 v42, v122, v123
	v_add_f32_e32 v0, v42, v0
	v_add_f32_e32 v42, v124, v125
	v_add_f32_e32 v0, v42, v0
	v_add_f32_e32 v42, v126, v127
	v_add_f32_e32 v0, v42, v0
	v_add_f32_e32 v42, v128, v129
	v_add_f32_e32 v0, v42, v0
	v_add_f32_e32 v42, v130, v131
	v_add_f32_e32 v0, v42, v0
	v_add_f32_e32 v42, v132, v133
	v_add_f32_e32 v0, v42, v0
	v_fmac_f32_e32 v0, v41, v66
	v_mul_f32_e32 v42, v0, v98
	v_add_f32_e32 v0, v134, v135
	v_add_f32_e32 v43, v38, v39
	v_pk_add_f32 v[38:39], v[68:69], v[72:73]
	v_pk_add_f32 v[44:45], v[74:75], v[76:77]
	v_pk_add_f32 v[38:39], v[38:39], v[0:1]
	v_pk_add_f32 v[46:47], v[78:79], v[80:81]
	v_pk_add_f32 v[38:39], v[44:45], v[38:39]
	v_pk_add_f32 v[48:49], v[82:83], v[84:85]
	v_pk_add_f32 v[38:39], v[46:47], v[38:39]
	v_pk_add_f32 v[54:55], v[86:87], v[88:89]
	v_pk_add_f32 v[38:39], v[48:49], v[38:39]
	v_pk_add_f32 v[56:57], v[90:91], v[92:93]
	v_pk_add_f32 v[38:39], v[54:55], v[38:39]
	v_pk_add_f32 v[58:59], v[94:95], v[96:97]
	v_pk_add_f32 v[38:39], v[56:57], v[38:39]
	s_lshl_b32 s86, s68, 1
	v_pk_add_f32 v[38:39], v[58:59], v[38:39]
	s_nop 0
	v_pk_add_f32 v[38:39], v[42:43], v[38:39]
	ds_read_b64_tr_b16 v[42:43], v106 offset:41984
	ds_read_b64_tr_b16 v[44:45], v106 offset:42496
	ds_read_b64_tr_b16 v[46:47], v106 offset:46080
	ds_read_b64_tr_b16 v[48:49], v106 offset:46592
	s_waitcnt lgkmcnt(2)
	v_mfma_f32_32x32x16_bf16 v[2:17], v[42:45], v[50:53], v[2:17]
	v_fmac_f32_e32 v39, v38, v40
	v_mov_b32_e32 v0, v39
	s_nop 1
	v_permlane32_swap_b32_e32 v39, v0
	v_add_f32_e32 v0, v39, v0
	v_lshlrev_b32_e32 v40, 2, v107
	v_ashrrev_i32_e32 v41, 31, v40
	s_waitcnt lgkmcnt(0)
	v_mfma_f32_32x32x16_bf16 v[18:33], v[46:49], v[50:53], v[18:33]
	ds_read_b64_tr_b16 v[42:43], v106 offset:43008
	ds_read_b64_tr_b16 v[44:45], v106 offset:43520
	ds_read_b64_tr_b16 v[46:47], v106 offset:47104
	ds_read_b64_tr_b16 v[48:49], v106 offset:47616
	s_waitcnt lgkmcnt(2)
	v_mfma_f32_32x32x16_bf16 v[2:17], v[42:45], v[34:37], v[2:17]
	s_waitcnt lgkmcnt(0)
	v_mfma_f32_32x32x16_bf16 v[18:33], v[46:49], v[34:37], v[18:33]
	v_div_scale_f32 v36, s[38:39], v0, v0, 1.0
	v_rcp_f32_e32 v37, v36
	v_lshlrev_b64 v[34:35], 10, v[70:71]
	v_lshl_add_u64 v[34:35], s[24:25], 0, v[34:35]
	v_lshl_add_u64 v[34:35], v[34:35], 0, s[86:87]
	v_fma_f32 v38, -v36, v37, 1.0
	v_fmac_f32_e32 v37, v38, v37
	v_div_scale_f32 v38, vcc, 1.0, v0, 1.0
	v_mul_f32_e32 v39, v38, v37
	v_lshl_add_u64 v[34:35], v[40:41], 1, v[34:35]
	v_fma_f32 v40, -v36, v39, v38
	v_fmac_f32_e32 v39, v40, v37
	v_fma_f32 v36, -v36, v39, v38
	v_div_fmas_f32 v36, v36, v37, v39
	v_div_fixup_f32 v0, v36, v0, 1.0
	v_mul_f32_e32 v2, v2, v0
	v_mul_f32_e32 v3, v3, v0
	v_cvt_pk_bf16_f32 v2, v2, v3
	v_mul_f32_e32 v3, v4, v0
	v_mul_f32_e32 v4, v5, v0
	v_cvt_pk_bf16_f32 v3, v3, v4
	v_mul_f32_e32 v4, v18, v0
	v_mul_f32_e32 v5, v19, v0
	v_cvt_pk_bf16_f32 v4, v4, v5
	v_mul_f32_e32 v5, v20, v0
	v_mul_f32_e32 v18, v21, v0
	v_cvt_pk_bf16_f32 v5, v5, v18
	global_store_dwordx2 v[34:35], v[2:3], off
	global_store_dwordx2 v[34:35], v[4:5], off offset:64
	v_mul_f32_e32 v2, v6, v0
	v_mul_f32_e32 v3, v7, v0
	v_cvt_pk_bf16_f32 v2, v2, v3
	v_mul_f32_e32 v3, v8, v0
	v_mul_f32_e32 v4, v9, v0
	v_cvt_pk_bf16_f32 v3, v3, v4
	v_mul_f32_e32 v4, v22, v0
	v_mul_f32_e32 v5, v23, v0
	v_cvt_pk_bf16_f32 v4, v4, v5
	v_mul_f32_e32 v5, v24, v0
	v_mul_f32_e32 v6, v25, v0
	v_cvt_pk_bf16_f32 v5, v5, v6
	global_store_dwordx2 v[34:35], v[2:3], off offset:16
	global_store_dwordx2 v[34:35], v[4:5], off offset:80
	v_mul_f32_e32 v2, v10, v0
	v_mul_f32_e32 v3, v11, v0
	v_cvt_pk_bf16_f32 v2, v2, v3
	v_mul_f32_e32 v3, v12, v0
	v_mul_f32_e32 v4, v13, v0
	v_cvt_pk_bf16_f32 v3, v3, v4
	v_mul_f32_e32 v4, v26, v0
	v_mul_f32_e32 v5, v27, v0
	v_cvt_pk_bf16_f32 v4, v4, v5
	v_mul_f32_e32 v5, v28, v0
	v_mul_f32_e32 v6, v29, v0
	v_cvt_pk_bf16_f32 v5, v5, v6
	global_store_dwordx2 v[34:35], v[2:3], off offset:32
	global_store_dwordx2 v[34:35], v[4:5], off offset:96
	v_mul_f32_e32 v2, v14, v0
	v_mul_f32_e32 v3, v15, v0
	v_cvt_pk_bf16_f32 v2, v2, v3
	v_mul_f32_e32 v3, v16, v0
	v_mul_f32_e32 v4, v17, v0
	v_cvt_pk_bf16_f32 v3, v3, v4
	v_mul_f32_e32 v4, v30, v0
	v_mul_f32_e32 v5, v31, v0
	v_cvt_pk_bf16_f32 v4, v4, v5
	v_mul_f32_e32 v5, v32, v0
	v_mul_f32_e32 v0, v33, v0
	v_cvt_pk_bf16_f32 v5, v5, v0
	global_store_dwordx2 v[34:35], v[2:3], off offset:48
	global_store_dwordx2 v[34:35], v[4:5], off offset:112
	s_barrier
	s_branch .LBB0_871

.LBB0_929:
	s_or_b32 s78, s86, s70
	s_ashr_i32 s79, s78, 31
	s_lshl_b64 vcc, s[78:79], 11
	s_add_u32 s56, s47, vcc_lo
	s_addc_u32 s86, s48, vcc_hi
	s_lshl_b64 s[78:79], s[78:79], 6
	s_add_u32 s78, s67, s78
	s_addc_u32 s79, s40, s79
	s_lshl_b32 vcc_lo, s81, 13
	s_add_i32 vcc_lo, vcc_lo, 0x9c00
	s_mul_i32 vcc_hi, s81, 0x3400
	v_mov_b32_e32 v36, s79
	v_mov_b32_e32 v38, s78
	s_and_b64 s[78:79], s[34:35], exec
	v_mov_b32_e32 v37, s56
	s_cselect_b32 s56, vcc_hi, vcc_lo
	v_mov_b32_e32 v0, s86
	s_add_i32 m0, s50, s56
	v_cndmask_b32_e64 v35, v0, v36, s[72:73]
	v_cndmask_b32_e64 v34, v37, v38, s[72:73]
	s_and_b64 s[78:79], s[30:31], exec
	s_waitcnt vmcnt(3)
	s_barrier
	v_lshl_add_u64 v[34:35], v[80:81], 1, v[34:35]
	s_cselect_b32 s56, vcc_hi, vcc_lo
	global_load_lds_dwordx4 v[34:35], off
	v_cndmask_b32_e64 v35, v0, v36, s[74:75]
	v_cndmask_b32_e64 v34, v37, v38, s[74:75]
	s_add_i32 m0, s51, s56
	v_lshl_add_u64 v[34:35], v[82:83], 1, v[34:35]
	s_and_b64 s[78:79], s[94:95], exec
	global_load_lds_dwordx4 v[34:35], off
	v_cndmask_b32_e64 v35, v0, v36, s[68:69]
	v_cndmask_b32_e64 v34, v37, v38, s[68:69]
	s_cselect_b32 s56, vcc_hi, vcc_lo
	v_lshl_add_u64 v[34:35], v[84:85], 1, v[34:35]
	s_add_i32 m0, s49, s56
	s_mul_i32 s56, s71, 0x3400
	global_load_lds_dwordx4 v[34:35], off
	v_add_u32_e32 v136, s56, v117
	ds_read_b128 v[34:37], v136
	ds_read_b128 v[120:123], v136 offset:32
	s_waitcnt lgkmcnt(0)
	v_mfma_f32_32x32x16_bf16 v[34:49], v[34:37], v[70:73], 0
	v_mfma_f32_32x32x16_bf16 v[34:49], v[120:123], v[66:69], v[34:49]
	ds_read_b128 v[120:123], v136 offset:64
	s_waitcnt lgkmcnt(0)
	v_mfma_f32_32x32x16_bf16 v[34:49], v[120:123], v[62:65], v[34:49]
	ds_read_b128 v[120:123], v136 offset:96
	s_waitcnt lgkmcnt(0)
	v_mfma_f32_32x32x16_bf16 v[34:49], v[120:123], v[58:61], v[34:49]
	ds_read_b128 v[120:123], v136 offset:128
	s_waitcnt lgkmcnt(0)
	v_mfma_f32_32x32x16_bf16 v[34:49], v[120:123], v[54:57], v[34:49]
	ds_read_b128 v[120:123], v136 offset:160
	s_waitcnt lgkmcnt(0)
	v_mfma_f32_32x32x16_bf16 v[34:49], v[120:123], v[50:53], v[34:49]
	s_nop 11
	v_max3_f32 v0, v34, s62, v35
	v_max3_f32 v0, v0, v36, v37
	v_max3_f32 v0, v0, v38, v39
	v_max3_f32 v0, v0, v40, v41
	v_max3_f32 v0, v0, v42, v43
	v_max3_f32 v0, v0, v44, v45
	v_max3_f32 v0, v0, v46, v47
	v_max3_f32 v0, v0, v48, v49
	v_mov_b32_e32 v119, v0
	s_nop 1
	v_permlane32_swap_b32_e32 v0, v119
	v_max_f32_e32 v0, v0, v119
	v_mul_f32_e32 v0, 0x3e16c740, v0
	v_add_f32_e32 v119, 0x41000000, v118
	v_cmp_gt_f32_e32 vcc, v0, v119
	s_nop 1
	v_cndmask_b32_e32 v135, v118, v0, vcc
	v_fma_f32 v34, v34, s63, -v135
	v_exp_f32_e32 v119, v34
	v_fma_f32 v34, v35, s63, -v135
	v_fma_f32 v35, v36, s63, -v135
	v_sub_f32_e32 v0, v118, v135
	v_exp_f32_e32 v121, v35
	v_fma_f32 v35, v37, s63, -v135
	v_fma_f32 v36, v38, s63, -v135
	v_fma_f32 v37, v40, s63, -v135
	v_exp_f32_e32 v123, v36
	v_fma_f32 v36, v39, s63, -v135
	v_exp_f32_e32 v125, v37
	v_fma_f32 v37, v41, s63, -v135
	v_fma_f32 v38, v42, s63, -v135
	v_fma_f32 v39, v44, s63, -v135
	v_fma_f32 v40, v46, s63, -v135
	v_fma_f32 v41, v48, s63, -v135
	v_exp_f32_e32 v0, v0
	v_exp_f32_e32 v127, v38
	v_fma_f32 v38, v43, s63, -v135
	v_exp_f32_e32 v129, v39
	v_fma_f32 v39, v45, s63, -v135
	v_exp_f32_e32 v131, v40
	v_fma_f32 v40, v47, s63, -v135
	v_exp_f32_e32 v133, v41
	v_fma_f32 v41, v49, s63, -v135
	v_exp_f32_e32 v120, v34
	v_exp_f32_e32 v122, v35
	v_exp_f32_e32 v124, v36
	v_exp_f32_e32 v126, v37
	v_exp_f32_e32 v128, v38
	v_exp_f32_e32 v130, v39
	v_exp_f32_e32 v132, v40
	v_exp_f32_e32 v134, v41
	v_cmp_eq_f32_e32 vcc, 1.0, v0
	s_cmp_eq_u64 vcc, exec
	v_cvt_pk_bf16_f32 v34, v119, v120
	v_cvt_pk_bf16_f32 v35, v121, v122
	v_cvt_pk_bf16_f32 v36, v123, v124
	v_cvt_pk_bf16_f32 v37, v125, v126
	v_cvt_pk_bf16_f32 v38, v127, v128
	v_cvt_pk_bf16_f32 v39, v129, v130
	v_cvt_pk_bf16_f32 v40, v131, v132
	v_cvt_pk_bf16_f32 v41, v133, v134
	s_cbranch_scc1 .LBB0_931
	v_pk_mul_f32 v[32:33], v[112:113], v[0:1] op_sel_hi:[1,0]
	v_pk_mul_f32 v[30:31], v[110:111], v[0:1] op_sel_hi:[1,0]
	v_pk_mul_f32 v[28:29], v[108:109], v[0:1] op_sel_hi:[1,0]
	v_pk_mul_f32 v[26:27], v[106:107], v[0:1] op_sel_hi:[1,0]
	v_pk_mul_f32 v[24:25], v[104:105], v[0:1] op_sel_hi:[1,0]
	v_pk_mul_f32 v[22:23], v[102:103], v[0:1] op_sel_hi:[1,0]
	v_pk_mul_f32 v[20:21], v[100:101], v[0:1] op_sel_hi:[1,0]
	v_pk_mul_f32 v[18:19], v[98:99], v[0:1] op_sel_hi:[1,0]
	v_pk_mul_f32 v[16:17], v[96:97], v[0:1] op_sel_hi:[1,0]
	v_pk_mul_f32 v[14:15], v[94:95], v[0:1] op_sel_hi:[1,0]
	v_pk_mul_f32 v[12:13], v[92:93], v[0:1] op_sel_hi:[1,0]
	v_pk_mul_f32 v[10:11], v[90:91], v[0:1] op_sel_hi:[1,0]
	v_pk_mul_f32 v[8:9], v[88:89], v[0:1] op_sel_hi:[1,0]
	v_pk_mul_f32 v[6:7], v[86:87], v[0:1] op_sel_hi:[1,0]
	v_pk_mul_f32 v[4:5], v[76:77], v[0:1] op_sel_hi:[1,0]
	v_pk_mul_f32 v[2:3], v[74:75], v[0:1] op_sel_hi:[1,0]
.LBB0_931:
	s_lshl_b32 s56, s71, 13
	v_add_u32_e32 v86, s56, v114
	ds_read_b64_tr_b16 v[42:43], v86 offset:39936
	ds_read_b64_tr_b16 v[44:45], v86 offset:40448
	ds_read_b64_tr_b16 v[46:47], v86 offset:44032
	ds_read_b64_tr_b16 v[48:49], v86 offset:44544
	s_waitcnt lgkmcnt(2)
	v_mfma_f32_32x32x16_bf16 v[2:17], v[42:45], v[34:37], v[2:17]
	s_waitcnt lgkmcnt(0)
	v_mfma_f32_32x32x16_bf16 v[18:33], v[46:49], v[34:37], v[18:33]
	ds_read_b64_tr_b16 v[34:35], v86 offset:40960
	ds_read_b64_tr_b16 v[36:37], v86 offset:41472
	ds_read_b64_tr_b16 v[42:43], v86 offset:45056
	ds_read_b64_tr_b16 v[44:45], v86 offset:45568
	s_waitcnt lgkmcnt(2)
	v_mfma_f32_32x32x16_bf16 v[2:17], v[34:37], v[38:41], v[2:17]
	ds_read_b128 v[34:37], v136 offset:6656
	ds_read_b128 v[74:77], v136 offset:6688
	s_waitcnt lgkmcnt(2)
	v_mfma_f32_32x32x16_bf16 v[18:33], v[42:45], v[38:41], v[18:33]
	s_waitcnt lgkmcnt(1)
	v_mfma_f32_32x32x16_bf16 v[34:49], v[34:37], v[70:73], 0
	s_waitcnt lgkmcnt(0)
	v_mfma_f32_32x32x16_bf16 v[34:49], v[74:77], v[66:69], v[34:49]
	ds_read_b128 v[74:77], v136 offset:6720
	s_waitcnt lgkmcnt(0)
	v_mfma_f32_32x32x16_bf16 v[34:49], v[74:77], v[62:65], v[34:49]
	ds_read_b128 v[74:77], v136 offset:6752
	s_waitcnt lgkmcnt(0)
	v_mfma_f32_32x32x16_bf16 v[34:49], v[74:77], v[58:61], v[34:49]
	ds_read_b128 v[74:77], v136 offset:6784
	s_waitcnt lgkmcnt(0)
	v_mfma_f32_32x32x16_bf16 v[34:49], v[74:77], v[54:57], v[34:49]
	ds_read_b128 v[74:77], v136 offset:6816
	s_waitcnt lgkmcnt(0)
	v_mfma_f32_32x32x16_bf16 v[34:49], v[74:77], v[50:53], v[34:49]
	s_nop 11
	v_max3_f32 v74, v34, s62, v35
	v_max3_f32 v74, v74, v36, v37
	v_max3_f32 v74, v74, v38, v39
	v_max3_f32 v74, v74, v40, v41
	v_max3_f32 v74, v74, v42, v43
	v_max3_f32 v74, v74, v44, v45
	v_max3_f32 v74, v74, v46, v47
	v_max3_f32 v74, v74, v48, v49
	v_mov_b32_e32 v75, v74
	s_nop 1
	v_permlane32_swap_b32_e32 v74, v75
	v_max_f32_e32 v74, v74, v75
	v_mul_f32_e32 v74, 0x3e16c740, v74
	v_add_f32_e32 v75, 0x41000000, v135
	v_cmp_gt_f32_e32 vcc, v74, v75
	s_nop 1
	v_cndmask_b32_e32 v118, v135, v74, vcc
	v_fma_f32 v34, v34, s63, -v118
	v_exp_f32_e32 v87, v34
	v_fma_f32 v34, v35, s63, -v118
	v_exp_f32_e32 v88, v34
	v_fma_f32 v34, v36, s63, -v118
	v_exp_f32_e32 v89, v34
	v_fma_f32 v34, v37, s63, -v118
	v_exp_f32_e32 v90, v34
	v_fma_f32 v34, v38, s63, -v118
	v_exp_f32_e32 v91, v34
	v_fma_f32 v34, v39, s63, -v118
	v_exp_f32_e32 v39, v34
	v_fma_f32 v34, v40, s63, -v118
	v_sub_f32_e32 v92, v135, v118
	v_exp_f32_e32 v40, v34
	v_fma_f32 v34, v41, s63, -v118
	v_exp_f32_e32 v41, v34
	v_fma_f32 v34, v42, s63, -v118
	v_fma_f32 v35, v44, s63, -v118
	v_fma_f32 v36, v46, s63, -v118
	v_fma_f32 v37, v48, s63, -v118
	v_exp_f32_e32 v38, v92
	v_exp_f32_e32 v42, v34
	v_fma_f32 v34, v43, s63, -v118
	v_exp_f32_e32 v44, v35
	v_fma_f32 v35, v45, s63, -v118
	v_exp_f32_e32 v46, v36
	v_fma_f32 v36, v47, s63, -v118
	v_exp_f32_e32 v48, v37
	v_fma_f32 v37, v49, s63, -v118
	v_exp_f32_e32 v43, v34
	v_exp_f32_e32 v45, v35
	v_exp_f32_e32 v47, v36
	v_exp_f32_e32 v49, v37
	v_cmp_eq_f32_e32 vcc, 1.0, v38
	s_cmp_eq_u64 vcc, exec
	v_cvt_pk_bf16_f32 v74, v87, v88
	v_cvt_pk_bf16_f32 v75, v89, v90
	v_cvt_pk_bf16_f32 v76, v91, v39
	v_cvt_pk_bf16_f32 v77, v40, v41
	v_cvt_pk_bf16_f32 v34, v42, v43
	v_cvt_pk_bf16_f32 v35, v44, v45
	v_cvt_pk_bf16_f32 v36, v46, v47
	v_cvt_pk_bf16_f32 v37, v48, v49
	s_cbranch_scc1 .LBB0_933
	v_pk_mul_f32 v[16:17], v[16:17], v[38:39] op_sel_hi:[1,0]
	v_pk_mul_f32 v[14:15], v[14:15], v[38:39] op_sel_hi:[1,0]
	v_pk_mul_f32 v[12:13], v[12:13], v[38:39] op_sel_hi:[1,0]
	v_pk_mul_f32 v[10:11], v[10:11], v[38:39] op_sel_hi:[1,0]
	v_pk_mul_f32 v[8:9], v[8:9], v[38:39] op_sel_hi:[1,0]
	v_pk_mul_f32 v[6:7], v[6:7], v[38:39] op_sel_hi:[1,0]
	v_pk_mul_f32 v[4:5], v[4:5], v[38:39] op_sel_hi:[1,0]
	v_pk_mul_f32 v[2:3], v[2:3], v[38:39] op_sel_hi:[1,0]
	v_pk_mul_f32 v[32:33], v[32:33], v[38:39] op_sel_hi:[1,0]
	v_pk_mul_f32 v[30:31], v[30:31], v[38:39] op_sel_hi:[1,0]
	v_pk_mul_f32 v[28:29], v[28:29], v[38:39] op_sel_hi:[1,0]
	v_pk_mul_f32 v[26:27], v[26:27], v[38:39] op_sel_hi:[1,0]
	v_pk_mul_f32 v[24:25], v[24:25], v[38:39] op_sel_hi:[1,0]
	v_pk_mul_f32 v[22:23], v[22:23], v[38:39] op_sel_hi:[1,0]
	v_pk_mul_f32 v[20:21], v[20:21], v[38:39] op_sel_hi:[1,0]
	v_pk_mul_f32 v[18:19], v[18:19], v[38:39] op_sel_hi:[1,0]
.LBB0_933:
	v_add_f32_e32 v92, v119, v120
	v_add_f32_e32 v93, v121, v122
	v_add_f32_e32 v92, v93, v92
	v_add_f32_e32 v93, v123, v124
	v_add_f32_e32 v92, v93, v92
	v_add_f32_e32 v93, v125, v126
	v_add_f32_e32 v92, v93, v92
	v_add_f32_e32 v93, v127, v128
	v_add_f32_e32 v92, v93, v92
	v_add_f32_e32 v93, v129, v130
	v_add_f32_e32 v92, v93, v92
	v_add_f32_e32 v93, v131, v132
	v_add_f32_e32 v92, v93, v92
	v_add_f32_e32 v93, v133, v134
	v_add_f32_e32 v92, v93, v92
	v_fmac_f32_e32 v92, v116, v0
	v_add_f32_e32 v0, v87, v88
	v_add_f32_e32 v87, v89, v90
	v_add_f32_e32 v0, v87, v0
	v_add_f32_e32 v39, v91, v39
	v_add_f32_e32 v0, v39, v0
	v_add_f32_e32 v39, v40, v41
	v_add_f32_e32 v0, v39, v0
	v_add_f32_e32 v39, v42, v43
	v_add_f32_e32 v0, v39, v0
	v_add_f32_e32 v39, v44, v45
	v_add_f32_e32 v0, v39, v0
	v_add_f32_e32 v39, v46, v47
	v_add_f32_e32 v0, v39, v0
	v_add_f32_e32 v39, v48, v49
	v_add_f32_e32 v116, v39, v0
	v_fmac_f32_e32 v116, v92, v38
	ds_read_b64_tr_b16 v[38:39], v86 offset:41984
	ds_read_b64_tr_b16 v[40:41], v86 offset:42496
	ds_read_b64_tr_b16 v[42:43], v86 offset:46080
	ds_read_b64_tr_b16 v[44:45], v86 offset:46592
	s_waitcnt lgkmcnt(2)
	v_mfma_f32_32x32x16_bf16 v[2:17], v[38:41], v[74:77], v[2:17]
	s_add_i32 s56, s71, 1
	s_cmp_lg_u32 s71, 2
	s_cselect_b32 s71, s56, 0
	s_add_i32 s56, s81, 1
	s_cmp_lg_u32 s81, 2
	s_cselect_b32 s81, s56, 0
	s_mov_b32 s86, 64
	s_waitcnt lgkmcnt(0)
	v_mfma_f32_32x32x16_bf16 v[18:33], v[42:45], v[74:77], v[18:33]
	ds_read_b64_tr_b16 v[38:39], v86 offset:43008
	ds_read_b64_tr_b16 v[40:41], v86 offset:43520
	ds_read_b64_tr_b16 v[42:43], v86 offset:47104
	ds_read_b64_tr_b16 v[44:45], v86 offset:47616
	s_and_b64 vcc, exec, s[38:39]
	s_waitcnt lgkmcnt(2)
	v_mfma_f32_32x32x16_bf16 v[2:17], v[38:41], v[34:37], v[2:17]
	s_waitcnt lgkmcnt(0)
	v_mfma_f32_32x32x16_bf16 v[18:33], v[42:45], v[34:37], v[18:33]
	s_cbranch_vccnz .LBB0_935
	s_mov_b64 s[38:39], -1
	s_nop 7
	v_mov_b32_e32 v74, v2
	v_mov_b32_e32 v75, v3
	v_mov_b32_e32 v76, v4
	v_mov_b32_e32 v77, v5
	v_mov_b32_e32 v86, v6
	v_mov_b32_e32 v87, v7
	v_mov_b32_e32 v88, v8
	v_mov_b32_e32 v89, v9
	v_mov_b32_e32 v90, v10
	v_mov_b32_e32 v91, v11
	v_mov_b32_e32 v92, v12
	v_mov_b32_e32 v93, v13
	v_mov_b32_e32 v94, v14
	v_mov_b32_e32 v95, v15
	v_mov_b32_e32 v96, v16
	v_mov_b32_e32 v97, v17
	v_mov_b32_e32 v98, v18
	v_mov_b32_e32 v99, v19
	v_mov_b32_e32 v100, v20
	v_mov_b32_e32 v101, v21
	v_mov_b32_e32 v102, v22
	v_mov_b32_e32 v103, v23
	v_mov_b32_e32 v104, v24
	v_mov_b32_e32 v105, v25
	v_mov_b32_e32 v106, v26
	v_mov_b32_e32 v107, v27
	v_mov_b32_e32 v108, v28
	v_mov_b32_e32 v109, v29
	v_mov_b32_e32 v110, v30
	v_mov_b32_e32 v111, v31
	v_mov_b32_e32 v112, v32
	v_mov_b32_e32 v113, v33
	s_branch .LBB0_929
.LBB0_935:
	s_waitcnt vmcnt(3)
	s_barrier
	ds_read_b128 v[34:37], v117 offset:26624
	ds_read_b128 v[74:77], v117 offset:26656
	v_add_f32_e32 v0, 0x41000000, v118
	s_waitcnt lgkmcnt(1)
	v_mfma_f32_32x32x16_bf16 v[34:49], v[34:37], v[70:73], 0
	s_waitcnt lgkmcnt(0)
	v_mfma_f32_32x32x16_bf16 v[34:49], v[74:77], v[66:69], v[34:49]
	ds_read_b128 v[74:77], v117 offset:26688
	s_waitcnt lgkmcnt(0)
	v_mfma_f32_32x32x16_bf16 v[34:49], v[74:77], v[62:65], v[34:49]
	ds_read_b128 v[74:77], v117 offset:26720
	s_waitcnt lgkmcnt(0)
	v_mfma_f32_32x32x16_bf16 v[34:49], v[74:77], v[58:61], v[34:49]
	ds_read_b128 v[74:77], v117 offset:26752
	s_waitcnt lgkmcnt(0)
	v_mfma_f32_32x32x16_bf16 v[34:49], v[74:77], v[54:57], v[34:49]
	ds_read_b128 v[74:77], v117 offset:26784
	s_waitcnt lgkmcnt(0)
	v_mfma_f32_32x32x16_bf16 v[34:49], v[74:77], v[50:53], v[34:49]
	s_nop 11
	v_max3_f32 v74, v34, s62, v35
	v_max3_f32 v74, v74, v36, v37
	v_max3_f32 v74, v74, v38, v39
	v_max3_f32 v74, v74, v40, v41
	v_max3_f32 v74, v74, v42, v43
	v_max3_f32 v74, v74, v44, v45
	v_max3_f32 v74, v74, v46, v47
	v_max3_f32 v74, v74, v48, v49
	v_mov_b32_e32 v75, v74
	s_nop 1
	v_permlane32_swap_b32_e32 v74, v75
	v_max_f32_e32 v74, v74, v75
	v_mul_f32_e32 v74, 0x3e16c740, v74
	v_cmp_gt_f32_e32 vcc, v74, v0
	s_nop 1
	v_cndmask_b32_e32 v74, v118, v74, vcc
	v_sub_f32_e32 v0, v118, v74
	v_exp_f32_e32 v0, v0
	v_fma_f32 v34, v34, s63, -v74
	v_fma_f32 v35, v35, s63, -v74
	v_fma_f32 v36, v36, s63, -v74
	v_fma_f32 v37, v37, s63, -v74
	v_fma_f32 v38, v38, s63, -v74
	v_fma_f32 v39, v39, s63, -v74
	v_fma_f32 v40, v40, s63, -v74
	v_fma_f32 v41, v41, s63, -v74
	v_fma_f32 v42, v42, s63, -v74
	v_fma_f32 v43, v43, s63, -v74
	v_fma_f32 v44, v44, s63, -v74
	v_fma_f32 v45, v45, s63, -v74
	v_fma_f32 v46, v46, s63, -v74
	v_fma_f32 v47, v47, s63, -v74
	v_fma_f32 v48, v48, s63, -v74
	v_fma_f32 v49, v49, s63, -v74
	v_exp_f32_e32 v75, v34
	v_exp_f32_e32 v118, v35
	v_exp_f32_e32 v107, v36
	v_exp_f32_e32 v119, v37
	v_exp_f32_e32 v108, v38
	v_exp_f32_e32 v120, v39
	v_exp_f32_e32 v109, v40
	v_exp_f32_e32 v121, v41
	v_exp_f32_e32 v110, v42
	v_exp_f32_e32 v122, v43
	v_exp_f32_e32 v111, v44
	v_exp_f32_e32 v123, v45
	v_exp_f32_e32 v112, v46
	v_exp_f32_e32 v124, v47
	v_exp_f32_e32 v113, v48
	v_exp_f32_e32 v125, v49
	v_cmp_eq_f32_e32 vcc, 1.0, v0
	s_cmp_eq_u64 vcc, exec
	v_cvt_pk_bf16_f32 v38, v75, v118
	v_cvt_pk_bf16_f32 v39, v107, v119
	v_cvt_pk_bf16_f32 v40, v108, v120
	v_cvt_pk_bf16_f32 v41, v109, v121
	v_cvt_pk_bf16_f32 v34, v110, v122
	v_cvt_pk_bf16_f32 v35, v111, v123
	v_cvt_pk_bf16_f32 v36, v112, v124
	v_cvt_pk_bf16_f32 v37, v113, v125
	s_cbranch_scc1 .LBB0_937
	v_pk_mul_f32 v[16:17], v[16:17], v[0:1] op_sel_hi:[1,0]
	v_pk_mul_f32 v[14:15], v[14:15], v[0:1] op_sel_hi:[1,0]
	v_pk_mul_f32 v[12:13], v[12:13], v[0:1] op_sel_hi:[1,0]
	v_pk_mul_f32 v[10:11], v[10:11], v[0:1] op_sel_hi:[1,0]
	v_pk_mul_f32 v[8:9], v[8:9], v[0:1] op_sel_hi:[1,0]
	v_pk_mul_f32 v[6:7], v[6:7], v[0:1] op_sel_hi:[1,0]
	v_pk_mul_f32 v[4:5], v[4:5], v[0:1] op_sel_hi:[1,0]
	v_pk_mul_f32 v[2:3], v[2:3], v[0:1] op_sel_hi:[1,0]
	v_pk_mul_f32 v[32:33], v[32:33], v[0:1] op_sel_hi:[1,0]
	v_pk_mul_f32 v[30:31], v[30:31], v[0:1] op_sel_hi:[1,0]
	v_pk_mul_f32 v[28:29], v[28:29], v[0:1] op_sel_hi:[1,0]
	v_pk_mul_f32 v[26:27], v[26:27], v[0:1] op_sel_hi:[1,0]
	v_pk_mul_f32 v[24:25], v[24:25], v[0:1] op_sel_hi:[1,0]
	v_pk_mul_f32 v[22:23], v[22:23], v[0:1] op_sel_hi:[1,0]
	v_pk_mul_f32 v[20:21], v[20:21], v[0:1] op_sel_hi:[1,0]
	v_pk_mul_f32 v[18:19], v[18:19], v[0:1] op_sel_hi:[1,0]
.LBB0_937:
	ds_read_b64_tr_b16 v[42:43], v114 offset:56320
	ds_read_b64_tr_b16 v[44:45], v114 offset:56832
	ds_read_b64_tr_b16 v[46:47], v114 offset:60416
	ds_read_b64_tr_b16 v[48:49], v114 offset:60928
	s_mov_b32 s92, 0x1ffffffc
	s_mov_b32 s93, 0x38e38e39
	s_waitcnt lgkmcnt(2)
	v_mfma_f32_32x32x16_bf16 v[2:17], v[42:45], v[38:41], v[2:17]
	s_waitcnt lgkmcnt(0)
	v_mfma_f32_32x32x16_bf16 v[18:33], v[46:49], v[38:41], v[18:33]
	ds_read_b64_tr_b16 v[38:39], v114 offset:57344
	ds_read_b64_tr_b16 v[40:41], v114 offset:57856
	ds_read_b64_tr_b16 v[42:43], v114 offset:61440
	ds_read_b64_tr_b16 v[44:45], v114 offset:61952
	s_waitcnt lgkmcnt(2)
	v_mfma_f32_32x32x16_bf16 v[2:17], v[38:41], v[34:37], v[2:17]
	s_waitcnt lgkmcnt(0)
	v_mfma_f32_32x32x16_bf16 v[18:33], v[42:45], v[34:37], v[18:33]
	ds_read_b128 v[34:37], v117 offset:33280
	ds_read_b128 v[80:83], v117 offset:33312
	s_waitcnt lgkmcnt(1)
	v_mfma_f32_32x32x16_bf16 v[34:49], v[34:37], v[70:73], 0
	s_waitcnt lgkmcnt(0)
	v_mfma_f32_32x32x16_bf16 v[34:49], v[80:83], v[66:69], v[34:49]
	ds_read_b128 v[80:83], v117 offset:33344
	s_waitcnt lgkmcnt(0)
	v_mfma_f32_32x32x16_bf16 v[34:49], v[80:83], v[62:65], v[34:49]
	ds_read_b128 v[80:83], v117 offset:33376
	s_waitcnt lgkmcnt(0)
	v_mfma_f32_32x32x16_bf16 v[34:49], v[80:83], v[58:61], v[34:49]
	ds_read_b128 v[80:83], v117 offset:33408
	s_waitcnt lgkmcnt(0)
	v_mfma_f32_32x32x16_bf16 v[34:49], v[80:83], v[54:57], v[34:49]
	ds_read_b128 v[80:83], v117 offset:33440
	s_waitcnt lgkmcnt(0)
	v_mfma_f32_32x32x16_bf16 v[34:49], v[80:83], v[50:53], v[34:49]
	s_nop 11
	v_max3_f32 v76, v34, s62, v35
	v_max3_f32 v76, v76, v36, v37
	v_max3_f32 v76, v76, v38, v39
	v_max3_f32 v76, v76, v40, v41
	v_max3_f32 v76, v76, v42, v43
	v_max3_f32 v76, v76, v44, v45
	v_max3_f32 v76, v76, v46, v47
	v_max3_f32 v76, v76, v48, v49
	v_mov_b32_e32 v77, v76
	s_nop 1
	v_permlane32_swap_b32_e32 v76, v77
	v_max_f32_e32 v76, v76, v77
	v_mul_f32_e32 v76, 0x3e16c740, v76
	v_add_f32_e32 v77, 0x41000000, v74
	v_cmp_gt_f32_e32 vcc, v76, v77
	s_nop 1
	v_cndmask_b32_e32 v76, v74, v76, vcc
	v_fma_f32 v34, v34, s63, -v76
	v_exp_f32_e32 v126, v34
	v_fma_f32 v34, v35, s63, -v76
	v_fma_f32 v35, v36, s63, -v76
	v_sub_f32_e32 v74, v74, v76
	v_exp_f32_e32 v128, v35
	v_fma_f32 v35, v37, s63, -v76
	v_fma_f32 v36, v38, s63, -v76
	v_fma_f32 v37, v40, s63, -v76
	v_exp_f32_e32 v130, v36
	v_fma_f32 v36, v39, s63, -v76
	v_exp_f32_e32 v132, v37
	v_fma_f32 v37, v41, s63, -v76
	v_fma_f32 v38, v42, s63, -v76
	v_fma_f32 v39, v44, s63, -v76
	v_fma_f32 v40, v46, s63, -v76
	v_fma_f32 v41, v48, s63, -v76
	v_exp_f32_e32 v74, v74
	v_exp_f32_e32 v134, v38
	v_fma_f32 v38, v43, s63, -v76
	v_exp_f32_e32 v136, v39
	v_fma_f32 v39, v45, s63, -v76
	v_exp_f32_e32 v138, v40
	v_fma_f32 v40, v47, s63, -v76
	v_exp_f32_e32 v140, v41
	v_fma_f32 v41, v49, s63, -v76
	v_exp_f32_e32 v127, v34
	v_exp_f32_e32 v129, v35
	v_exp_f32_e32 v131, v36
	v_exp_f32_e32 v133, v37
	v_exp_f32_e32 v135, v38
	v_exp_f32_e32 v137, v39
	v_exp_f32_e32 v139, v40
	v_exp_f32_e32 v141, v41
	v_cmp_eq_f32_e32 vcc, 1.0, v74
	s_cmp_eq_u64 vcc, exec
	v_cvt_pk_bf16_f32 v34, v126, v127
	v_cvt_pk_bf16_f32 v35, v128, v129
	v_cvt_pk_bf16_f32 v36, v130, v131
	v_cvt_pk_bf16_f32 v37, v132, v133
	v_cvt_pk_bf16_f32 v38, v134, v135
	v_cvt_pk_bf16_f32 v39, v136, v137
	v_cvt_pk_bf16_f32 v40, v138, v139
	v_cvt_pk_bf16_f32 v41, v140, v141
	s_cbranch_scc1 .LBB0_939
	v_pk_mul_f32 v[16:17], v[16:17], v[74:75] op_sel_hi:[1,0]
	v_pk_mul_f32 v[14:15], v[14:15], v[74:75] op_sel_hi:[1,0]
	v_pk_mul_f32 v[12:13], v[12:13], v[74:75] op_sel_hi:[1,0]
	v_pk_mul_f32 v[10:11], v[10:11], v[74:75] op_sel_hi:[1,0]
	v_pk_mul_f32 v[8:9], v[8:9], v[74:75] op_sel_hi:[1,0]
	v_pk_mul_f32 v[6:7], v[6:7], v[74:75] op_sel_hi:[1,0]
	v_pk_mul_f32 v[4:5], v[4:5], v[74:75] op_sel_hi:[1,0]
	v_pk_mul_f32 v[2:3], v[2:3], v[74:75] op_sel_hi:[1,0]
	v_pk_mul_f32 v[32:33], v[32:33], v[74:75] op_sel_hi:[1,0]
	v_pk_mul_f32 v[30:31], v[30:31], v[74:75] op_sel_hi:[1,0]
	v_pk_mul_f32 v[28:29], v[28:29], v[74:75] op_sel_hi:[1,0]
	v_pk_mul_f32 v[26:27], v[26:27], v[74:75] op_sel_hi:[1,0]
	v_pk_mul_f32 v[24:25], v[24:25], v[74:75] op_sel_hi:[1,0]
	v_pk_mul_f32 v[22:23], v[22:23], v[74:75] op_sel_hi:[1,0]
	v_pk_mul_f32 v[20:21], v[20:21], v[74:75] op_sel_hi:[1,0]
	v_pk_mul_f32 v[18:19], v[18:19], v[74:75] op_sel_hi:[1,0]
.LBB0_939:
	ds_read_b64_tr_b16 v[42:43], v114 offset:58368
	ds_read_b64_tr_b16 v[44:45], v114 offset:58880
	ds_read_b64_tr_b16 v[46:47], v114 offset:62464
	ds_read_b64_tr_b16 v[48:49], v114 offset:62976
	s_waitcnt lgkmcnt(2)
	v_mfma_f32_32x32x16_bf16 v[2:17], v[42:45], v[34:37], v[2:17]
	s_waitcnt lgkmcnt(0)
	v_mfma_f32_32x32x16_bf16 v[18:33], v[46:49], v[34:37], v[18:33]
	ds_read_b64_tr_b16 v[34:35], v114 offset:59392
	ds_read_b64_tr_b16 v[36:37], v114 offset:59904
	ds_read_b64_tr_b16 v[42:43], v114 offset:63488
	ds_read_b64_tr_b16 v[44:45], v114 offset:64000
	s_waitcnt vmcnt(0)
	s_barrier
	s_waitcnt lgkmcnt(2)
	v_mfma_f32_32x32x16_bf16 v[2:17], v[34:37], v[38:41], v[2:17]
	ds_read_b128 v[34:37], v117
	ds_read_b128 v[80:83], v117 offset:32
	s_waitcnt lgkmcnt(2)
	v_mfma_f32_32x32x16_bf16 v[18:33], v[42:45], v[38:41], v[18:33]
	s_waitcnt lgkmcnt(1)
	v_mfma_f32_32x32x16_bf16 v[34:49], v[34:37], v[70:73], 0
	s_waitcnt lgkmcnt(0)
	v_mfma_f32_32x32x16_bf16 v[34:49], v[80:83], v[66:69], v[34:49]
	ds_read_b128 v[80:83], v117 offset:64
	s_waitcnt lgkmcnt(0)
	v_mfma_f32_32x32x16_bf16 v[34:49], v[80:83], v[62:65], v[34:49]
	ds_read_b128 v[80:83], v117 offset:96
	s_waitcnt lgkmcnt(0)
	v_mfma_f32_32x32x16_bf16 v[34:49], v[80:83], v[58:61], v[34:49]
	ds_read_b128 v[80:83], v117 offset:128
	s_waitcnt lgkmcnt(0)
	v_mfma_f32_32x32x16_bf16 v[34:49], v[80:83], v[54:57], v[34:49]
	ds_read_b128 v[80:83], v117 offset:160
	s_waitcnt lgkmcnt(0)
	v_mfma_f32_32x32x16_bf16 v[34:49], v[80:83], v[50:53], v[34:49]
	s_nop 11
	v_max3_f32 v77, v34, s62, v35
	v_max3_f32 v77, v77, v36, v37
	v_max3_f32 v77, v77, v38, v39
	v_max3_f32 v77, v77, v40, v41
	v_max3_f32 v77, v77, v42, v43
	v_max3_f32 v77, v77, v44, v45
	v_max3_f32 v77, v77, v46, v47
	v_max3_f32 v77, v77, v48, v49
	v_mov_b32_e32 v80, v77
	s_nop 1
	v_permlane32_swap_b32_e32 v77, v80
	v_max_f32_e32 v77, v77, v80
	v_mul_f32_e32 v77, 0x3e16c740, v77
	v_add_f32_e32 v80, 0x41000000, v76
	v_cmp_gt_f32_e32 vcc, v77, v80
	s_nop 1
	v_cndmask_b32_e32 v77, v76, v77, vcc
	v_fma_f32 v34, v34, s63, -v77
	v_exp_f32_e32 v142, v34
	v_fma_f32 v34, v35, s63, -v77
	v_fma_f32 v35, v36, s63, -v77
	v_sub_f32_e32 v81, v76, v77
	v_exp_f32_e32 v76, v35
	v_fma_f32 v35, v37, s63, -v77
	v_fma_f32 v36, v38, s63, -v77
	v_fma_f32 v37, v40, s63, -v77
	v_exp_f32_e32 v82, v36
	v_fma_f32 v36, v39, s63, -v77
	v_exp_f32_e32 v86, v37
	v_fma_f32 v37, v41, s63, -v77
	v_fma_f32 v38, v42, s63, -v77
	v_fma_f32 v39, v44, s63, -v77
	v_fma_f32 v40, v46, s63, -v77
	v_fma_f32 v41, v48, s63, -v77
	v_exp_f32_e32 v106, v81
	v_exp_f32_e32 v90, v38
	v_fma_f32 v38, v43, s63, -v77
	v_exp_f32_e32 v94, v39
	v_fma_f32 v39, v45, s63, -v77
	v_exp_f32_e32 v98, v40
	v_fma_f32 v40, v47, s63, -v77
	v_exp_f32_e32 v102, v41
	v_fma_f32 v41, v49, s63, -v77
	v_exp_f32_e32 v143, v34
	v_exp_f32_e32 v80, v35
	v_exp_f32_e32 v84, v36
	v_exp_f32_e32 v88, v37
	v_exp_f32_e32 v92, v38
	v_exp_f32_e32 v96, v39
	v_exp_f32_e32 v100, v40
	v_exp_f32_e32 v104, v41
	v_cmp_eq_f32_e32 vcc, 1.0, v106
	s_cmp_eq_u64 vcc, exec
	v_cvt_pk_bf16_f32 v34, v142, v143
	v_cvt_pk_bf16_f32 v35, v76, v80
	v_cvt_pk_bf16_f32 v36, v82, v84
	v_cvt_pk_bf16_f32 v37, v86, v88
	v_cvt_pk_bf16_f32 v38, v90, v92
	v_cvt_pk_bf16_f32 v39, v94, v96
	v_cvt_pk_bf16_f32 v40, v98, v100
	v_cvt_pk_bf16_f32 v41, v102, v104
	s_cbranch_scc1 .LBB0_941
	v_pk_mul_f32 v[16:17], v[16:17], v[106:107] op_sel_hi:[1,0]
	v_pk_mul_f32 v[14:15], v[14:15], v[106:107] op_sel_hi:[1,0]
	v_pk_mul_f32 v[12:13], v[12:13], v[106:107] op_sel_hi:[1,0]
	v_pk_mul_f32 v[10:11], v[10:11], v[106:107] op_sel_hi:[1,0]
	v_pk_mul_f32 v[8:9], v[8:9], v[106:107] op_sel_hi:[1,0]
	v_pk_mul_f32 v[6:7], v[6:7], v[106:107] op_sel_hi:[1,0]
	v_pk_mul_f32 v[4:5], v[4:5], v[106:107] op_sel_hi:[1,0]
	v_pk_mul_f32 v[2:3], v[2:3], v[106:107] op_sel_hi:[1,0]
	v_pk_mul_f32 v[32:33], v[32:33], v[106:107] op_sel_hi:[1,0]
	v_pk_mul_f32 v[30:31], v[30:31], v[106:107] op_sel_hi:[1,0]
	v_pk_mul_f32 v[28:29], v[28:29], v[106:107] op_sel_hi:[1,0]
	v_pk_mul_f32 v[26:27], v[26:27], v[106:107] op_sel_hi:[1,0]
	v_pk_mul_f32 v[24:25], v[24:25], v[106:107] op_sel_hi:[1,0]
	v_pk_mul_f32 v[22:23], v[22:23], v[106:107] op_sel_hi:[1,0]
	v_pk_mul_f32 v[20:21], v[20:21], v[106:107] op_sel_hi:[1,0]
	v_pk_mul_f32 v[18:19], v[18:19], v[106:107] op_sel_hi:[1,0]
.LBB0_941:
	ds_read_b64_tr_b16 v[42:43], v114 offset:39936
	ds_read_b64_tr_b16 v[44:45], v114 offset:40448
	ds_read_b64_tr_b16 v[46:47], v114 offset:44032
	ds_read_b64_tr_b16 v[48:49], v114 offset:44544
	s_waitcnt lgkmcnt(2)
	v_mfma_f32_32x32x16_bf16 v[2:17], v[42:45], v[34:37], v[2:17]
	s_waitcnt lgkmcnt(0)
	v_mfma_f32_32x32x16_bf16 v[18:33], v[46:49], v[34:37], v[18:33]
	ds_read_b64_tr_b16 v[34:35], v114 offset:40960
	ds_read_b64_tr_b16 v[36:37], v114 offset:41472
	ds_read_b64_tr_b16 v[42:43], v114 offset:45056
	ds_read_b64_tr_b16 v[44:45], v114 offset:45568
	s_waitcnt lgkmcnt(2)
	v_mfma_f32_32x32x16_bf16 v[2:17], v[34:37], v[38:41], v[2:17]
	ds_read_b128 v[34:37], v117 offset:6656
	ds_read_b128 v[144:147], v117 offset:6688
	s_waitcnt lgkmcnt(2)
	v_mfma_f32_32x32x16_bf16 v[18:33], v[42:45], v[38:41], v[18:33]
	s_waitcnt lgkmcnt(1)
	v_mfma_f32_32x32x16_bf16 v[34:49], v[34:37], v[70:73], 0
	s_waitcnt lgkmcnt(0)
	v_mfma_f32_32x32x16_bf16 v[34:49], v[144:147], v[66:69], v[34:49]
	ds_read_b128 v[66:69], v117 offset:6720
	s_waitcnt lgkmcnt(0)
	v_mfma_f32_32x32x16_bf16 v[34:49], v[66:69], v[62:65], v[34:49]
	ds_read_b128 v[62:65], v117 offset:6752
	s_waitcnt lgkmcnt(0)
	v_mfma_f32_32x32x16_bf16 v[34:49], v[62:65], v[58:61], v[34:49]
	ds_read_b128 v[58:61], v117 offset:6784
	s_waitcnt lgkmcnt(0)
	v_mfma_f32_32x32x16_bf16 v[34:49], v[58:61], v[54:57], v[34:49]
	ds_read_b128 v[54:57], v117 offset:6816
	s_waitcnt lgkmcnt(0)
	v_mfma_f32_32x32x16_bf16 v[34:49], v[54:57], v[50:53], v[34:49]
	s_nop 11
	v_max3_f32 v50, v34, s62, v35
	v_max3_f32 v50, v50, v36, v37
	v_max3_f32 v50, v50, v38, v39
	v_max3_f32 v50, v50, v40, v41
	v_max3_f32 v50, v50, v42, v43
	v_max3_f32 v50, v50, v44, v45
	v_max3_f32 v50, v50, v46, v47
	v_max3_f32 v50, v50, v48, v49
	v_mov_b32_e32 v51, v50
	s_nop 1
	v_permlane32_swap_b32_e32 v50, v51
	v_max_f32_e32 v50, v50, v51
	v_mul_f32_e32 v50, 0x3e16c740, v50
	v_add_f32_e32 v51, 0x41000000, v77
	v_cmp_gt_f32_e32 vcc, v50, v51
	s_nop 1
	v_cndmask_b32_e32 v54, v77, v50, vcc
	v_fma_f32 v34, v34, s63, -v54
	v_sub_f32_e32 v55, v77, v54
	v_exp_f32_e32 v77, v34
	v_fma_f32 v34, v35, s63, -v54
	v_exp_f32_e32 v81, v34
	v_fma_f32 v34, v36, s63, -v54
	v_exp_f32_e32 v83, v34
	v_fma_f32 v34, v37, s63, -v54
	v_exp_f32_e32 v85, v34
	v_fma_f32 v34, v38, s63, -v54
	v_exp_f32_e32 v87, v34
	v_fma_f32 v34, v39, s63, -v54
	v_exp_f32_e32 v89, v34
	v_fma_f32 v34, v40, s63, -v54
	v_exp_f32_e32 v91, v34
	v_fma_f32 v34, v41, s63, -v54
	v_exp_f32_e32 v93, v34
	v_fma_f32 v34, v42, s63, -v54
	v_fma_f32 v35, v44, s63, -v54
	v_fma_f32 v36, v46, s63, -v54
	v_fma_f32 v37, v48, s63, -v54
	v_exp_f32_e32 v40, v55
	v_exp_f32_e32 v95, v34
	v_fma_f32 v34, v43, s63, -v54
	v_exp_f32_e32 v99, v35
	v_fma_f32 v35, v45, s63, -v54
	v_exp_f32_e32 v103, v36
	v_fma_f32 v36, v47, s63, -v54
	v_exp_f32_e32 v38, v37
	v_fma_f32 v37, v49, s63, -v54
	v_exp_f32_e32 v97, v34
	v_exp_f32_e32 v101, v35
	v_exp_f32_e32 v105, v36
	v_exp_f32_e32 v39, v37
	v_cmp_eq_f32_e32 vcc, 1.0, v40
	s_cmp_eq_u64 vcc, exec
	v_cvt_pk_bf16_f32 v50, v77, v81
	v_cvt_pk_bf16_f32 v51, v83, v85
	v_cvt_pk_bf16_f32 v52, v87, v89
	v_cvt_pk_bf16_f32 v53, v91, v93
	v_cvt_pk_bf16_f32 v34, v95, v97
	v_cvt_pk_bf16_f32 v35, v99, v101
	v_cvt_pk_bf16_f32 v36, v103, v105
	v_cvt_pk_bf16_f32 v37, v38, v39
	s_cbranch_scc1 .LBB0_870
	v_pk_mul_f32 v[16:17], v[16:17], v[40:41] op_sel_hi:[1,0]
	v_pk_mul_f32 v[14:15], v[14:15], v[40:41] op_sel_hi:[1,0]
	v_pk_mul_f32 v[12:13], v[12:13], v[40:41] op_sel_hi:[1,0]
	v_pk_mul_f32 v[10:11], v[10:11], v[40:41] op_sel_hi:[1,0]
	v_pk_mul_f32 v[8:9], v[8:9], v[40:41] op_sel_hi:[1,0]
	v_pk_mul_f32 v[6:7], v[6:7], v[40:41] op_sel_hi:[1,0]
	v_pk_mul_f32 v[4:5], v[4:5], v[40:41] op_sel_hi:[1,0]
	v_pk_mul_f32 v[2:3], v[2:3], v[40:41] op_sel_hi:[1,0]
	v_pk_mul_f32 v[32:33], v[32:33], v[40:41] op_sel_hi:[1,0]
	v_pk_mul_f32 v[30:31], v[30:31], v[40:41] op_sel_hi:[1,0]
	v_pk_mul_f32 v[28:29], v[28:29], v[40:41] op_sel_hi:[1,0]
	v_pk_mul_f32 v[26:27], v[26:27], v[40:41] op_sel_hi:[1,0]
	v_pk_mul_f32 v[24:25], v[24:25], v[40:41] op_sel_hi:[1,0]
	v_pk_mul_f32 v[22:23], v[22:23], v[40:41] op_sel_hi:[1,0]
	v_pk_mul_f32 v[20:21], v[20:21], v[40:41] op_sel_hi:[1,0]
	v_pk_mul_f32 v[18:19], v[18:19], v[40:41] op_sel_hi:[1,0]
	s_branch .LBB0_870
